# GEMM unit loops: first K-iteration peeled with SrcC=0 MFMAs, accumulator clears removed
# speedup vs baseline: 1.0092x; 1.0092x over previous
; #define PG8_STAGE(bufoff, gbase, voff) do { _Pragma("unroll") for (int _i = 0; _i < 2; ++_i) \
;         __builtin_amdgcn_global_load_lds((const unsigned*)((const char*)(gbase) + (voff)[_i]), (PG8_LAS unsigned*)(lds + (bufoff) + ldsw + _i * 8192), 16, 0, 0); } while (0)
; #define PG8_LDA(dst, b, h) do { _Pragma("unroll") for (int m = 0; m < 4; ++m) _Pragma("unroll") for (int k = 0; k < 2; ++k) dst[m][k] = *(const PG8_LAS bf16x8*)(lds + PG8_SA(b, h) + aoff + m * 2048 + k * 1024); } while (0)
; #define PG8_LDB(dst, b, h) do { _Pragma("unroll") for (int n = 0; n < 2; ++n) _Pragma("unroll") for (int k = 0; k < 2; ++k) dst[n][k] = *(const PG8_LAS bf16x8*)(lds + PG8_SB(b, h) + boff + n * 2048 + k * 1024); } while (0)
; #define PG8_MMA(ai, bj, At, Bt) do { __builtin_amdgcn_s_setprio(1); _Pragma("unroll") for (int m = 0; m < 4; ++m) _Pragma("unroll") for (int n = 0; n < 2; ++n) _Pragma("unroll") for (int k = 0; k < 2; ++k) \
;         acc[ai][bj][m][n] = __builtin_amdgcn_mfma_f32_16x16x32_bf16(Bt[n][k], At[m][k], acc[ai][bj][m][n], 0, 0, 0); __builtin_amdgcn_s_setprio(0); } while (0)
; template <class Epi, class Sched, bool ALIGN_EPI = false, bool SP2 = false>
; __device__ __forceinline__ void gemm_phase(PG8_LAS unsigned char* lds, const Gemm g, const Sched& S, const Epi& E) {
;     ...
;     for (;;) {
;         const bool has_next = S.next(ui + 1, nxt);
;         const char* nA = has_next ? (const char*)g.A + (size_t)nxt.pm * tstep : cA; const char* nB = has_next ? (const char*)g.Bt + (size_t)nxt.pn * tstep : cB;
;         for (int t = 0; t < nt; t += 2) {
;             const bool last = (t == nt - 2);
;             const char* a1 = cA + (size_t)(t + 1) * kstep;
;             const char* a2 = last ? nA : cA + (size_t)(t + 2) * kstep; const char* b2 = last ? nB : cB + (size_t)(t + 2) * kstep;
;             const char* a3 = a2 + kstep; const char* b3 = b2 + kstep;
;             if (last && has_next) S.a_ready(nxt);
;             if constexpr (SP2) {
;             PG8_LDB(B0, 0, 0); PG8_LDB(B1, 0, 1); PG8_SCHED; PG8_LDA(At, 0, 0); PG8_STAGE(PG8_SA(1, 1), a1 + hstep, voffA);
;             PG8_WAIT_V(8); PG8_WAIT_L(0); PG8_BAR; PG8_MMA(0, 0, At, B0); PG8_MMA(0, 1, At, B1); PG8_BAR; PG8_SCHED;
;             PG8_LDA(At, 0, 1); PG8_STAGE(PG8_SB(0, 0), b2, voffB); PG8_STAGE(PG8_SB(0, 1), b2 + hstep, voffB); PG8_STAGE(PG8_SA(0, 0), a2, voffA);
.LBB0_90:
	s_ashr_i32 s55, s54, 31
	s_lshl_b64 s[24:25], s[54:55], 19
	s_add_u32 s60, s70, s24
	s_addc_u32 s61, s71, s25
	s_and_b64 s[24:25], s[58:59], exec
	s_cselect_b32 s23, s61, s77
	s_cselect_b32 s24, s60, s76
	s_ashr_i32 s53, s52, 31
	s_lshl_b64 s[26:27], s[52:53], 19
	s_add_u32 s62, s83, s26
	s_addc_u32 s63, s84, s27
	s_and_b64 s[26:27], s[58:59], exec
	s_cselect_b32 s25, s63, s79
	s_cselect_b32 s26, s62, s78
	s_add_u32 s76, s76, 0x40080
	s_addc_u32 s77, s77, 0
	s_add_u32 s27, s78, 0x100
	s_addc_u32 s28, s79, 0
	s_mov_b32 s29, -2
	ds_read_b128 v[128:131], v183
	ds_read_b128 v[132:135], v183 offset:1024
	ds_read_b128 v[136:139], v183 offset:2048
	ds_read_b128 v[140:143], v183 offset:3072
	ds_read_b128 v[192:195], v185
	ds_read_b128 v[196:199], v185 offset:1024
	ds_read_b128 v[200:203], v185 offset:2048
	ds_read_b128 v[204:207], v185 offset:3072
	s_add_u32 s30, s76, 0xfffc0080
	s_addc_u32 s31, s77, -1
	s_cmp_eq_u32 s29, 12
	s_cselect_b32 s81, s23, s31
	s_cselect_b32 s80, s24, s30
	s_cselect_b32 s79, s25, s28
	s_cselect_b32 s78, s26, s27
	v_lshl_add_u64 v[172:173], s[76:77], 0, v[158:159]
	s_add_i32 m0, s87, 0xc000
	ds_read_b128 v[208:211], v186
	ds_read_b128 v[212:215], v186 offset:1024
	ds_read_b128 v[216:219], v186 offset:2048
	ds_read_b128 v[220:223], v186 offset:3072
	ds_read_b128 v[224:227], v186 offset:4096
	ds_read_b128 v[232:235], v186 offset:5120
	ds_read_b128 v[236:239], v186 offset:6144
	ds_read_b128 v[240:243], v186 offset:7168
	global_load_lds_dwordx4 v[172:173], off
	v_lshl_add_u64 v[172:173], s[76:77], 0, v[160:161]
	s_add_i32 m0, s87, 0xe000
	s_nop 0
	global_load_lds_dwordx4 v[172:173], off
	s_waitcnt vmcnt(8)
	s_waitcnt lgkmcnt(0)
	s_barrier
	s_setprio 1
	s_waitcnt lgkmcnt(0)
	v_mfma_f32_16x16x32_bf16 v[124:127], v[128:131], v[208:211], 0
	v_mfma_f32_16x16x32_bf16 v[120:123], v[136:139], v[208:211], 0
	v_mfma_f32_16x16x32_bf16 v[112:115], v[128:131], v[216:219], 0
	v_mfma_f32_16x16x32_bf16 v[108:111], v[136:139], v[216:219], 0
	v_mfma_f32_16x16x32_bf16 v[96:99], v[128:131], v[224:227], 0
	v_mfma_f32_16x16x32_bf16 v[88:91], v[136:139], v[224:227], 0
	v_mfma_f32_16x16x32_bf16 v[80:83], v[128:131], v[236:239], 0
	v_mfma_f32_16x16x32_bf16 v[72:75], v[136:139], v[236:239], 0
	v_mfma_f32_16x16x32_bf16 v[124:127], v[132:135], v[212:215], v[124:127]
	v_mfma_f32_16x16x32_bf16 v[120:123], v[140:143], v[212:215], v[120:123]
	v_mfma_f32_16x16x32_bf16 v[112:115], v[132:135], v[220:223], v[112:115]
	v_mfma_f32_16x16x32_bf16 v[108:111], v[140:143], v[220:223], v[108:111]
	v_mfma_f32_16x16x32_bf16 v[96:99], v[132:135], v[232:235], v[96:99]
	v_mfma_f32_16x16x32_bf16 v[88:91], v[140:143], v[232:235], v[88:91]
	v_mfma_f32_16x16x32_bf16 v[80:83], v[132:135], v[240:243], v[80:83]
	v_mfma_f32_16x16x32_bf16 v[72:75], v[140:143], v[240:243], v[72:75]
	s_setprio 0
	s_setprio 1
	v_mfma_f32_16x16x32_bf16 v[116:119], v[192:195], v[208:211], 0
	v_mfma_f32_16x16x32_bf16 v[104:107], v[200:203], v[208:211], 0
	v_mfma_f32_16x16x32_bf16 v[100:103], v[192:195], v[216:219], 0
	v_mfma_f32_16x16x32_bf16 v[92:95], v[200:203], v[216:219], 0
	v_mfma_f32_16x16x32_bf16 v[84:87], v[192:195], v[224:227], 0
	v_mfma_f32_16x16x32_bf16 v[76:79], v[200:203], v[224:227], 0
	v_mfma_f32_16x16x32_bf16 v[68:71], v[192:195], v[236:239], 0
	v_mfma_f32_16x16x32_bf16 v[64:67], v[200:203], v[236:239], 0
	v_mfma_f32_16x16x32_bf16 v[116:119], v[196:199], v[212:215], v[116:119]
	v_mfma_f32_16x16x32_bf16 v[104:107], v[204:207], v[212:215], v[104:107]
	v_mfma_f32_16x16x32_bf16 v[100:103], v[196:199], v[220:223], v[100:103]
	v_mfma_f32_16x16x32_bf16 v[92:95], v[204:207], v[220:223], v[92:95]
	v_mfma_f32_16x16x32_bf16 v[84:87], v[196:199], v[232:235], v[84:87]
	v_mfma_f32_16x16x32_bf16 v[76:79], v[204:207], v[232:235], v[76:79]
	v_mfma_f32_16x16x32_bf16 v[68:71], v[196:199], v[240:243], v[68:71]
	v_mfma_f32_16x16x32_bf16 v[64:67], v[204:207], v[240:243], v[64:67]
	s_setprio 0
	s_barrier
	s_add_i32 s30, s33, s86
	v_lshl_add_u64 v[172:173], s[78:79], 0, v[146:147]
	s_mov_b32 m0, s30
	ds_read_b128 v[208:211], v186 offset:16384
	ds_read_b128 v[212:215], v186 offset:17408
	ds_read_b128 v[216:219], v186 offset:18432
	ds_read_b128 v[220:223], v186 offset:19456
	ds_read_b128 v[224:227], v186 offset:20480
	ds_read_b128 v[232:235], v186 offset:21504
	ds_read_b128 v[236:239], v186 offset:22528
	ds_read_b128 v[240:243], v186 offset:23552
	global_load_lds_dwordx4 v[172:173], off
	s_add_i32 m0, s30, 0x2000
	s_add_u32 s30, s78, 0x40000
	v_lshl_add_u64 v[228:229], s[78:79], 0, v[150:151]
	s_addc_u32 s31, s79, 0
	s_add_i32 s53, s16, s86
	global_load_lds_dwordx4 v[228:229], off
	v_lshl_add_u64 v[244:245], s[30:31], 0, v[146:147]
	s_mov_b32 m0, s53
	v_lshl_add_u64 v[246:247], s[80:81], 0, v[148:149]
	global_load_lds_dwordx4 v[244:245], off
	v_lshl_add_u64 v[244:245], s[30:31], 0, v[150:151]
	s_add_i32 m0, s53, 0x2000
	s_nop 0
	global_load_lds_dwordx4 v[244:245], off
	v_lshl_add_u64 v[244:245], s[80:81], 0, v[144:145]
	s_mov_b32 m0, s87
	s_nop 0
	global_load_lds_dwordx4 v[244:245], off
	s_mov_b32 m0, s88
	s_nop 0
	global_load_lds_dwordx4 v[246:247], off
	s_waitcnt vmcnt(8)
	s_waitcnt lgkmcnt(0)
	s_barrier
; #define PG8_STAGE(bufoff, gbase, voff) do { _Pragma("unroll") for (int _i = 0; _i < 2; ++_i) \
;         __builtin_amdgcn_global_load_lds((const unsigned*)((const char*)(gbase) + (voff)[_i]), (PG8_LAS unsigned*)(lds + (bufoff) + ldsw + _i * 8192), 16, 0, 0); } while (0)
; #define PG8_LDA(dst, b, h) do { _Pragma("unroll") for (int m = 0; m < 4; ++m) _Pragma("unroll") for (int k = 0; k < 2; ++k) dst[m][k] = *(const PG8_LAS bf16x8*)(lds + PG8_SA(b, h) + aoff + m * 2048 + k * 1024); } while (0)
; #define PG8_LDB(dst, b, h) do { _Pragma("unroll") for (int n = 0; n < 2; ++n) _Pragma("unroll") for (int k = 0; k < 2; ++k) dst[n][k] = *(const PG8_LAS bf16x8*)(lds + PG8_SB(b, h) + boff + n * 2048 + k * 1024); } while (0)
; #define PG8_MMA(ai, bj, At, Bt) do { __builtin_amdgcn_s_setprio(1); _Pragma("unroll") for (int m = 0; m < 4; ++m) _Pragma("unroll") for (int n = 0; n < 2; ++n) _Pragma("unroll") for (int k = 0; k < 2; ++k) \
;         acc[ai][bj][m][n] = __builtin_amdgcn_mfma_f32_16x16x32_bf16(Bt[n][k], At[m][k], acc[ai][bj][m][n], 0, 0, 0); __builtin_amdgcn_s_setprio(0); } while (0)
; #define PG8_WAIT_V(n) asm volatile("s_waitcnt vmcnt(" #n ")" ::: "memory")
; #define PG8_WAIT_L(n) asm volatile("s_waitcnt lgkmcnt(" #n ")" ::: "memory")
; #define PG8_BAR __builtin_amdgcn_s_barrier()
; #define PG8_SCHED __builtin_amdgcn_sched_barrier(0)
; template <class Epi, class Sched, bool ALIGN_EPI = false, bool SP2 = false>
; __device__ __forceinline__ void gemm_phase(PG8_LAS unsigned char* lds, const Gemm g, const Sched& S, const Epi& E) {
;     ...
;             PG8_WAIT_V(8); PG8_WAIT_L(0); PG8_BAR; PG8_MMA(1, 0, At, B0); PG8_MMA(1, 1, At, B1); PG8_BAR; PG8_SCHED;
;             PG8_LDB(B0, 1, 0); PG8_LDB(B1, 1, 1); PG8_SCHED; PG8_LDA(At, 1, 0); PG8_STAGE(PG8_SA(0, 1), a2 + hstep, voffA);
;             PG8_WAIT_V(8); PG8_WAIT_L(0); PG8_BAR; PG8_MMA(0, 0, At, B0); PG8_MMA(0, 1, At, B1); PG8_BAR; PG8_SCHED;
	s_setprio 1
	s_waitcnt lgkmcnt(0)
	v_mfma_f32_16x16x32_bf16 v[60:63], v[128:131], v[208:211], 0
	v_mfma_f32_16x16x32_bf16 v[56:59], v[136:139], v[208:211], 0
	v_mfma_f32_16x16x32_bf16 v[48:51], v[128:131], v[216:219], 0
	v_mfma_f32_16x16x32_bf16 v[44:47], v[136:139], v[216:219], 0
	v_mfma_f32_16x16x32_bf16 v[32:35], v[128:131], v[224:227], 0
	v_mfma_f32_16x16x32_bf16 v[28:31], v[136:139], v[224:227], 0
	v_mfma_f32_16x16x32_bf16 v[16:19], v[128:131], v[236:239], 0
	v_mfma_f32_16x16x32_bf16 v[12:15], v[136:139], v[236:239], 0
	v_mfma_f32_16x16x32_bf16 v[60:63], v[132:135], v[212:215], v[60:63]
	v_mfma_f32_16x16x32_bf16 v[56:59], v[140:143], v[212:215], v[56:59]
	v_mfma_f32_16x16x32_bf16 v[48:51], v[132:135], v[220:223], v[48:51]
	v_mfma_f32_16x16x32_bf16 v[44:47], v[140:143], v[220:223], v[44:47]
	v_mfma_f32_16x16x32_bf16 v[32:35], v[132:135], v[232:235], v[32:35]
	v_mfma_f32_16x16x32_bf16 v[28:31], v[140:143], v[232:235], v[28:31]
	v_mfma_f32_16x16x32_bf16 v[16:19], v[132:135], v[240:243], v[16:19]
	v_mfma_f32_16x16x32_bf16 v[12:15], v[140:143], v[240:243], v[12:15]
	s_setprio 0
	s_setprio 1
	v_mfma_f32_16x16x32_bf16 v[52:55], v[192:195], v[208:211], 0
	v_mfma_f32_16x16x32_bf16 v[40:43], v[200:203], v[208:211], 0
	v_mfma_f32_16x16x32_bf16 v[36:39], v[192:195], v[216:219], 0
	v_mfma_f32_16x16x32_bf16 v[24:27], v[200:203], v[216:219], 0
	v_mfma_f32_16x16x32_bf16 v[20:23], v[192:195], v[224:227], 0
	v_mfma_f32_16x16x32_bf16 v[8:11], v[200:203], v[224:227], 0
	v_mfma_f32_16x16x32_bf16 v[4:7], v[192:195], v[236:239], 0
	v_mfma_f32_16x16x32_bf16 v[0:3], v[200:203], v[236:239], 0
	v_mfma_f32_16x16x32_bf16 v[52:55], v[196:199], v[212:215], v[52:55]
	v_mfma_f32_16x16x32_bf16 v[40:43], v[204:207], v[212:215], v[40:43]
	v_mfma_f32_16x16x32_bf16 v[36:39], v[196:199], v[220:223], v[36:39]
	v_mfma_f32_16x16x32_bf16 v[24:27], v[204:207], v[220:223], v[24:27]
	v_mfma_f32_16x16x32_bf16 v[20:23], v[196:199], v[232:235], v[20:23]
	v_mfma_f32_16x16x32_bf16 v[8:11], v[204:207], v[232:235], v[8:11]
	v_mfma_f32_16x16x32_bf16 v[4:7], v[196:199], v[240:243], v[4:7]
	v_mfma_f32_16x16x32_bf16 v[0:3], v[204:207], v[240:243], v[0:3]
	s_setprio 0
	s_barrier
	s_add_i32 s53, 0, 0x18000
	s_add_i32 s55, 0, 0x1c000
	v_add_u32_e32 v140, s53, v177
	v_add_u32_e32 v163, s55, v177
	ds_read_b128 v[128:131], v140
	ds_read_b128 v[132:135], v140 offset:1024
	ds_read_b128 v[136:139], v140 offset:2048
	ds_read_b128 v[140:143], v140 offset:3072
	ds_read_b128 v[192:195], v163
	ds_read_b128 v[196:199], v163 offset:1024
	ds_read_b128 v[200:203], v163 offset:2048
	ds_read_b128 v[204:207], v163 offset:3072
	s_add_u32 s30, s80, 0x40000
	s_addc_u32 s31, s81, 0
	s_mov_b32 m0, s89
	v_lshl_add_u64 v[248:249], s[30:31], 0, v[144:145]
	ds_read_b128 v[208:211], v186 offset:32768
	ds_read_b128 v[212:215], v186 offset:33792
	ds_read_b128 v[216:219], v186 offset:34816
	ds_read_b128 v[220:223], v186 offset:35840
	ds_read_b128 v[224:227], v186 offset:36864
	ds_read_b128 v[232:235], v186 offset:37888
	ds_read_b128 v[236:239], v186 offset:38912
	ds_read_b128 v[240:243], v186 offset:39936
	global_load_lds_dwordx4 v[248:249], off
	v_lshl_add_u64 v[248:249], s[30:31], 0, v[148:149]
	s_mov_b32 m0, s90
	s_nop 0
	global_load_lds_dwordx4 v[248:249], off
	s_waitcnt vmcnt(8)
	s_waitcnt lgkmcnt(0)
	s_barrier
	s_setprio 1
	s_waitcnt lgkmcnt(0)
	v_mfma_f32_16x16x32_bf16 v[124:127], v[128:131], v[208:211], v[124:127]
	v_mfma_f32_16x16x32_bf16 v[120:123], v[136:139], v[208:211], v[120:123]
	v_mfma_f32_16x16x32_bf16 v[112:115], v[128:131], v[216:219], v[112:115]
	v_mfma_f32_16x16x32_bf16 v[108:111], v[136:139], v[216:219], v[108:111]
	v_mfma_f32_16x16x32_bf16 v[96:99], v[128:131], v[224:227], v[96:99]
	v_mfma_f32_16x16x32_bf16 v[88:91], v[136:139], v[224:227], v[88:91]
	v_mfma_f32_16x16x32_bf16 v[80:83], v[128:131], v[236:239], v[80:83]
	v_mfma_f32_16x16x32_bf16 v[72:75], v[136:139], v[236:239], v[72:75]
	v_mfma_f32_16x16x32_bf16 v[124:127], v[132:135], v[212:215], v[124:127]
	v_mfma_f32_16x16x32_bf16 v[120:123], v[140:143], v[212:215], v[120:123]
	v_mfma_f32_16x16x32_bf16 v[112:115], v[132:135], v[220:223], v[112:115]
	v_mfma_f32_16x16x32_bf16 v[108:111], v[140:143], v[220:223], v[108:111]
	v_mfma_f32_16x16x32_bf16 v[96:99], v[132:135], v[232:235], v[96:99]
	v_mfma_f32_16x16x32_bf16 v[88:91], v[140:143], v[232:235], v[88:91]
	v_mfma_f32_16x16x32_bf16 v[80:83], v[132:135], v[240:243], v[80:83]
	v_mfma_f32_16x16x32_bf16 v[72:75], v[140:143], v[240:243], v[72:75]
	s_setprio 0
	s_setprio 1
	v_mfma_f32_16x16x32_bf16 v[116:119], v[192:195], v[208:211], v[116:119]
	v_mfma_f32_16x16x32_bf16 v[104:107], v[200:203], v[208:211], v[104:107]
	v_mfma_f32_16x16x32_bf16 v[100:103], v[192:195], v[216:219], v[100:103]
	v_mfma_f32_16x16x32_bf16 v[92:95], v[200:203], v[216:219], v[92:95]
	v_mfma_f32_16x16x32_bf16 v[84:87], v[192:195], v[224:227], v[84:87]
	v_mfma_f32_16x16x32_bf16 v[76:79], v[200:203], v[224:227], v[76:79]
	v_mfma_f32_16x16x32_bf16 v[68:71], v[192:195], v[236:239], v[68:71]
	v_mfma_f32_16x16x32_bf16 v[64:67], v[200:203], v[236:239], v[64:67]
	v_mfma_f32_16x16x32_bf16 v[116:119], v[196:199], v[212:215], v[116:119]
	v_mfma_f32_16x16x32_bf16 v[104:107], v[204:207], v[212:215], v[104:107]
	v_mfma_f32_16x16x32_bf16 v[100:103], v[196:199], v[220:223], v[100:103]
	v_mfma_f32_16x16x32_bf16 v[92:95], v[204:207], v[220:223], v[92:95]
	v_mfma_f32_16x16x32_bf16 v[84:87], v[196:199], v[232:235], v[84:87]
	v_mfma_f32_16x16x32_bf16 v[76:79], v[204:207], v[232:235], v[76:79]
	v_mfma_f32_16x16x32_bf16 v[68:71], v[196:199], v[240:243], v[68:71]
	v_mfma_f32_16x16x32_bf16 v[64:67], v[204:207], v[240:243], v[64:67]
	s_setprio 0
	s_barrier
; #define PG8_STAGE(bufoff, gbase, voff) do { _Pragma("unroll") for (int _i = 0; _i < 2; ++_i) \
;         __builtin_amdgcn_global_load_lds((const unsigned*)((const char*)(gbase) + (voff)[_i]), (PG8_LAS unsigned*)(lds + (bufoff) + ldsw + _i * 8192), 16, 0, 0); } while (0)
; #define PG8_LDA(dst, b, h) do { _Pragma("unroll") for (int m = 0; m < 4; ++m) _Pragma("unroll") for (int k = 0; k < 2; ++k) dst[m][k] = *(const PG8_LAS bf16x8*)(lds + PG8_SA(b, h) + aoff + m * 2048 + k * 1024); } while (0)
; #define PG8_MMA(ai, bj, At, Bt) do { __builtin_amdgcn_s_setprio(1); _Pragma("unroll") for (int m = 0; m < 4; ++m) _Pragma("unroll") for (int n = 0; n < 2; ++n) _Pragma("unroll") for (int k = 0; k < 2; ++k) \
;         acc[ai][bj][m][n] = __builtin_amdgcn_mfma_f32_16x16x32_bf16(Bt[n][k], At[m][k], acc[ai][bj][m][n], 0, 0, 0); __builtin_amdgcn_s_setprio(0); } while (0)
; #define PG8_WAIT_V(n) asm volatile("s_waitcnt vmcnt(" #n ")" ::: "memory")
; #define PG8_WAIT_L(n) asm volatile("s_waitcnt lgkmcnt(" #n ")" ::: "memory")
; #define PG8_BAR __builtin_amdgcn_s_barrier()
; #define PG8_SCHED __builtin_amdgcn_sched_barrier(0)
; template <class Epi, class Sched, bool ALIGN_EPI = false, bool SP2 = false>
; __device__ __forceinline__ void gemm_phase(PG8_LAS unsigned char* lds, const Gemm g, const Sched& S, const Epi& E) {
;     ...
;         for (int t = 0; t < nt; t += 2) {
;             const bool last = (t == nt - 2);
;             const char* a1 = cA + (size_t)(t + 1) * kstep;
;             const char* a2 = last ? nA : cA + (size_t)(t + 2) * kstep; const char* b2 = last ? nB : cB + (size_t)(t + 2) * kstep;
;             const char* a3 = a2 + kstep; const char* b3 = b2 + kstep;
;     ...
;             PG8_LDA(At, 1, 1); PG8_STAGE(PG8_SB(1, 0), b3, voffB); PG8_STAGE(PG8_SB(1, 1), b3 + hstep, voffB); PG8_STAGE(PG8_SA(1, 0), a3, voffA);
;             PG8_WAIT_V(8); PG8_WAIT_L(0); PG8_BAR; PG8_MMA(1, 0, At, B0); PG8_MMA(1, 1, At, B1); PG8_BAR; PG8_SCHED;
	s_add_i32 s30, s53, s86
	v_lshl_add_u64 v[172:173], v[172:173], 0, s[18:19]
	s_mov_b32 m0, s30
	ds_read_b128 v[208:211], v186 offset:49152
	ds_read_b128 v[212:215], v186 offset:50176
	ds_read_b128 v[216:219], v186 offset:51200
	ds_read_b128 v[220:223], v186 offset:52224
	ds_read_b128 v[224:227], v186 offset:53248
	ds_read_b128 v[232:235], v186 offset:54272
	ds_read_b128 v[236:239], v186 offset:55296
	ds_read_b128 v[240:243], v186 offset:56320
	global_load_lds_dwordx4 v[172:173], off
	s_add_i32 m0, s30, 0x2000
	s_add_u32 s30, s78, 0x40080
	v_lshl_add_u64 v[172:173], v[228:229], 0, s[18:19]
	s_addc_u32 s31, s79, 0
	s_add_i32 s53, s55, s86
	global_load_lds_dwordx4 v[172:173], off
	v_lshl_add_u64 v[172:173], s[30:31], 0, v[146:147]
	s_mov_b32 m0, s53
	s_nop 0
	global_load_lds_dwordx4 v[172:173], off
	v_lshl_add_u64 v[172:173], s[30:31], 0, v[150:151]
	s_add_i32 m0, s53, 0x2000
	s_nop 0
	global_load_lds_dwordx4 v[172:173], off
	v_lshl_add_u64 v[172:173], v[244:245], 0, s[18:19]
	s_mov_b32 m0, s93
	s_nop 0
	global_load_lds_dwordx4 v[172:173], off
	v_lshl_add_u64 v[172:173], v[246:247], 0, s[18:19]
	s_mov_b32 m0, s94
	s_nop 0
	global_load_lds_dwordx4 v[172:173], off
	s_waitcnt vmcnt(8)
	s_waitcnt lgkmcnt(0)
	s_barrier
	s_setprio 1
	s_waitcnt lgkmcnt(0)
	v_mfma_f32_16x16x32_bf16 v[60:63], v[128:131], v[208:211], v[60:63]
	v_mfma_f32_16x16x32_bf16 v[56:59], v[136:139], v[208:211], v[56:59]
	v_mfma_f32_16x16x32_bf16 v[48:51], v[128:131], v[216:219], v[48:51]
	v_mfma_f32_16x16x32_bf16 v[44:47], v[136:139], v[216:219], v[44:47]
	v_mfma_f32_16x16x32_bf16 v[32:35], v[128:131], v[224:227], v[32:35]
	v_mfma_f32_16x16x32_bf16 v[28:31], v[136:139], v[224:227], v[28:31]
	v_mfma_f32_16x16x32_bf16 v[16:19], v[128:131], v[236:239], v[16:19]
	v_mfma_f32_16x16x32_bf16 v[12:15], v[136:139], v[236:239], v[12:15]
	v_mfma_f32_16x16x32_bf16 v[60:63], v[132:135], v[212:215], v[60:63]
	v_mfma_f32_16x16x32_bf16 v[56:59], v[140:143], v[212:215], v[56:59]
	v_mfma_f32_16x16x32_bf16 v[48:51], v[132:135], v[220:223], v[48:51]
	v_mfma_f32_16x16x32_bf16 v[44:47], v[140:143], v[220:223], v[44:47]
	v_mfma_f32_16x16x32_bf16 v[32:35], v[132:135], v[232:235], v[32:35]
	v_mfma_f32_16x16x32_bf16 v[28:31], v[140:143], v[232:235], v[28:31]
	v_mfma_f32_16x16x32_bf16 v[16:19], v[132:135], v[240:243], v[16:19]
	v_mfma_f32_16x16x32_bf16 v[12:15], v[140:143], v[240:243], v[12:15]
	s_setprio 0
	s_setprio 1
	v_mfma_f32_16x16x32_bf16 v[52:55], v[192:195], v[208:211], v[52:55]
	v_mfma_f32_16x16x32_bf16 v[40:43], v[200:203], v[208:211], v[40:43]
	v_mfma_f32_16x16x32_bf16 v[36:39], v[192:195], v[216:219], v[36:39]
	v_mfma_f32_16x16x32_bf16 v[24:27], v[200:203], v[216:219], v[24:27]
	v_mfma_f32_16x16x32_bf16 v[20:23], v[192:195], v[224:227], v[20:23]
	v_mfma_f32_16x16x32_bf16 v[8:11], v[200:203], v[224:227], v[8:11]
	v_mfma_f32_16x16x32_bf16 v[4:7], v[192:195], v[236:239], v[4:7]
	v_mfma_f32_16x16x32_bf16 v[0:3], v[200:203], v[236:239], v[0:3]
	v_mfma_f32_16x16x32_bf16 v[52:55], v[196:199], v[212:215], v[52:55]
	v_mfma_f32_16x16x32_bf16 v[40:43], v[204:207], v[212:215], v[40:43]
	v_mfma_f32_16x16x32_bf16 v[36:39], v[196:199], v[220:223], v[36:39]
	v_mfma_f32_16x16x32_bf16 v[24:27], v[204:207], v[220:223], v[24:27]
	v_mfma_f32_16x16x32_bf16 v[20:23], v[196:199], v[232:235], v[20:23]
	v_mfma_f32_16x16x32_bf16 v[8:11], v[204:207], v[232:235], v[8:11]
	v_mfma_f32_16x16x32_bf16 v[4:7], v[196:199], v[240:243], v[4:7]
	v_mfma_f32_16x16x32_bf16 v[0:3], v[204:207], v[240:243], v[0:3]
	s_setprio 0
	s_barrier
	s_add_i32 s29, s29, 2
	s_add_u32 s76, s76, 0x100
	s_addc_u32 s77, s77, 0
	s_add_u32 s27, s27, 0x100
	s_addc_u32 s28, s28, 0
	s_cmp_gt_u32 s29, 13

; #define PG8_STAGE(bufoff, gbase, voff) do { _Pragma("unroll") for (int _i = 0; _i < 2; ++_i) \
;         __builtin_amdgcn_global_load_lds((const unsigned*)((const char*)(gbase) + (voff)[_i]), (PG8_LAS unsigned*)(lds + (bufoff) + ldsw + _i * 8192), 16, 0, 0); } while (0)
; #define PG8_LDA(dst, b, h) do { _Pragma("unroll") for (int m = 0; m < 4; ++m) _Pragma("unroll") for (int k = 0; k < 2; ++k) dst[m][k] = *(const PG8_LAS bf16x8*)(lds + PG8_SA(b, h) + aoff + m * 2048 + k * 1024); } while (0)
; #define PG8_LDB(dst, b, h) do { _Pragma("unroll") for (int n = 0; n < 2; ++n) _Pragma("unroll") for (int k = 0; k < 2; ++k) dst[n][k] = *(const PG8_LAS bf16x8*)(lds + PG8_SB(b, h) + boff + n * 2048 + k * 1024); } while (0)
; #define PG8_MMA(ai, bj, At, Bt) do { __builtin_amdgcn_s_setprio(1); _Pragma("unroll") for (int m = 0; m < 4; ++m) _Pragma("unroll") for (int n = 0; n < 2; ++n) _Pragma("unroll") for (int k = 0; k < 2; ++k) \
;         acc[ai][bj][m][n] = __builtin_amdgcn_mfma_f32_16x16x32_bf16(Bt[n][k], At[m][k], acc[ai][bj][m][n], 0, 0, 0); __builtin_amdgcn_s_setprio(0); } while (0)
; template <class Epi, class Sched, bool ALIGN_EPI = false, bool SP2 = false>
; __device__ __forceinline__ void gemm_phase(PG8_LAS unsigned char* lds, const Gemm g, const Sched& S, const Epi& E) {
;     ...
;     for (;;) {
;         const bool has_next = S.next(ui + 1, nxt);
;         const char* nA = has_next ? (const char*)g.A + (size_t)nxt.pm * tstep : cA; const char* nB = has_next ? (const char*)g.Bt + (size_t)nxt.pn * tstep : cB;
;         for (int t = 0; t < nt; t += 2) {
;             const bool last = (t == nt - 2);
;             const char* a1 = cA + (size_t)(t + 1) * kstep;
;             const char* a2 = last ? nA : cA + (size_t)(t + 2) * kstep; const char* b2 = last ? nB : cB + (size_t)(t + 2) * kstep;
;             const char* a3 = a2 + kstep; const char* b3 = b2 + kstep;
;             if (last && has_next) S.a_ready(nxt);
;             if constexpr (SP2) {
;             PG8_LDB(B0, 0, 0); PG8_LDB(B1, 0, 1); PG8_SCHED; PG8_LDA(At, 0, 0); PG8_STAGE(PG8_SA(1, 1), a1 + hstep, voffA);
;             PG8_WAIT_V(8); PG8_WAIT_L(0); PG8_BAR; PG8_MMA(0, 0, At, B0); PG8_MMA(0, 1, At, B1); PG8_BAR; PG8_SCHED;
;             PG8_LDA(At, 0, 1); PG8_STAGE(PG8_SB(0, 0), b2, voffB); PG8_STAGE(PG8_SB(0, 1), b2 + hstep, voffB); PG8_STAGE(PG8_SA(0, 0), a2, voffA);
.LBB0_392:
	s_ashr_i32 s39, s38, 31
	s_lshl_b64 s[42:43], s[38:39], 19
	s_add_u32 s42, s68, s42
	s_addc_u32 s43, s69, s43
	s_and_b64 s[44:45], s[40:41], exec
	s_cselect_b32 s39, s43, s49
	s_cselect_b32 s47, s42, s48
	s_ashr_i32 s37, s36, 31
	s_lshl_b64 s[44:45], s[36:37], 19
	s_add_u32 s44, s23, s44
	s_addc_u32 s45, s24, s45
	s_and_b64 s[52:53], s[40:41], exec
	s_cselect_b32 s37, s45, s51
	s_cselect_b32 s59, s44, s50
	s_add_u32 s48, s48, 0x40080
	s_addc_u32 s49, s49, 0
	s_add_u32 s60, s50, 0x100
	s_addc_u32 s61, s51, 0
	s_mov_b32 s62, -2
	s_waitcnt lgkmcnt(0)
	ds_read_b128 v[124:127], v234
	ds_read_b128 v[132:135], v234 offset:1024
	ds_read_b128 v[136:139], v234 offset:2048
	ds_read_b128 v[140:143], v234 offset:3072
	ds_read_b128 v[144:147], v235
	ds_read_b128 v[148:151], v235 offset:1024
	ds_read_b128 v[152:155], v235 offset:2048
	ds_read_b128 v[156:159], v235 offset:3072
	s_add_u32 s50, s48, 0xfffc0080
	s_addc_u32 s51, s49, -1
	s_cmp_eq_u32 s62, 12
	s_cselect_b32 s53, s39, s51
	s_cselect_b32 s52, s47, s50
	s_cselect_b32 s51, s37, s61
	s_cselect_b32 s50, s59, s60
	v_lshl_add_u64 v[206:207], s[48:49], 0, v[192:193]
	s_add_i32 m0, s26, 0xc000
	ds_read_b128 v[160:163], v236
	ds_read_b128 v[164:167], v236 offset:1024
	ds_read_b128 v[168:171], v236 offset:2048
	ds_read_b128 v[172:175], v236 offset:3072
	ds_read_b128 v[176:179], v236 offset:4096
	ds_read_b128 v[180:183], v236 offset:5120
	ds_read_b128 v[198:201], v236 offset:6144
	ds_read_b128 v[202:205], v236 offset:7168
	global_load_lds_dwordx4 v[206:207], off
	v_lshl_add_u64 v[206:207], s[48:49], 0, v[194:195]
	s_add_i32 m0, s26, 0xe000
	s_nop 0
	global_load_lds_dwordx4 v[206:207], off
	s_waitcnt vmcnt(8)
	s_waitcnt lgkmcnt(0)
	s_barrier
	s_setprio 1
	s_waitcnt lgkmcnt(0)
	v_mfma_f32_16x16x32_bf16 v[128:131], v[124:127], v[160:163], 0
	v_mfma_f32_16x16x32_bf16 v[120:123], v[136:139], v[160:163], 0
	v_mfma_f32_16x16x32_bf16 v[108:111], v[124:127], v[168:171], 0
	v_mfma_f32_16x16x32_bf16 v[104:107], v[136:139], v[168:171], 0
	v_mfma_f32_16x16x32_bf16 v[92:95], v[124:127], v[176:179], 0
	v_mfma_f32_16x16x32_bf16 v[88:91], v[136:139], v[176:179], 0
	v_mfma_f32_16x16x32_bf16 v[76:79], v[124:127], v[198:201], 0
	v_mfma_f32_16x16x32_bf16 v[72:75], v[136:139], v[198:201], 0
	v_mfma_f32_16x16x32_bf16 v[128:131], v[132:135], v[164:167], v[128:131]
	v_mfma_f32_16x16x32_bf16 v[120:123], v[140:143], v[164:167], v[120:123]
	v_mfma_f32_16x16x32_bf16 v[108:111], v[132:135], v[172:175], v[108:111]
	v_mfma_f32_16x16x32_bf16 v[104:107], v[140:143], v[172:175], v[104:107]
	v_mfma_f32_16x16x32_bf16 v[92:95], v[132:135], v[180:183], v[92:95]
	v_mfma_f32_16x16x32_bf16 v[88:91], v[140:143], v[180:183], v[88:91]
	v_mfma_f32_16x16x32_bf16 v[76:79], v[132:135], v[202:205], v[76:79]
	v_mfma_f32_16x16x32_bf16 v[72:75], v[140:143], v[202:205], v[72:75]
	s_setprio 0
	s_setprio 1
	v_mfma_f32_16x16x32_bf16 v[116:119], v[144:147], v[160:163], 0
	v_mfma_f32_16x16x32_bf16 v[112:115], v[152:155], v[160:163], 0
	v_mfma_f32_16x16x32_bf16 v[100:103], v[144:147], v[168:171], 0
	v_mfma_f32_16x16x32_bf16 v[96:99], v[152:155], v[168:171], 0
	v_mfma_f32_16x16x32_bf16 v[84:87], v[144:147], v[176:179], 0
	v_mfma_f32_16x16x32_bf16 v[80:83], v[152:155], v[176:179], 0
	v_mfma_f32_16x16x32_bf16 v[68:71], v[144:147], v[198:201], 0
	v_mfma_f32_16x16x32_bf16 v[64:67], v[152:155], v[198:201], 0
	v_mfma_f32_16x16x32_bf16 v[116:119], v[148:151], v[164:167], v[116:119]
	v_mfma_f32_16x16x32_bf16 v[112:115], v[156:159], v[164:167], v[112:115]
	v_mfma_f32_16x16x32_bf16 v[100:103], v[148:151], v[172:175], v[100:103]
	v_mfma_f32_16x16x32_bf16 v[96:99], v[156:159], v[172:175], v[96:99]
	v_mfma_f32_16x16x32_bf16 v[84:87], v[148:151], v[180:183], v[84:87]
	v_mfma_f32_16x16x32_bf16 v[80:83], v[156:159], v[180:183], v[80:83]
	v_mfma_f32_16x16x32_bf16 v[68:71], v[148:151], v[202:205], v[68:71]
	v_mfma_f32_16x16x32_bf16 v[64:67], v[156:159], v[202:205], v[64:67]
	s_setprio 0
	s_barrier
	s_add_i32 s63, s56, s25
	v_lshl_add_u64 v[206:207], s[50:51], 0, v[186:187]
	s_mov_b32 m0, s63
	ds_read_b128 v[160:163], v236 offset:16384
	ds_read_b128 v[164:167], v236 offset:17408
	ds_read_b128 v[168:171], v236 offset:18432
	ds_read_b128 v[172:175], v236 offset:19456
	ds_read_b128 v[176:179], v236 offset:20480
	ds_read_b128 v[180:183], v236 offset:21504
	ds_read_b128 v[198:201], v236 offset:22528
	ds_read_b128 v[202:205], v236 offset:23552
	global_load_lds_dwordx4 v[206:207], off
	s_add_i32 m0, s63, 0x2000
	s_add_u32 s64, s50, 0x40000
	v_lshl_add_u64 v[208:209], s[50:51], 0, v[190:191]
	s_addc_u32 s65, s51, 0
	s_add_i32 s63, s57, s25
	global_load_lds_dwordx4 v[208:209], off
	v_lshl_add_u64 v[210:211], s[64:65], 0, v[186:187]
	s_mov_b32 m0, s63
	v_lshl_add_u64 v[212:213], s[52:53], 0, v[188:189]
	global_load_lds_dwordx4 v[210:211], off
	v_lshl_add_u64 v[210:211], s[64:65], 0, v[190:191]
	s_add_i32 m0, s63, 0x2000
	s_nop 0
	global_load_lds_dwordx4 v[210:211], off
	v_lshl_add_u64 v[210:211], s[52:53], 0, v[184:185]
	s_mov_b32 m0, s26
	s_nop 0
	global_load_lds_dwordx4 v[210:211], off
	s_mov_b32 m0, s27
	s_nop 0
	global_load_lds_dwordx4 v[212:213], off
	s_waitcnt vmcnt(8)
	s_waitcnt lgkmcnt(0)
	s_barrier
; #define PG8_STAGE(bufoff, gbase, voff) do { _Pragma("unroll") for (int _i = 0; _i < 2; ++_i) \
;         __builtin_amdgcn_global_load_lds((const unsigned*)((const char*)(gbase) + (voff)[_i]), (PG8_LAS unsigned*)(lds + (bufoff) + ldsw + _i * 8192), 16, 0, 0); } while (0)
; #define PG8_LDA(dst, b, h) do { _Pragma("unroll") for (int m = 0; m < 4; ++m) _Pragma("unroll") for (int k = 0; k < 2; ++k) dst[m][k] = *(const PG8_LAS bf16x8*)(lds + PG8_SA(b, h) + aoff + m * 2048 + k * 1024); } while (0)
; #define PG8_LDB(dst, b, h) do { _Pragma("unroll") for (int n = 0; n < 2; ++n) _Pragma("unroll") for (int k = 0; k < 2; ++k) dst[n][k] = *(const PG8_LAS bf16x8*)(lds + PG8_SB(b, h) + boff + n * 2048 + k * 1024); } while (0)
; #define PG8_MMA(ai, bj, At, Bt) do { __builtin_amdgcn_s_setprio(1); _Pragma("unroll") for (int m = 0; m < 4; ++m) _Pragma("unroll") for (int n = 0; n < 2; ++n) _Pragma("unroll") for (int k = 0; k < 2; ++k) \
;         acc[ai][bj][m][n] = __builtin_amdgcn_mfma_f32_16x16x32_bf16(Bt[n][k], At[m][k], acc[ai][bj][m][n], 0, 0, 0); __builtin_amdgcn_s_setprio(0); } while (0)
; #define PG8_WAIT_V(n) asm volatile("s_waitcnt vmcnt(" #n ")" ::: "memory")
; #define PG8_WAIT_L(n) asm volatile("s_waitcnt lgkmcnt(" #n ")" ::: "memory")
; #define PG8_BAR __builtin_amdgcn_s_barrier()
; #define PG8_SCHED __builtin_amdgcn_sched_barrier(0)
; template <class Epi, class Sched, bool ALIGN_EPI = false, bool SP2 = false>
; __device__ __forceinline__ void gemm_phase(PG8_LAS unsigned char* lds, const Gemm g, const Sched& S, const Epi& E) {
;     ...
;             PG8_WAIT_V(8); PG8_WAIT_L(0); PG8_BAR; PG8_MMA(1, 0, At, B0); PG8_MMA(1, 1, At, B1); PG8_BAR; PG8_SCHED;
;             PG8_LDB(B0, 1, 0); PG8_LDB(B1, 1, 1); PG8_SCHED; PG8_LDA(At, 1, 0); PG8_STAGE(PG8_SA(0, 1), a2 + hstep, voffA);
;             PG8_WAIT_V(8); PG8_WAIT_L(0); PG8_BAR; PG8_MMA(0, 0, At, B0); PG8_MMA(0, 1, At, B1); PG8_BAR; PG8_SCHED;
	s_setprio 1
	s_waitcnt lgkmcnt(0)
	v_mfma_f32_16x16x32_bf16 v[60:63], v[124:127], v[160:163], 0
	v_mfma_f32_16x16x32_bf16 v[56:59], v[136:139], v[160:163], 0
	v_mfma_f32_16x16x32_bf16 v[44:47], v[124:127], v[168:171], 0
	v_mfma_f32_16x16x32_bf16 v[40:43], v[136:139], v[168:171], 0
	v_mfma_f32_16x16x32_bf16 v[28:31], v[124:127], v[176:179], 0
	v_mfma_f32_16x16x32_bf16 v[24:27], v[136:139], v[176:179], 0
	v_mfma_f32_16x16x32_bf16 v[12:15], v[124:127], v[198:201], 0
	v_mfma_f32_16x16x32_bf16 v[8:11], v[136:139], v[198:201], 0
	v_mfma_f32_16x16x32_bf16 v[60:63], v[132:135], v[164:167], v[60:63]
	v_mfma_f32_16x16x32_bf16 v[56:59], v[140:143], v[164:167], v[56:59]
	v_mfma_f32_16x16x32_bf16 v[44:47], v[132:135], v[172:175], v[44:47]
	v_mfma_f32_16x16x32_bf16 v[40:43], v[140:143], v[172:175], v[40:43]
	v_mfma_f32_16x16x32_bf16 v[28:31], v[132:135], v[180:183], v[28:31]
	v_mfma_f32_16x16x32_bf16 v[24:27], v[140:143], v[180:183], v[24:27]
	v_mfma_f32_16x16x32_bf16 v[12:15], v[132:135], v[202:205], v[12:15]
	v_mfma_f32_16x16x32_bf16 v[8:11], v[140:143], v[202:205], v[8:11]
	s_setprio 0
	s_setprio 1
	v_mfma_f32_16x16x32_bf16 v[52:55], v[144:147], v[160:163], 0
	v_mfma_f32_16x16x32_bf16 v[48:51], v[152:155], v[160:163], 0
	v_mfma_f32_16x16x32_bf16 v[36:39], v[144:147], v[168:171], 0
	v_mfma_f32_16x16x32_bf16 v[32:35], v[152:155], v[168:171], 0
	v_mfma_f32_16x16x32_bf16 v[20:23], v[144:147], v[176:179], 0
	v_mfma_f32_16x16x32_bf16 v[16:19], v[152:155], v[176:179], 0
	v_mfma_f32_16x16x32_bf16 v[4:7], v[144:147], v[198:201], 0
	v_mfma_f32_16x16x32_bf16 v[0:3], v[152:155], v[198:201], 0
	v_mfma_f32_16x16x32_bf16 v[52:55], v[148:151], v[164:167], v[52:55]
	v_mfma_f32_16x16x32_bf16 v[48:51], v[156:159], v[164:167], v[48:51]
	v_mfma_f32_16x16x32_bf16 v[36:39], v[148:151], v[172:175], v[36:39]
	v_mfma_f32_16x16x32_bf16 v[32:35], v[156:159], v[172:175], v[32:35]
	v_mfma_f32_16x16x32_bf16 v[20:23], v[148:151], v[180:183], v[20:23]
	v_mfma_f32_16x16x32_bf16 v[16:19], v[156:159], v[180:183], v[16:19]
	v_mfma_f32_16x16x32_bf16 v[4:7], v[148:151], v[202:205], v[4:7]
	v_mfma_f32_16x16x32_bf16 v[0:3], v[156:159], v[202:205], v[0:3]
	s_setprio 0
	s_barrier
	s_add_i32 s63, 0, 0x18000
	s_add_i32 s64, 0, 0x1c000
	v_add_u32_e32 v140, s63, v232
	v_add_u32_e32 v156, s64, v232
	ds_read_b128 v[124:127], v140
	ds_read_b128 v[132:135], v140 offset:1024
	ds_read_b128 v[136:139], v140 offset:2048
	ds_read_b128 v[140:143], v140 offset:3072
	ds_read_b128 v[144:147], v156
	ds_read_b128 v[148:151], v156 offset:1024
	ds_read_b128 v[152:155], v156 offset:2048
	ds_read_b128 v[156:159], v156 offset:3072
	s_add_u32 s52, s52, 0x40000
	s_addc_u32 s53, s53, 0
	s_mov_b32 m0, s28
	v_lshl_add_u64 v[214:215], s[52:53], 0, v[184:185]
	ds_read_b128 v[160:163], v236 offset:32768
	ds_read_b128 v[164:167], v236 offset:33792
	ds_read_b128 v[168:171], v236 offset:34816
	ds_read_b128 v[172:175], v236 offset:35840
	ds_read_b128 v[176:179], v236 offset:36864
	ds_read_b128 v[180:183], v236 offset:37888
	ds_read_b128 v[198:201], v236 offset:38912
	ds_read_b128 v[202:205], v236 offset:39936
	global_load_lds_dwordx4 v[214:215], off
	v_lshl_add_u64 v[214:215], s[52:53], 0, v[188:189]
	s_mov_b32 m0, s29
	s_nop 0
	global_load_lds_dwordx4 v[214:215], off
	s_waitcnt vmcnt(8)
	s_waitcnt lgkmcnt(0)
	s_barrier
	s_setprio 1
	s_waitcnt lgkmcnt(0)
	v_mfma_f32_16x16x32_bf16 v[128:131], v[124:127], v[160:163], v[128:131]
	v_mfma_f32_16x16x32_bf16 v[120:123], v[136:139], v[160:163], v[120:123]
	v_mfma_f32_16x16x32_bf16 v[108:111], v[124:127], v[168:171], v[108:111]
	v_mfma_f32_16x16x32_bf16 v[104:107], v[136:139], v[168:171], v[104:107]
	v_mfma_f32_16x16x32_bf16 v[92:95], v[124:127], v[176:179], v[92:95]
	v_mfma_f32_16x16x32_bf16 v[88:91], v[136:139], v[176:179], v[88:91]
	v_mfma_f32_16x16x32_bf16 v[76:79], v[124:127], v[198:201], v[76:79]
	v_mfma_f32_16x16x32_bf16 v[72:75], v[136:139], v[198:201], v[72:75]
	v_mfma_f32_16x16x32_bf16 v[128:131], v[132:135], v[164:167], v[128:131]
	v_mfma_f32_16x16x32_bf16 v[120:123], v[140:143], v[164:167], v[120:123]
	v_mfma_f32_16x16x32_bf16 v[108:111], v[132:135], v[172:175], v[108:111]
	v_mfma_f32_16x16x32_bf16 v[104:107], v[140:143], v[172:175], v[104:107]
	v_mfma_f32_16x16x32_bf16 v[92:95], v[132:135], v[180:183], v[92:95]
	v_mfma_f32_16x16x32_bf16 v[88:91], v[140:143], v[180:183], v[88:91]
	v_mfma_f32_16x16x32_bf16 v[76:79], v[132:135], v[202:205], v[76:79]
	v_mfma_f32_16x16x32_bf16 v[72:75], v[140:143], v[202:205], v[72:75]
	s_setprio 0
	s_setprio 1
	v_mfma_f32_16x16x32_bf16 v[116:119], v[144:147], v[160:163], v[116:119]
	v_mfma_f32_16x16x32_bf16 v[112:115], v[152:155], v[160:163], v[112:115]
	v_mfma_f32_16x16x32_bf16 v[100:103], v[144:147], v[168:171], v[100:103]
	v_mfma_f32_16x16x32_bf16 v[96:99], v[152:155], v[168:171], v[96:99]
	v_mfma_f32_16x16x32_bf16 v[84:87], v[144:147], v[176:179], v[84:87]
	v_mfma_f32_16x16x32_bf16 v[80:83], v[152:155], v[176:179], v[80:83]
	v_mfma_f32_16x16x32_bf16 v[68:71], v[144:147], v[198:201], v[68:71]
	v_mfma_f32_16x16x32_bf16 v[64:67], v[152:155], v[198:201], v[64:67]
	v_mfma_f32_16x16x32_bf16 v[116:119], v[148:151], v[164:167], v[116:119]
	v_mfma_f32_16x16x32_bf16 v[112:115], v[156:159], v[164:167], v[112:115]
	v_mfma_f32_16x16x32_bf16 v[100:103], v[148:151], v[172:175], v[100:103]
	v_mfma_f32_16x16x32_bf16 v[96:99], v[156:159], v[172:175], v[96:99]
	v_mfma_f32_16x16x32_bf16 v[84:87], v[148:151], v[180:183], v[84:87]
	v_mfma_f32_16x16x32_bf16 v[80:83], v[156:159], v[180:183], v[80:83]
	v_mfma_f32_16x16x32_bf16 v[68:71], v[148:151], v[202:205], v[68:71]
	v_mfma_f32_16x16x32_bf16 v[64:67], v[156:159], v[202:205], v[64:67]
	s_setprio 0
	s_barrier
; #define PG8_STAGE(bufoff, gbase, voff) do { _Pragma("unroll") for (int _i = 0; _i < 2; ++_i) \
;         __builtin_amdgcn_global_load_lds((const unsigned*)((const char*)(gbase) + (voff)[_i]), (PG8_LAS unsigned*)(lds + (bufoff) + ldsw + _i * 8192), 16, 0, 0); } while (0)
; #define PG8_LDA(dst, b, h) do { _Pragma("unroll") for (int m = 0; m < 4; ++m) _Pragma("unroll") for (int k = 0; k < 2; ++k) dst[m][k] = *(const PG8_LAS bf16x8*)(lds + PG8_SA(b, h) + aoff + m * 2048 + k * 1024); } while (0)
; #define PG8_MMA(ai, bj, At, Bt) do { __builtin_amdgcn_s_setprio(1); _Pragma("unroll") for (int m = 0; m < 4; ++m) _Pragma("unroll") for (int n = 0; n < 2; ++n) _Pragma("unroll") for (int k = 0; k < 2; ++k) \
;         acc[ai][bj][m][n] = __builtin_amdgcn_mfma_f32_16x16x32_bf16(Bt[n][k], At[m][k], acc[ai][bj][m][n], 0, 0, 0); __builtin_amdgcn_s_setprio(0); } while (0)
; #define PG8_WAIT_V(n) asm volatile("s_waitcnt vmcnt(" #n ")" ::: "memory")
; #define PG8_WAIT_L(n) asm volatile("s_waitcnt lgkmcnt(" #n ")" ::: "memory")
; #define PG8_BAR __builtin_amdgcn_s_barrier()
; #define PG8_SCHED __builtin_amdgcn_sched_barrier(0)
; template <class Epi, class Sched, bool ALIGN_EPI = false, bool SP2 = false>
; __device__ __forceinline__ void gemm_phase(PG8_LAS unsigned char* lds, const Gemm g, const Sched& S, const Epi& E) {
;     ...
;             PG8_LDA(At, 1, 1); PG8_STAGE(PG8_SB(1, 0), b3, voffB); PG8_STAGE(PG8_SB(1, 1), b3 + hstep, voffB); PG8_STAGE(PG8_SA(1, 0), a3, voffA);
;             PG8_WAIT_V(8); PG8_WAIT_L(0); PG8_BAR; PG8_MMA(1, 0, At, B0); PG8_MMA(1, 1, At, B1); PG8_BAR; PG8_SCHED;
	s_add_i32 s52, s63, s25
	v_lshl_add_u64 v[206:207], v[206:207], 0, s[18:19]
	s_mov_b32 m0, s52
	ds_read_b128 v[160:163], v236 offset:49152
	ds_read_b128 v[164:167], v236 offset:50176
	ds_read_b128 v[168:171], v236 offset:51200
	ds_read_b128 v[172:175], v236 offset:52224
	ds_read_b128 v[176:179], v236 offset:53248
	ds_read_b128 v[180:183], v236 offset:54272
	ds_read_b128 v[198:201], v236 offset:55296
	ds_read_b128 v[202:205], v236 offset:56320
	global_load_lds_dwordx4 v[206:207], off
	s_add_i32 m0, s52, 0x2000
	s_add_u32 s50, s50, 0x40080
	v_lshl_add_u64 v[206:207], v[208:209], 0, s[18:19]
	s_addc_u32 s51, s51, 0
	s_add_i32 s52, s64, s25
	global_load_lds_dwordx4 v[206:207], off
	v_lshl_add_u64 v[206:207], s[50:51], 0, v[186:187]
	s_mov_b32 m0, s52
	s_nop 0
	global_load_lds_dwordx4 v[206:207], off
	v_lshl_add_u64 v[206:207], s[50:51], 0, v[190:191]
	s_add_i32 m0, s52, 0x2000
	s_nop 0
	global_load_lds_dwordx4 v[206:207], off
	v_lshl_add_u64 v[206:207], v[210:211], 0, s[18:19]
	s_mov_b32 m0, s31
	s_nop 0
	global_load_lds_dwordx4 v[206:207], off
	v_lshl_add_u64 v[206:207], v[212:213], 0, s[18:19]
	s_mov_b32 m0, s33
	s_nop 0
	global_load_lds_dwordx4 v[206:207], off
	s_waitcnt vmcnt(8)
	s_waitcnt lgkmcnt(0)
	s_barrier
	s_setprio 1
	s_waitcnt lgkmcnt(0)
	v_mfma_f32_16x16x32_bf16 v[60:63], v[124:127], v[160:163], v[60:63]
	v_mfma_f32_16x16x32_bf16 v[56:59], v[136:139], v[160:163], v[56:59]
	v_mfma_f32_16x16x32_bf16 v[44:47], v[124:127], v[168:171], v[44:47]
	v_mfma_f32_16x16x32_bf16 v[40:43], v[136:139], v[168:171], v[40:43]
	v_mfma_f32_16x16x32_bf16 v[28:31], v[124:127], v[176:179], v[28:31]
	v_mfma_f32_16x16x32_bf16 v[24:27], v[136:139], v[176:179], v[24:27]
	v_mfma_f32_16x16x32_bf16 v[12:15], v[124:127], v[198:201], v[12:15]
	v_mfma_f32_16x16x32_bf16 v[8:11], v[136:139], v[198:201], v[8:11]
	v_mfma_f32_16x16x32_bf16 v[60:63], v[132:135], v[164:167], v[60:63]
	v_mfma_f32_16x16x32_bf16 v[56:59], v[140:143], v[164:167], v[56:59]
	v_mfma_f32_16x16x32_bf16 v[44:47], v[132:135], v[172:175], v[44:47]
	v_mfma_f32_16x16x32_bf16 v[40:43], v[140:143], v[172:175], v[40:43]
	v_mfma_f32_16x16x32_bf16 v[28:31], v[132:135], v[180:183], v[28:31]
	v_mfma_f32_16x16x32_bf16 v[24:27], v[140:143], v[180:183], v[24:27]
	v_mfma_f32_16x16x32_bf16 v[12:15], v[132:135], v[202:205], v[12:15]
	v_mfma_f32_16x16x32_bf16 v[8:11], v[140:143], v[202:205], v[8:11]
	s_setprio 0
	s_setprio 1
	v_mfma_f32_16x16x32_bf16 v[52:55], v[144:147], v[160:163], v[52:55]
	v_mfma_f32_16x16x32_bf16 v[48:51], v[152:155], v[160:163], v[48:51]
	v_mfma_f32_16x16x32_bf16 v[36:39], v[144:147], v[168:171], v[36:39]
	v_mfma_f32_16x16x32_bf16 v[32:35], v[152:155], v[168:171], v[32:35]
	v_mfma_f32_16x16x32_bf16 v[20:23], v[144:147], v[176:179], v[20:23]
	v_mfma_f32_16x16x32_bf16 v[16:19], v[152:155], v[176:179], v[16:19]
	v_mfma_f32_16x16x32_bf16 v[4:7], v[144:147], v[198:201], v[4:7]
	v_mfma_f32_16x16x32_bf16 v[0:3], v[152:155], v[198:201], v[0:3]
	v_mfma_f32_16x16x32_bf16 v[52:55], v[148:151], v[164:167], v[52:55]
	v_mfma_f32_16x16x32_bf16 v[48:51], v[156:159], v[164:167], v[48:51]
	v_mfma_f32_16x16x32_bf16 v[36:39], v[148:151], v[172:175], v[36:39]
	v_mfma_f32_16x16x32_bf16 v[32:35], v[156:159], v[172:175], v[32:35]
	v_mfma_f32_16x16x32_bf16 v[20:23], v[148:151], v[180:183], v[20:23]
	v_mfma_f32_16x16x32_bf16 v[16:19], v[156:159], v[180:183], v[16:19]
	v_mfma_f32_16x16x32_bf16 v[4:7], v[148:151], v[202:205], v[4:7]
	v_mfma_f32_16x16x32_bf16 v[0:3], v[156:159], v[202:205], v[0:3]
	s_setprio 0
	s_barrier
	s_add_i32 s62, s62, 2
	s_add_u32 s48, s48, 0x100
	s_addc_u32 s49, s49, 0
	s_add_u32 s60, s60, 0x100
	s_addc_u32 s61, s61, 0
	s_cmp_gt_u32 s62, 13

; #define PG8_STAGE(bufoff, gbase, voff) do { _Pragma("unroll") for (int _i = 0; _i < 2; ++_i) \
;         __builtin_amdgcn_global_load_lds((const unsigned*)((const char*)(gbase) + (voff)[_i]), (PG8_LAS unsigned*)(lds + (bufoff) + ldsw + _i * 8192), 16, 0, 0); } while (0)
; #define PG8_LDA(dst, b, h) do { _Pragma("unroll") for (int m = 0; m < 4; ++m) _Pragma("unroll") for (int k = 0; k < 2; ++k) dst[m][k] = *(const PG8_LAS bf16x8*)(lds + PG8_SA(b, h) + aoff + m * 2048 + k * 1024); } while (0)
; #define PG8_LDB(dst, b, h) do { _Pragma("unroll") for (int n = 0; n < 2; ++n) _Pragma("unroll") for (int k = 0; k < 2; ++k) dst[n][k] = *(const PG8_LAS bf16x8*)(lds + PG8_SB(b, h) + boff + n * 2048 + k * 1024); } while (0)
; #define PG8_WAIT_V(n) asm volatile("s_waitcnt vmcnt(" #n ")" ::: "memory")
; #define PG8_WAIT_L(n) asm volatile("s_waitcnt lgkmcnt(" #n ")" ::: "memory")
; #define PG8_BAR __builtin_amdgcn_s_barrier()
; #define PG8_SCHED __builtin_amdgcn_sched_barrier(0)
; template <class Epi, class Sched, bool ALIGN_EPI = false, bool SP2 = false>
; __device__ __forceinline__ void gemm_phase(PG8_LAS unsigned char* lds, const Gemm g, const Sched& S, const Epi& E) {
;     ...
;         const char* nA = has_next ? (const char*)g.A + (size_t)nxt.pm * tstep : cA; const char* nB = has_next ? (const char*)g.Bt + (size_t)nxt.pn * tstep : cB;
;         for (int t = 0; t < nt; t += 2) {
;             const bool last = (t == nt - 2);
;             const char* a1 = cA + (size_t)(t + 1) * kstep;
;             const char* a2 = last ? nA : cA + (size_t)(t + 2) * kstep; const char* b2 = last ? nB : cB + (size_t)(t + 2) * kstep;
;             const char* a3 = a2 + kstep; const char* b3 = b2 + kstep;
;             if (last && has_next) S.a_ready(nxt);
;             if constexpr (SP2) {
;             PG8_LDB(B0, 0, 0); PG8_LDB(B1, 0, 1); PG8_SCHED; PG8_LDA(At, 0, 0); PG8_STAGE(PG8_SA(1, 1), a1 + hstep, voffA);
;             PG8_WAIT_V(8); PG8_WAIT_L(0); PG8_BAR; PG8_MMA(0, 0, At, B0); PG8_MMA(0, 1, At, B1); PG8_BAR; PG8_SCHED;
;             PG8_LDA(At, 0, 1); PG8_STAGE(PG8_SB(0, 0), b2, voffB); PG8_STAGE(PG8_SB(0, 1), b2 + hstep, voffB); PG8_STAGE(PG8_SA(0, 0), a2, voffA);
;             PG8_WAIT_V(8); PG8_WAIT_L(0); PG8_BAR; PG8_MMA(1, 0, At, B0); PG8_MMA(1, 1, At, B1); PG8_BAR; PG8_SCHED;
.LBB0_481:
	s_ashr_i32 s19, s18, 31
	s_lshl_b64 s[36:37], s[18:19], 19
	s_add_u32 s36, s70, s36
	s_addc_u32 s37, s71, s37
	s_and_b64 s[38:39], s[20:21], exec
	s_cselect_b32 s19, s37, s43
	s_cselect_b32 s55, s36, s42
	s_ashr_i32 s17, s16, 31
	s_lshl_b64 s[38:39], s[16:17], 19
	s_add_u32 s38, s23, s38
	s_addc_u32 s39, s24, s39
	s_and_b64 s[46:47], s[20:21], exec
	s_cselect_b32 s17, s39, s45
	s_cselect_b32 s56, s38, s44
	s_add_u32 s42, s42, 0x40080
	s_addc_u32 s43, s43, 0
	s_add_u32 s57, s44, 0x100
	s_addc_u32 s58, s45, 0
	s_mov_b32 s59, -2
	ds_read_b128 v[144:147], v161
	ds_read_b128 v[170:173], v161 offset:1024
	ds_read_b128 v[178:181], v161 offset:2048
	ds_read_b128 v[182:185], v161 offset:3072
	ds_read_b128 v[186:189], v165
	ds_read_b128 v[190:193], v165 offset:1024
	ds_read_b128 v[194:197], v165 offset:2048
	ds_read_b128 v[198:201], v165 offset:3072
	s_add_u32 s44, s42, 0xfffc0080
	s_addc_u32 s45, s43, -1
	s_cmp_eq_u32 s59, 12
	s_cselect_b32 s47, s19, s45
	s_cselect_b32 s46, s55, s44
	s_cselect_b32 s45, s17, s58
	s_cselect_b32 s44, s56, s57
	v_lshl_add_u64 v[150:151], s[42:43], 0, v[138:139]
	s_add_i32 m0, s28, 0xc000
	ds_read_b128 v[202:205], v169
	ds_read_b128 v[206:209], v169 offset:1024
	ds_read_b128 v[210:213], v169 offset:2048
	ds_read_b128 v[214:217], v169 offset:3072
	ds_read_b128 v[218:221], v169 offset:4096
	ds_read_b128 v[222:225], v169 offset:5120
	ds_read_b128 v[226:229], v169 offset:6144
	ds_read_b128 v[232:235], v169 offset:7168
	global_load_lds_dwordx4 v[150:151], off
	v_lshl_add_u64 v[150:151], s[42:43], 0, v[140:141]
	s_add_i32 m0, s28, 0xe000
	s_nop 0
	global_load_lds_dwordx4 v[150:151], off
	s_waitcnt vmcnt(8)
	s_waitcnt lgkmcnt(0)
	s_barrier
	s_setprio 1
	s_waitcnt lgkmcnt(0)
	v_mfma_f32_16x16x32_bf16 v[124:127], v[144:147], v[202:205], 0
	v_mfma_f32_16x16x32_bf16 v[116:119], v[178:181], v[202:205], 0
	v_mfma_f32_16x16x32_bf16 v[108:111], v[144:147], v[210:213], 0
	v_mfma_f32_16x16x32_bf16 v[100:103], v[178:181], v[210:213], 0
	v_mfma_f32_16x16x32_bf16 v[92:95], v[144:147], v[218:221], 0
	v_mfma_f32_16x16x32_bf16 v[84:87], v[178:181], v[218:221], 0
	v_mfma_f32_16x16x32_bf16 v[76:79], v[144:147], v[226:229], 0
	v_mfma_f32_16x16x32_bf16 v[68:71], v[178:181], v[226:229], 0
	v_mfma_f32_16x16x32_bf16 v[124:127], v[170:173], v[206:209], v[124:127]
	v_mfma_f32_16x16x32_bf16 v[116:119], v[182:185], v[206:209], v[116:119]
	v_mfma_f32_16x16x32_bf16 v[108:111], v[170:173], v[214:217], v[108:111]
	v_mfma_f32_16x16x32_bf16 v[100:103], v[182:185], v[214:217], v[100:103]
	v_mfma_f32_16x16x32_bf16 v[92:95], v[170:173], v[222:225], v[92:95]
	v_mfma_f32_16x16x32_bf16 v[84:87], v[182:185], v[222:225], v[84:87]
	v_mfma_f32_16x16x32_bf16 v[76:79], v[170:173], v[232:235], v[76:79]
	v_mfma_f32_16x16x32_bf16 v[68:71], v[182:185], v[232:235], v[68:71]
	s_setprio 0
	s_setprio 1
	v_mfma_f32_16x16x32_bf16 v[120:123], v[186:189], v[202:205], 0
	v_mfma_f32_16x16x32_bf16 v[112:115], v[194:197], v[202:205], 0
	v_mfma_f32_16x16x32_bf16 v[104:107], v[186:189], v[210:213], 0
	v_mfma_f32_16x16x32_bf16 v[96:99], v[194:197], v[210:213], 0
	v_mfma_f32_16x16x32_bf16 v[88:91], v[186:189], v[218:221], 0
	v_mfma_f32_16x16x32_bf16 v[80:83], v[194:197], v[218:221], 0
	v_mfma_f32_16x16x32_bf16 v[72:75], v[186:189], v[226:229], 0
	v_mfma_f32_16x16x32_bf16 v[64:67], v[194:197], v[226:229], 0
	v_mfma_f32_16x16x32_bf16 v[120:123], v[190:193], v[206:209], v[120:123]
	v_mfma_f32_16x16x32_bf16 v[112:115], v[198:201], v[206:209], v[112:115]
	v_mfma_f32_16x16x32_bf16 v[104:107], v[190:193], v[214:217], v[104:107]
	v_mfma_f32_16x16x32_bf16 v[96:99], v[198:201], v[214:217], v[96:99]
	v_mfma_f32_16x16x32_bf16 v[88:91], v[190:193], v[222:225], v[88:91]
	v_mfma_f32_16x16x32_bf16 v[80:83], v[198:201], v[222:225], v[80:83]
	v_mfma_f32_16x16x32_bf16 v[72:75], v[190:193], v[232:235], v[72:75]
	v_mfma_f32_16x16x32_bf16 v[64:67], v[198:201], v[232:235], v[64:67]
	s_setprio 0
	s_barrier
	s_add_i32 s60, s51, s25
	v_lshl_add_u64 v[150:151], s[44:45], 0, v[130:131]
	s_mov_b32 m0, s60
	ds_read_b128 v[202:205], v169 offset:16384
	ds_read_b128 v[206:209], v169 offset:17408
	ds_read_b128 v[210:213], v169 offset:18432
	ds_read_b128 v[214:217], v169 offset:19456
	ds_read_b128 v[218:221], v169 offset:20480
	ds_read_b128 v[222:225], v169 offset:21504
	ds_read_b128 v[226:229], v169 offset:22528
	ds_read_b128 v[232:235], v169 offset:23552
	global_load_lds_dwordx4 v[150:151], off
	s_add_i32 m0, s60, 0x2000
	s_add_u32 s60, s44, 0x40000
	v_lshl_add_u64 v[154:155], s[44:45], 0, v[134:135]
	s_addc_u32 s61, s45, 0
	s_add_i32 s62, s52, s25
	global_load_lds_dwordx4 v[154:155], off
	v_lshl_add_u64 v[158:159], s[60:61], 0, v[130:131]
	s_mov_b32 m0, s62
	v_lshl_add_u64 v[162:163], s[46:47], 0, v[132:133]
	global_load_lds_dwordx4 v[158:159], off
	v_lshl_add_u64 v[158:159], s[60:61], 0, v[134:135]
	s_add_i32 m0, s62, 0x2000
	s_nop 0
	global_load_lds_dwordx4 v[158:159], off
	v_lshl_add_u64 v[158:159], s[46:47], 0, v[128:129]
	s_mov_b32 m0, s28
	s_nop 0
	global_load_lds_dwordx4 v[158:159], off
	s_mov_b32 m0, s29
	s_nop 0
	global_load_lds_dwordx4 v[162:163], off
	s_cmp_lg_i32 s59, -2
	s_cbranch_scc1 .Lrsa_a_pl
	v_lshrrev_b32_e32 v250, 6, v230
	v_lshlrev_b32_e32 v250, 11, v250
	v_and_b32_e32 v251, 63, v230
	v_lshl_or_b32 v250, v251, 4, v250
	v_lshl_add_u32 v250, s40, 14, v250
	v_readfirstlane_b32 s98, v230
	s_lshr_b32 s98, s98, 6
	s_lshl_b32 s98, s98, 11
	s_add_i32 m0, s98, 0x20000
	s_add_u32 s100, s70, 0x3f000000
	s_addc_u32 s101, s71, 0
	global_load_lds_dwordx4 v250, s[100:101]
	global_load_lds_dwordx4 v250, s[100:101] offset:1024
	s_waitcnt vmcnt(10)
	s_branch .Lrsa_b_pl

; #define PG8_STAGE(bufoff, gbase, voff) do { _Pragma("unroll") for (int _i = 0; _i < 2; ++_i) \
;         __builtin_amdgcn_global_load_lds((const unsigned*)((const char*)(gbase) + (voff)[_i]), (PG8_LAS unsigned*)(lds + (bufoff) + ldsw + _i * 8192), 16, 0, 0); } while (0)
; #define PG8_LDA(dst, b, h) do { _Pragma("unroll") for (int m = 0; m < 4; ++m) _Pragma("unroll") for (int k = 0; k < 2; ++k) dst[m][k] = *(const PG8_LAS bf16x8*)(lds + PG8_SA(b, h) + aoff + m * 2048 + k * 1024); } while (0)
; #define PG8_LDB(dst, b, h) do { _Pragma("unroll") for (int n = 0; n < 2; ++n) _Pragma("unroll") for (int k = 0; k < 2; ++k) dst[n][k] = *(const PG8_LAS bf16x8*)(lds + PG8_SB(b, h) + boff + n * 2048 + k * 1024); } while (0)
; #define PG8_MMA(ai, bj, At, Bt) do { __builtin_amdgcn_s_setprio(1); _Pragma("unroll") for (int m = 0; m < 4; ++m) _Pragma("unroll") for (int n = 0; n < 2; ++n) _Pragma("unroll") for (int k = 0; k < 2; ++k) \
;         acc[ai][bj][m][n] = __builtin_amdgcn_mfma_f32_16x16x32_bf16(Bt[n][k], At[m][k], acc[ai][bj][m][n], 0, 0, 0); __builtin_amdgcn_s_setprio(0); } while (0)
; #define PG8_WAIT_V(n) asm volatile("s_waitcnt vmcnt(" #n ")" ::: "memory")
; #define PG8_WAIT_L(n) asm volatile("s_waitcnt lgkmcnt(" #n ")" ::: "memory")
; #define PG8_BAR __builtin_amdgcn_s_barrier()
; #define PG8_SCHED __builtin_amdgcn_sched_barrier(0)
; template <class Epi, class Sched, bool ALIGN_EPI = false, bool SP2 = false>
; __device__ __forceinline__ void gemm_phase(PG8_LAS unsigned char* lds, const Gemm g, const Sched& S, const Epi& E) {
;     ...
;             PG8_WAIT_V(8); PG8_WAIT_L(0); PG8_BAR; PG8_MMA(1, 0, At, B0); PG8_MMA(1, 1, At, B1); PG8_BAR; PG8_SCHED;
;             PG8_LDB(B0, 1, 0); PG8_LDB(B1, 1, 1); PG8_SCHED; PG8_LDA(At, 1, 0); PG8_STAGE(PG8_SA(0, 1), a2 + hstep, voffA);
;             PG8_WAIT_V(8); PG8_WAIT_L(0); PG8_BAR; PG8_MMA(0, 0, At, B0); PG8_MMA(0, 1, At, B1); PG8_BAR; PG8_SCHED;
.Lrsa_b_pl:
	s_waitcnt lgkmcnt(0)
	s_barrier
	s_setprio 1
	s_waitcnt lgkmcnt(0)
	v_mfma_f32_16x16x32_bf16 v[60:63], v[144:147], v[202:205], 0
	v_mfma_f32_16x16x32_bf16 v[52:55], v[178:181], v[202:205], 0
	v_mfma_f32_16x16x32_bf16 v[44:47], v[144:147], v[210:213], 0
	v_mfma_f32_16x16x32_bf16 v[36:39], v[178:181], v[210:213], 0
	v_mfma_f32_16x16x32_bf16 v[28:31], v[144:147], v[218:221], 0
	v_mfma_f32_16x16x32_bf16 v[20:23], v[178:181], v[218:221], 0
	v_mfma_f32_16x16x32_bf16 v[12:15], v[144:147], v[226:229], 0
	v_mfma_f32_16x16x32_bf16 v[4:7], v[178:181], v[226:229], 0
	v_mfma_f32_16x16x32_bf16 v[60:63], v[170:173], v[206:209], v[60:63]
	v_mfma_f32_16x16x32_bf16 v[52:55], v[182:185], v[206:209], v[52:55]
	v_mfma_f32_16x16x32_bf16 v[44:47], v[170:173], v[214:217], v[44:47]
	v_mfma_f32_16x16x32_bf16 v[36:39], v[182:185], v[214:217], v[36:39]
	v_mfma_f32_16x16x32_bf16 v[28:31], v[170:173], v[222:225], v[28:31]
	v_mfma_f32_16x16x32_bf16 v[20:23], v[182:185], v[222:225], v[20:23]
	v_mfma_f32_16x16x32_bf16 v[12:15], v[170:173], v[232:235], v[12:15]
	v_mfma_f32_16x16x32_bf16 v[4:7], v[182:185], v[232:235], v[4:7]
	s_setprio 0
	s_setprio 1
	v_mfma_f32_16x16x32_bf16 v[56:59], v[186:189], v[202:205], 0
	v_mfma_f32_16x16x32_bf16 v[48:51], v[194:197], v[202:205], 0
	v_mfma_f32_16x16x32_bf16 v[40:43], v[186:189], v[210:213], 0
	v_mfma_f32_16x16x32_bf16 v[32:35], v[194:197], v[210:213], 0
	v_mfma_f32_16x16x32_bf16 v[24:27], v[186:189], v[218:221], 0
	v_mfma_f32_16x16x32_bf16 v[16:19], v[194:197], v[218:221], 0
	v_mfma_f32_16x16x32_bf16 v[8:11], v[186:189], v[226:229], 0
	v_mfma_f32_16x16x32_bf16 v[0:3], v[194:197], v[226:229], 0
	v_mfma_f32_16x16x32_bf16 v[56:59], v[190:193], v[206:209], v[56:59]
	v_mfma_f32_16x16x32_bf16 v[48:51], v[198:201], v[206:209], v[48:51]
	v_mfma_f32_16x16x32_bf16 v[40:43], v[190:193], v[214:217], v[40:43]
	v_mfma_f32_16x16x32_bf16 v[32:35], v[198:201], v[214:217], v[32:35]
	v_mfma_f32_16x16x32_bf16 v[24:27], v[190:193], v[222:225], v[24:27]
	v_mfma_f32_16x16x32_bf16 v[16:19], v[198:201], v[222:225], v[16:19]
	v_mfma_f32_16x16x32_bf16 v[8:11], v[190:193], v[232:235], v[8:11]
	v_mfma_f32_16x16x32_bf16 v[0:3], v[198:201], v[232:235], v[0:3]
	s_setprio 0
	s_barrier
	s_add_i32 s60, 0, 0x18000
	v_add_u32_e32 v148, s60, v153
	s_add_i32 s61, 0, 0x1c000
	ds_read_b128 v[144:147], v148
	ds_read_b128 v[170:173], v148 offset:1024
	ds_read_b128 v[178:181], v148 offset:2048
	ds_read_b128 v[182:185], v148 offset:3072
	v_add_u32_e32 v148, s61, v153
	ds_read_b128 v[186:189], v148
	ds_read_b128 v[190:193], v148 offset:1024
	ds_read_b128 v[194:197], v148 offset:2048
	ds_read_b128 v[198:201], v148 offset:3072
	s_add_u32 s46, s46, 0x40000
	s_addc_u32 s47, s47, 0
	s_mov_b32 m0, s30
	v_lshl_add_u64 v[166:167], s[46:47], 0, v[128:129]
	ds_read_b128 v[202:205], v169 offset:32768
	ds_read_b128 v[206:209], v169 offset:33792
	ds_read_b128 v[210:213], v169 offset:34816
	ds_read_b128 v[214:217], v169 offset:35840
	ds_read_b128 v[218:221], v169 offset:36864
	ds_read_b128 v[222:225], v169 offset:37888
	ds_read_b128 v[226:229], v169 offset:38912
	ds_read_b128 v[232:235], v169 offset:39936
	global_load_lds_dwordx4 v[166:167], off
	v_lshl_add_u64 v[166:167], s[46:47], 0, v[132:133]
	s_mov_b32 m0, s31
	s_nop 0
	global_load_lds_dwordx4 v[166:167], off
	s_cmp_lg_i32 s59, -2
	s_cbranch_scc1 .Lrsa_c_pl
	s_waitcnt vmcnt(10)
	s_branch .Lrsa_d_pl

; #define PG8_STAGE(bufoff, gbase, voff) do { _Pragma("unroll") for (int _i = 0; _i < 2; ++_i) \
;         __builtin_amdgcn_global_load_lds((const unsigned*)((const char*)(gbase) + (voff)[_i]), (PG8_LAS unsigned*)(lds + (bufoff) + ldsw + _i * 8192), 16, 0, 0); } while (0)
; #define PG8_LDA(dst, b, h) do { _Pragma("unroll") for (int m = 0; m < 4; ++m) _Pragma("unroll") for (int k = 0; k < 2; ++k) dst[m][k] = *(const PG8_LAS bf16x8*)(lds + PG8_SA(b, h) + aoff + m * 2048 + k * 1024); } while (0)
; #define PG8_MMA(ai, bj, At, Bt) do { __builtin_amdgcn_s_setprio(1); _Pragma("unroll") for (int m = 0; m < 4; ++m) _Pragma("unroll") for (int n = 0; n < 2; ++n) _Pragma("unroll") for (int k = 0; k < 2; ++k) \
;         acc[ai][bj][m][n] = __builtin_amdgcn_mfma_f32_16x16x32_bf16(Bt[n][k], At[m][k], acc[ai][bj][m][n], 0, 0, 0); __builtin_amdgcn_s_setprio(0); } while (0)
; #define PG8_WAIT_V(n) asm volatile("s_waitcnt vmcnt(" #n ")" ::: "memory")
; #define PG8_WAIT_L(n) asm volatile("s_waitcnt lgkmcnt(" #n ")" ::: "memory")
; #define PG8_BAR __builtin_amdgcn_s_barrier()
; #define PG8_SCHED __builtin_amdgcn_sched_barrier(0)
; template <class Epi, class Sched, bool ALIGN_EPI = false, bool SP2 = false>
; __device__ __forceinline__ void gemm_phase(PG8_LAS unsigned char* lds, const Gemm g, const Sched& S, const Epi& E) {
;     ...
;             PG8_WAIT_V(8); PG8_WAIT_L(0); PG8_BAR; PG8_MMA(0, 0, At, B0); PG8_MMA(0, 1, At, B1); PG8_BAR; PG8_SCHED;
;             PG8_LDA(At, 1, 1); PG8_STAGE(PG8_SB(1, 0), b3, voffB); PG8_STAGE(PG8_SB(1, 1), b3 + hstep, voffB); PG8_STAGE(PG8_SA(1, 0), a3, voffA);
;             PG8_WAIT_V(8); PG8_WAIT_L(0); PG8_BAR; PG8_MMA(1, 0, At, B0); PG8_MMA(1, 1, At, B1); PG8_BAR; PG8_SCHED;
.Lrsa_d_pl:
	s_waitcnt lgkmcnt(0)
	s_barrier
	s_setprio 1
	s_waitcnt lgkmcnt(0)
	v_mfma_f32_16x16x32_bf16 v[124:127], v[144:147], v[202:205], v[124:127]
	v_mfma_f32_16x16x32_bf16 v[116:119], v[178:181], v[202:205], v[116:119]
	v_mfma_f32_16x16x32_bf16 v[108:111], v[144:147], v[210:213], v[108:111]
	v_mfma_f32_16x16x32_bf16 v[100:103], v[178:181], v[210:213], v[100:103]
	v_mfma_f32_16x16x32_bf16 v[92:95], v[144:147], v[218:221], v[92:95]
	v_mfma_f32_16x16x32_bf16 v[84:87], v[178:181], v[218:221], v[84:87]
	v_mfma_f32_16x16x32_bf16 v[76:79], v[144:147], v[226:229], v[76:79]
	v_mfma_f32_16x16x32_bf16 v[68:71], v[178:181], v[226:229], v[68:71]
	v_mfma_f32_16x16x32_bf16 v[124:127], v[170:173], v[206:209], v[124:127]
	v_mfma_f32_16x16x32_bf16 v[116:119], v[182:185], v[206:209], v[116:119]
	v_mfma_f32_16x16x32_bf16 v[108:111], v[170:173], v[214:217], v[108:111]
	v_mfma_f32_16x16x32_bf16 v[100:103], v[182:185], v[214:217], v[100:103]
	v_mfma_f32_16x16x32_bf16 v[92:95], v[170:173], v[222:225], v[92:95]
	v_mfma_f32_16x16x32_bf16 v[84:87], v[182:185], v[222:225], v[84:87]
	v_mfma_f32_16x16x32_bf16 v[76:79], v[170:173], v[232:235], v[76:79]
	v_mfma_f32_16x16x32_bf16 v[68:71], v[182:185], v[232:235], v[68:71]
	s_setprio 0
	s_setprio 1
	v_mfma_f32_16x16x32_bf16 v[120:123], v[186:189], v[202:205], v[120:123]
	v_mfma_f32_16x16x32_bf16 v[112:115], v[194:197], v[202:205], v[112:115]
	v_mfma_f32_16x16x32_bf16 v[104:107], v[186:189], v[210:213], v[104:107]
	v_mfma_f32_16x16x32_bf16 v[96:99], v[194:197], v[210:213], v[96:99]
	v_mfma_f32_16x16x32_bf16 v[88:91], v[186:189], v[218:221], v[88:91]
	v_mfma_f32_16x16x32_bf16 v[80:83], v[194:197], v[218:221], v[80:83]
	v_mfma_f32_16x16x32_bf16 v[72:75], v[186:189], v[226:229], v[72:75]
	v_mfma_f32_16x16x32_bf16 v[64:67], v[194:197], v[226:229], v[64:67]
	v_mfma_f32_16x16x32_bf16 v[120:123], v[190:193], v[206:209], v[120:123]
	v_mfma_f32_16x16x32_bf16 v[112:115], v[198:201], v[206:209], v[112:115]
	v_mfma_f32_16x16x32_bf16 v[104:107], v[190:193], v[214:217], v[104:107]
	v_mfma_f32_16x16x32_bf16 v[96:99], v[198:201], v[214:217], v[96:99]
	v_mfma_f32_16x16x32_bf16 v[88:91], v[190:193], v[222:225], v[88:91]
	v_mfma_f32_16x16x32_bf16 v[80:83], v[198:201], v[222:225], v[80:83]
	v_mfma_f32_16x16x32_bf16 v[72:75], v[190:193], v[232:235], v[72:75]
	v_mfma_f32_16x16x32_bf16 v[64:67], v[198:201], v[232:235], v[64:67]
	s_setprio 0
	s_barrier
	s_add_i32 s46, s60, s25
	v_lshl_add_u64 v[150:151], v[150:151], 0, s[8:9]
	s_mov_b32 m0, s46
	ds_read_b128 v[202:205], v169 offset:49152
	ds_read_b128 v[206:209], v169 offset:50176
	ds_read_b128 v[210:213], v169 offset:51200
	ds_read_b128 v[214:217], v169 offset:52224
	ds_read_b128 v[218:221], v169 offset:53248
	ds_read_b128 v[222:225], v169 offset:54272
	ds_read_b128 v[226:229], v169 offset:55296
	ds_read_b128 v[232:235], v169 offset:56320
	global_load_lds_dwordx4 v[150:151], off
	s_add_i32 m0, s46, 0x2000
	s_add_u32 s44, s44, 0x40080
	v_lshl_add_u64 v[150:151], v[154:155], 0, s[8:9]
	s_addc_u32 s45, s45, 0
	s_add_i32 s46, s61, s25
	global_load_lds_dwordx4 v[150:151], off
	v_lshl_add_u64 v[150:151], s[44:45], 0, v[130:131]
	s_mov_b32 m0, s46
	s_nop 0
	global_load_lds_dwordx4 v[150:151], off
	v_lshl_add_u64 v[150:151], s[44:45], 0, v[134:135]
	s_add_i32 m0, s46, 0x2000
	s_nop 0
	global_load_lds_dwordx4 v[150:151], off
	v_lshl_add_u64 v[150:151], v[158:159], 0, s[8:9]
	s_mov_b32 m0, s48
	s_nop 0
	global_load_lds_dwordx4 v[150:151], off
	v_lshl_add_u64 v[150:151], v[162:163], 0, s[8:9]
	s_mov_b32 m0, s49
	s_nop 0
	global_load_lds_dwordx4 v[150:151], off
	s_waitcnt vmcnt(8)
	s_waitcnt lgkmcnt(0)
	s_barrier
	s_setprio 1
	s_waitcnt lgkmcnt(0)
	v_mfma_f32_16x16x32_bf16 v[60:63], v[144:147], v[202:205], v[60:63]
	v_mfma_f32_16x16x32_bf16 v[52:55], v[178:181], v[202:205], v[52:55]
	v_mfma_f32_16x16x32_bf16 v[44:47], v[144:147], v[210:213], v[44:47]
	v_mfma_f32_16x16x32_bf16 v[36:39], v[178:181], v[210:213], v[36:39]
	v_mfma_f32_16x16x32_bf16 v[28:31], v[144:147], v[218:221], v[28:31]
	v_mfma_f32_16x16x32_bf16 v[20:23], v[178:181], v[218:221], v[20:23]
	v_mfma_f32_16x16x32_bf16 v[12:15], v[144:147], v[226:229], v[12:15]
	v_mfma_f32_16x16x32_bf16 v[4:7], v[178:181], v[226:229], v[4:7]
	v_mfma_f32_16x16x32_bf16 v[60:63], v[170:173], v[206:209], v[60:63]
	v_mfma_f32_16x16x32_bf16 v[52:55], v[182:185], v[206:209], v[52:55]
	v_mfma_f32_16x16x32_bf16 v[44:47], v[170:173], v[214:217], v[44:47]
	v_mfma_f32_16x16x32_bf16 v[36:39], v[182:185], v[214:217], v[36:39]
	v_mfma_f32_16x16x32_bf16 v[28:31], v[170:173], v[222:225], v[28:31]
	v_mfma_f32_16x16x32_bf16 v[20:23], v[182:185], v[222:225], v[20:23]
	v_mfma_f32_16x16x32_bf16 v[12:15], v[170:173], v[232:235], v[12:15]
	v_mfma_f32_16x16x32_bf16 v[4:7], v[182:185], v[232:235], v[4:7]
	s_setprio 0
	s_setprio 1
	v_mfma_f32_16x16x32_bf16 v[56:59], v[186:189], v[202:205], v[56:59]
	v_mfma_f32_16x16x32_bf16 v[48:51], v[194:197], v[202:205], v[48:51]
	v_mfma_f32_16x16x32_bf16 v[40:43], v[186:189], v[210:213], v[40:43]
	v_mfma_f32_16x16x32_bf16 v[32:35], v[194:197], v[210:213], v[32:35]
	v_mfma_f32_16x16x32_bf16 v[24:27], v[186:189], v[218:221], v[24:27]
	v_mfma_f32_16x16x32_bf16 v[16:19], v[194:197], v[218:221], v[16:19]
	v_mfma_f32_16x16x32_bf16 v[8:11], v[186:189], v[226:229], v[8:11]
	v_mfma_f32_16x16x32_bf16 v[0:3], v[194:197], v[226:229], v[0:3]
	v_mfma_f32_16x16x32_bf16 v[56:59], v[190:193], v[206:209], v[56:59]
	v_mfma_f32_16x16x32_bf16 v[48:51], v[198:201], v[206:209], v[48:51]
	v_mfma_f32_16x16x32_bf16 v[40:43], v[190:193], v[214:217], v[40:43]
	v_mfma_f32_16x16x32_bf16 v[32:35], v[198:201], v[214:217], v[32:35]
	v_mfma_f32_16x16x32_bf16 v[24:27], v[190:193], v[222:225], v[24:27]
	v_mfma_f32_16x16x32_bf16 v[16:19], v[198:201], v[222:225], v[16:19]
	v_mfma_f32_16x16x32_bf16 v[8:11], v[190:193], v[232:235], v[8:11]
	v_mfma_f32_16x16x32_bf16 v[0:3], v[198:201], v[232:235], v[0:3]
	s_setprio 0
	s_barrier
	s_add_i32 s59, s59, 2
	s_add_u32 s42, s42, 0x100
	s_addc_u32 s43, s43, 0
	s_add_u32 s57, s57, 0x100
	s_addc_u32 s58, s58, 0
	s_cmp_gt_u32 s59, 13
; #define PG8_STAGE(bufoff, gbase, voff) do { _Pragma("unroll") for (int _i = 0; _i < 2; ++_i) \
;         __builtin_amdgcn_global_load_lds((const unsigned*)((const char*)(gbase) + (voff)[_i]), (PG8_LAS unsigned*)(lds + (bufoff) + ldsw + _i * 8192), 16, 0, 0); } while (0)
; #define PG8_LDA(dst, b, h) do { _Pragma("unroll") for (int m = 0; m < 4; ++m) _Pragma("unroll") for (int k = 0; k < 2; ++k) dst[m][k] = *(const PG8_LAS bf16x8*)(lds + PG8_SA(b, h) + aoff + m * 2048 + k * 1024); } while (0)
; #define PG8_LDB(dst, b, h) do { _Pragma("unroll") for (int n = 0; n < 2; ++n) _Pragma("unroll") for (int k = 0; k < 2; ++k) dst[n][k] = *(const PG8_LAS bf16x8*)(lds + PG8_SB(b, h) + boff + n * 2048 + k * 1024); } while (0)
; #define PG8_MMA(ai, bj, At, Bt) do { __builtin_amdgcn_s_setprio(1); _Pragma("unroll") for (int m = 0; m < 4; ++m) _Pragma("unroll") for (int n = 0; n < 2; ++n) _Pragma("unroll") for (int k = 0; k < 2; ++k) \
;         acc[ai][bj][m][n] = __builtin_amdgcn_mfma_f32_16x16x32_bf16(Bt[n][k], At[m][k], acc[ai][bj][m][n], 0, 0, 0); __builtin_amdgcn_s_setprio(0); } while (0)
; #define PG8_WAIT_V(n) asm volatile("s_waitcnt vmcnt(" #n ")" ::: "memory")
; #define PG8_WAIT_L(n) asm volatile("s_waitcnt lgkmcnt(" #n ")" ::: "memory")
; #define PG8_BAR __builtin_amdgcn_s_barrier()
; #define PG8_SCHED __builtin_amdgcn_sched_barrier(0)
; template <class Epi, class Sched, bool ALIGN_EPI = false, bool SP2 = false>
; __device__ __forceinline__ void gemm_phase(PG8_LAS unsigned char* lds, const Gemm g, const Sched& S, const Epi& E) {
;     ...
;             PG8_LDB(B0, 0, 0); PG8_LDB(B1, 0, 1); PG8_SCHED; PG8_LDA(At, 0, 0); PG8_STAGE(PG8_SA(1, 1), a1 + hstep, voffA);
;             PG8_WAIT_V(8); PG8_WAIT_L(0); PG8_BAR; PG8_MMA(0, 0, At, B0); PG8_MMA(0, 1, At, B1); PG8_BAR; PG8_SCHED;
;             PG8_LDA(At, 0, 1); PG8_STAGE(PG8_SB(0, 0), b2, voffB); PG8_STAGE(PG8_SB(0, 1), b2 + hstep, voffB); PG8_STAGE(PG8_SA(0, 0), a2, voffA);
;             PG8_WAIT_V(8); PG8_WAIT_L(0); PG8_BAR; PG8_MMA(1, 0, At, B0); PG8_MMA(1, 1, At, B1); PG8_BAR; PG8_SCHED;
.LBB0_482:
	ds_read_b128 v[144:147], v161
	ds_read_b128 v[170:173], v161 offset:1024
	ds_read_b128 v[178:181], v161 offset:2048
	ds_read_b128 v[182:185], v161 offset:3072
	ds_read_b128 v[186:189], v165
	ds_read_b128 v[190:193], v165 offset:1024
	ds_read_b128 v[194:197], v165 offset:2048
	ds_read_b128 v[198:201], v165 offset:3072
	s_add_u32 s44, s42, 0xfffc0080
	s_addc_u32 s45, s43, -1
	s_cmp_eq_u32 s59, 12
	s_cselect_b32 s47, s19, s45
	s_cselect_b32 s46, s55, s44
	s_cselect_b32 s45, s17, s58
	s_cselect_b32 s44, s56, s57
	v_lshl_add_u64 v[150:151], s[42:43], 0, v[138:139]
	s_add_i32 m0, s28, 0xc000
	ds_read_b128 v[202:205], v169
	ds_read_b128 v[206:209], v169 offset:1024
	ds_read_b128 v[210:213], v169 offset:2048
	ds_read_b128 v[214:217], v169 offset:3072
	ds_read_b128 v[218:221], v169 offset:4096
	ds_read_b128 v[222:225], v169 offset:5120
	ds_read_b128 v[226:229], v169 offset:6144
	ds_read_b128 v[232:235], v169 offset:7168
	global_load_lds_dwordx4 v[150:151], off
	v_lshl_add_u64 v[150:151], s[42:43], 0, v[140:141]
	s_add_i32 m0, s28, 0xe000
	s_nop 0
	global_load_lds_dwordx4 v[150:151], off
	s_waitcnt vmcnt(8)
	s_waitcnt lgkmcnt(0)
	s_barrier
	s_setprio 1
	s_waitcnt lgkmcnt(0)
	v_mfma_f32_16x16x32_bf16 v[124:127], v[144:147], v[202:205], v[124:127]
	v_mfma_f32_16x16x32_bf16 v[116:119], v[178:181], v[202:205], v[116:119]
	v_mfma_f32_16x16x32_bf16 v[108:111], v[144:147], v[210:213], v[108:111]
	v_mfma_f32_16x16x32_bf16 v[100:103], v[178:181], v[210:213], v[100:103]
	v_mfma_f32_16x16x32_bf16 v[92:95], v[144:147], v[218:221], v[92:95]
	v_mfma_f32_16x16x32_bf16 v[84:87], v[178:181], v[218:221], v[84:87]
	v_mfma_f32_16x16x32_bf16 v[76:79], v[144:147], v[226:229], v[76:79]
	v_mfma_f32_16x16x32_bf16 v[68:71], v[178:181], v[226:229], v[68:71]
	v_mfma_f32_16x16x32_bf16 v[124:127], v[170:173], v[206:209], v[124:127]
	v_mfma_f32_16x16x32_bf16 v[116:119], v[182:185], v[206:209], v[116:119]
	v_mfma_f32_16x16x32_bf16 v[108:111], v[170:173], v[214:217], v[108:111]
	v_mfma_f32_16x16x32_bf16 v[100:103], v[182:185], v[214:217], v[100:103]
	v_mfma_f32_16x16x32_bf16 v[92:95], v[170:173], v[222:225], v[92:95]
	v_mfma_f32_16x16x32_bf16 v[84:87], v[182:185], v[222:225], v[84:87]
	v_mfma_f32_16x16x32_bf16 v[76:79], v[170:173], v[232:235], v[76:79]
	v_mfma_f32_16x16x32_bf16 v[68:71], v[182:185], v[232:235], v[68:71]
	s_setprio 0
	s_setprio 1
	v_mfma_f32_16x16x32_bf16 v[120:123], v[186:189], v[202:205], v[120:123]
	v_mfma_f32_16x16x32_bf16 v[112:115], v[194:197], v[202:205], v[112:115]
	v_mfma_f32_16x16x32_bf16 v[104:107], v[186:189], v[210:213], v[104:107]
	v_mfma_f32_16x16x32_bf16 v[96:99], v[194:197], v[210:213], v[96:99]
	v_mfma_f32_16x16x32_bf16 v[88:91], v[186:189], v[218:221], v[88:91]
	v_mfma_f32_16x16x32_bf16 v[80:83], v[194:197], v[218:221], v[80:83]
	v_mfma_f32_16x16x32_bf16 v[72:75], v[186:189], v[226:229], v[72:75]
	v_mfma_f32_16x16x32_bf16 v[64:67], v[194:197], v[226:229], v[64:67]
	v_mfma_f32_16x16x32_bf16 v[120:123], v[190:193], v[206:209], v[120:123]
	v_mfma_f32_16x16x32_bf16 v[112:115], v[198:201], v[206:209], v[112:115]
	v_mfma_f32_16x16x32_bf16 v[104:107], v[190:193], v[214:217], v[104:107]
	v_mfma_f32_16x16x32_bf16 v[96:99], v[198:201], v[214:217], v[96:99]
	v_mfma_f32_16x16x32_bf16 v[88:91], v[190:193], v[222:225], v[88:91]
	v_mfma_f32_16x16x32_bf16 v[80:83], v[198:201], v[222:225], v[80:83]
	v_mfma_f32_16x16x32_bf16 v[72:75], v[190:193], v[232:235], v[72:75]
	v_mfma_f32_16x16x32_bf16 v[64:67], v[198:201], v[232:235], v[64:67]
	s_setprio 0
	s_barrier
	s_add_i32 s60, s51, s25
	v_lshl_add_u64 v[150:151], s[44:45], 0, v[130:131]
	s_mov_b32 m0, s60
	ds_read_b128 v[202:205], v169 offset:16384
	ds_read_b128 v[206:209], v169 offset:17408
	ds_read_b128 v[210:213], v169 offset:18432
	ds_read_b128 v[214:217], v169 offset:19456
	ds_read_b128 v[218:221], v169 offset:20480
	ds_read_b128 v[222:225], v169 offset:21504
	ds_read_b128 v[226:229], v169 offset:22528
	ds_read_b128 v[232:235], v169 offset:23552
	global_load_lds_dwordx4 v[150:151], off
	s_add_i32 m0, s60, 0x2000
	s_add_u32 s60, s44, 0x40000
	v_lshl_add_u64 v[154:155], s[44:45], 0, v[134:135]
	s_addc_u32 s61, s45, 0
	s_add_i32 s62, s52, s25
	global_load_lds_dwordx4 v[154:155], off
	v_lshl_add_u64 v[158:159], s[60:61], 0, v[130:131]
	s_mov_b32 m0, s62
	v_lshl_add_u64 v[162:163], s[46:47], 0, v[132:133]
	global_load_lds_dwordx4 v[158:159], off
	v_lshl_add_u64 v[158:159], s[60:61], 0, v[134:135]
	s_add_i32 m0, s62, 0x2000
	s_nop 0
	global_load_lds_dwordx4 v[158:159], off
	v_lshl_add_u64 v[158:159], s[46:47], 0, v[128:129]
	s_mov_b32 m0, s28
	s_nop 0
	global_load_lds_dwordx4 v[158:159], off
	s_mov_b32 m0, s29
	s_nop 0
	global_load_lds_dwordx4 v[162:163], off
	s_cmp_lg_i32 s59, -2
	s_cbranch_scc1 .Lrsa_a
	v_lshrrev_b32_e32 v250, 6, v230
	v_lshlrev_b32_e32 v250, 11, v250
	v_and_b32_e32 v251, 63, v230
	v_lshl_or_b32 v250, v251, 4, v250
	v_lshl_add_u32 v250, s40, 14, v250
	v_readfirstlane_b32 s98, v230
	s_lshr_b32 s98, s98, 6
	s_lshl_b32 s98, s98, 11
	s_add_i32 m0, s98, 0x20000
	s_add_u32 s100, s70, 0x3f000000
	s_addc_u32 s101, s71, 0
	global_load_lds_dwordx4 v250, s[100:101]
	global_load_lds_dwordx4 v250, s[100:101] offset:1024
	s_waitcnt vmcnt(10)
	s_branch .Lrsa_b

; #define PG8_STAGE(bufoff, gbase, voff) do { _Pragma("unroll") for (int _i = 0; _i < 2; ++_i) \
;         __builtin_amdgcn_global_load_lds((const unsigned*)((const char*)(gbase) + (voff)[_i]), (PG8_LAS unsigned*)(lds + (bufoff) + ldsw + _i * 8192), 16, 0, 0); } while (0)
; #define PG8_LDA(dst, b, h) do { _Pragma("unroll") for (int m = 0; m < 4; ++m) _Pragma("unroll") for (int k = 0; k < 2; ++k) dst[m][k] = *(const PG8_LAS bf16x8*)(lds + PG8_SA(b, h) + aoff + m * 2048 + k * 1024); } while (0)
; #define PG8_LDB(dst, b, h) do { _Pragma("unroll") for (int n = 0; n < 2; ++n) _Pragma("unroll") for (int k = 0; k < 2; ++k) dst[n][k] = *(const PG8_LAS bf16x8*)(lds + PG8_SB(b, h) + boff + n * 2048 + k * 1024); } while (0)
; #define PG8_MMA(ai, bj, At, Bt) do { __builtin_amdgcn_s_setprio(1); _Pragma("unroll") for (int m = 0; m < 4; ++m) _Pragma("unroll") for (int n = 0; n < 2; ++n) _Pragma("unroll") for (int k = 0; k < 2; ++k) \
;         acc[ai][bj][m][n] = __builtin_amdgcn_mfma_f32_16x16x32_bf16(Bt[n][k], At[m][k], acc[ai][bj][m][n], 0, 0, 0); __builtin_amdgcn_s_setprio(0); } while (0)
; #define PG8_WAIT_V(n) asm volatile("s_waitcnt vmcnt(" #n ")" ::: "memory")
; #define PG8_WAIT_L(n) asm volatile("s_waitcnt lgkmcnt(" #n ")" ::: "memory")
; #define PG8_BAR __builtin_amdgcn_s_barrier()
; #define PG8_SCHED __builtin_amdgcn_sched_barrier(0)
; template <class Epi, class Sched, bool ALIGN_EPI = false, bool SP2 = false>
; __device__ __forceinline__ void gemm_phase(PG8_LAS unsigned char* lds, const Gemm g, const Sched& S, const Epi& E) {
;     ...
;             const char* a2 = last ? nA : cA + (size_t)(t + 2) * kstep; const char* b2 = last ? nB : cB + (size_t)(t + 2) * kstep;
;             const char* a3 = a2 + kstep; const char* b3 = b2 + kstep;
;             if (last && has_next) S.a_ready(nxt);
;             if constexpr (SP2) {
;             PG8_LDB(B0, 0, 0); PG8_LDB(B1, 0, 1); PG8_SCHED; PG8_LDA(At, 0, 0); PG8_STAGE(PG8_SA(1, 1), a1 + hstep, voffA);
;             PG8_WAIT_V(8); PG8_WAIT_L(0); PG8_BAR; PG8_MMA(0, 0, At, B0); PG8_MMA(0, 1, At, B1); PG8_BAR; PG8_SCHED;
;             PG8_LDA(At, 0, 1); PG8_STAGE(PG8_SB(0, 0), b2, voffB); PG8_STAGE(PG8_SB(0, 1), b2 + hstep, voffB); PG8_STAGE(PG8_SA(0, 0), a2, voffA);
;             PG8_WAIT_V(8); PG8_WAIT_L(0); PG8_BAR; PG8_MMA(1, 0, At, B0); PG8_MMA(1, 1, At, B1); PG8_BAR; PG8_SCHED;
.LBB0_569:
	s_add_u32 s42, s42, 0xb0080
	s_addc_u32 s43, s43, 0
	s_add_u32 s56, s44, 0x100
	s_addc_u32 s57, s45, 0
	s_mov_b32 s58, -2
	s_waitcnt lgkmcnt(0)
	ds_read_b128 v[124:127], v234
	ds_read_b128 v[132:135], v234 offset:1024
	ds_read_b128 v[136:139], v234 offset:2048
	ds_read_b128 v[140:143], v234 offset:3072
	ds_read_b128 v[144:147], v235
	ds_read_b128 v[148:151], v235 offset:1024
	ds_read_b128 v[152:155], v235 offset:2048
	ds_read_b128 v[156:159], v235 offset:3072
	s_add_u32 s44, s42, 0xfff50080
	s_addc_u32 s45, s43, -1
	s_cmp_eq_u32 s58, 40
	s_cselect_b32 s47, s39, s45
	s_cselect_b32 s46, s38, s44
	s_cselect_b32 s45, s41, s57
	s_cselect_b32 s44, s40, s56
	v_lshl_add_u64 v[206:207], s[42:43], 0, v[192:193]
	s_add_i32 m0, s26, 0xc000
	ds_read_b128 v[160:163], v236
	ds_read_b128 v[164:167], v236 offset:1024
	ds_read_b128 v[168:171], v236 offset:2048
	ds_read_b128 v[172:175], v236 offset:3072
	ds_read_b128 v[176:179], v236 offset:4096
	ds_read_b128 v[180:183], v236 offset:5120
	ds_read_b128 v[198:201], v236 offset:6144
	ds_read_b128 v[202:205], v236 offset:7168
	global_load_lds_dwordx4 v[206:207], off
	v_lshl_add_u64 v[206:207], s[42:43], 0, v[194:195]
	s_add_i32 m0, s26, 0xe000
	s_nop 0
	global_load_lds_dwordx4 v[206:207], off
	s_waitcnt vmcnt(8)
	s_waitcnt lgkmcnt(0)
	s_barrier
	s_setprio 1
	s_waitcnt lgkmcnt(0)
	v_mfma_f32_16x16x32_bf16 v[128:131], v[124:127], v[160:163], 0
	v_mfma_f32_16x16x32_bf16 v[120:123], v[136:139], v[160:163], 0
	v_mfma_f32_16x16x32_bf16 v[108:111], v[124:127], v[168:171], 0
	v_mfma_f32_16x16x32_bf16 v[104:107], v[136:139], v[168:171], 0
	v_mfma_f32_16x16x32_bf16 v[92:95], v[124:127], v[176:179], 0
	v_mfma_f32_16x16x32_bf16 v[88:91], v[136:139], v[176:179], 0
	v_mfma_f32_16x16x32_bf16 v[76:79], v[124:127], v[198:201], 0
	v_mfma_f32_16x16x32_bf16 v[72:75], v[136:139], v[198:201], 0
	v_mfma_f32_16x16x32_bf16 v[128:131], v[132:135], v[164:167], v[128:131]
	v_mfma_f32_16x16x32_bf16 v[120:123], v[140:143], v[164:167], v[120:123]
	v_mfma_f32_16x16x32_bf16 v[108:111], v[132:135], v[172:175], v[108:111]
	v_mfma_f32_16x16x32_bf16 v[104:107], v[140:143], v[172:175], v[104:107]
	v_mfma_f32_16x16x32_bf16 v[92:95], v[132:135], v[180:183], v[92:95]
	v_mfma_f32_16x16x32_bf16 v[88:91], v[140:143], v[180:183], v[88:91]
	v_mfma_f32_16x16x32_bf16 v[76:79], v[132:135], v[202:205], v[76:79]
	v_mfma_f32_16x16x32_bf16 v[72:75], v[140:143], v[202:205], v[72:75]
	s_setprio 0
	s_setprio 1
	v_mfma_f32_16x16x32_bf16 v[116:119], v[144:147], v[160:163], 0
	v_mfma_f32_16x16x32_bf16 v[112:115], v[152:155], v[160:163], 0
	v_mfma_f32_16x16x32_bf16 v[100:103], v[144:147], v[168:171], 0
	v_mfma_f32_16x16x32_bf16 v[96:99], v[152:155], v[168:171], 0
	v_mfma_f32_16x16x32_bf16 v[84:87], v[144:147], v[176:179], 0
	v_mfma_f32_16x16x32_bf16 v[80:83], v[152:155], v[176:179], 0
	v_mfma_f32_16x16x32_bf16 v[68:71], v[144:147], v[198:201], 0
	v_mfma_f32_16x16x32_bf16 v[64:67], v[152:155], v[198:201], 0
	v_mfma_f32_16x16x32_bf16 v[116:119], v[148:151], v[164:167], v[116:119]
	v_mfma_f32_16x16x32_bf16 v[112:115], v[156:159], v[164:167], v[112:115]
	v_mfma_f32_16x16x32_bf16 v[100:103], v[148:151], v[172:175], v[100:103]
	v_mfma_f32_16x16x32_bf16 v[96:99], v[156:159], v[172:175], v[96:99]
	v_mfma_f32_16x16x32_bf16 v[84:87], v[148:151], v[180:183], v[84:87]
	v_mfma_f32_16x16x32_bf16 v[80:83], v[156:159], v[180:183], v[80:83]
	v_mfma_f32_16x16x32_bf16 v[68:71], v[148:151], v[202:205], v[68:71]
	v_mfma_f32_16x16x32_bf16 v[64:67], v[156:159], v[202:205], v[64:67]
	s_setprio 0
	s_barrier
	s_add_i32 s59, s50, s25
	v_lshl_add_u64 v[206:207], s[44:45], 0, v[186:187]
	s_mov_b32 m0, s59
	ds_read_b128 v[160:163], v236 offset:16384
	ds_read_b128 v[164:167], v236 offset:17408
	ds_read_b128 v[168:171], v236 offset:18432
	ds_read_b128 v[172:175], v236 offset:19456
	ds_read_b128 v[176:179], v236 offset:20480
	ds_read_b128 v[180:183], v236 offset:21504
	ds_read_b128 v[198:201], v236 offset:22528
	ds_read_b128 v[202:205], v236 offset:23552
	global_load_lds_dwordx4 v[206:207], off
	s_add_i32 m0, s59, 0x2000
	s_add_u32 s60, s44, 0xb0000
	v_lshl_add_u64 v[208:209], s[44:45], 0, v[190:191]
	s_addc_u32 s61, s45, 0
	s_add_i32 s59, s51, s25
	global_load_lds_dwordx4 v[208:209], off
	v_lshl_add_u64 v[210:211], s[60:61], 0, v[186:187]
	s_mov_b32 m0, s59
	v_lshl_add_u64 v[212:213], s[46:47], 0, v[188:189]
	global_load_lds_dwordx4 v[210:211], off
	v_lshl_add_u64 v[210:211], s[60:61], 0, v[190:191]
	s_add_i32 m0, s59, 0x2000
	s_nop 0
	global_load_lds_dwordx4 v[210:211], off
	v_lshl_add_u64 v[210:211], s[46:47], 0, v[184:185]
	s_mov_b32 m0, s26
	s_nop 0
	global_load_lds_dwordx4 v[210:211], off
	s_mov_b32 m0, s27
	s_nop 0
	global_load_lds_dwordx4 v[212:213], off
	s_waitcnt vmcnt(8)
	s_waitcnt lgkmcnt(0)
	s_barrier
; #define PG8_STAGE(bufoff, gbase, voff) do { _Pragma("unroll") for (int _i = 0; _i < 2; ++_i) \
;         __builtin_amdgcn_global_load_lds((const unsigned*)((const char*)(gbase) + (voff)[_i]), (PG8_LAS unsigned*)(lds + (bufoff) + ldsw + _i * 8192), 16, 0, 0); } while (0)
; #define PG8_LDA(dst, b, h) do { _Pragma("unroll") for (int m = 0; m < 4; ++m) _Pragma("unroll") for (int k = 0; k < 2; ++k) dst[m][k] = *(const PG8_LAS bf16x8*)(lds + PG8_SA(b, h) + aoff + m * 2048 + k * 1024); } while (0)
; #define PG8_LDB(dst, b, h) do { _Pragma("unroll") for (int n = 0; n < 2; ++n) _Pragma("unroll") for (int k = 0; k < 2; ++k) dst[n][k] = *(const PG8_LAS bf16x8*)(lds + PG8_SB(b, h) + boff + n * 2048 + k * 1024); } while (0)
; #define PG8_MMA(ai, bj, At, Bt) do { __builtin_amdgcn_s_setprio(1); _Pragma("unroll") for (int m = 0; m < 4; ++m) _Pragma("unroll") for (int n = 0; n < 2; ++n) _Pragma("unroll") for (int k = 0; k < 2; ++k) \
;         acc[ai][bj][m][n] = __builtin_amdgcn_mfma_f32_16x16x32_bf16(Bt[n][k], At[m][k], acc[ai][bj][m][n], 0, 0, 0); __builtin_amdgcn_s_setprio(0); } while (0)
; #define PG8_WAIT_V(n) asm volatile("s_waitcnt vmcnt(" #n ")" ::: "memory")
; #define PG8_WAIT_L(n) asm volatile("s_waitcnt lgkmcnt(" #n ")" ::: "memory")
; #define PG8_BAR __builtin_amdgcn_s_barrier()
; #define PG8_SCHED __builtin_amdgcn_sched_barrier(0)
; template <class Epi, class Sched, bool ALIGN_EPI = false, bool SP2 = false>
; __device__ __forceinline__ void gemm_phase(PG8_LAS unsigned char* lds, const Gemm g, const Sched& S, const Epi& E) {
;     ...
;             PG8_WAIT_V(8); PG8_WAIT_L(0); PG8_BAR; PG8_MMA(1, 0, At, B0); PG8_MMA(1, 1, At, B1); PG8_BAR; PG8_SCHED;
;             PG8_LDB(B0, 1, 0); PG8_LDB(B1, 1, 1); PG8_SCHED; PG8_LDA(At, 1, 0); PG8_STAGE(PG8_SA(0, 1), a2 + hstep, voffA);
;             PG8_WAIT_V(8); PG8_WAIT_L(0); PG8_BAR; PG8_MMA(0, 0, At, B0); PG8_MMA(0, 1, At, B1); PG8_BAR; PG8_SCHED;
	s_setprio 1
	s_waitcnt lgkmcnt(0)
	v_mfma_f32_16x16x32_bf16 v[60:63], v[124:127], v[160:163], 0
	v_mfma_f32_16x16x32_bf16 v[56:59], v[136:139], v[160:163], 0
	v_mfma_f32_16x16x32_bf16 v[44:47], v[124:127], v[168:171], 0
	v_mfma_f32_16x16x32_bf16 v[40:43], v[136:139], v[168:171], 0
	v_mfma_f32_16x16x32_bf16 v[28:31], v[124:127], v[176:179], 0
	v_mfma_f32_16x16x32_bf16 v[24:27], v[136:139], v[176:179], 0
	v_mfma_f32_16x16x32_bf16 v[12:15], v[124:127], v[198:201], 0
	v_mfma_f32_16x16x32_bf16 v[8:11], v[136:139], v[198:201], 0
	v_mfma_f32_16x16x32_bf16 v[60:63], v[132:135], v[164:167], v[60:63]
	v_mfma_f32_16x16x32_bf16 v[56:59], v[140:143], v[164:167], v[56:59]
	v_mfma_f32_16x16x32_bf16 v[44:47], v[132:135], v[172:175], v[44:47]
	v_mfma_f32_16x16x32_bf16 v[40:43], v[140:143], v[172:175], v[40:43]
	v_mfma_f32_16x16x32_bf16 v[28:31], v[132:135], v[180:183], v[28:31]
	v_mfma_f32_16x16x32_bf16 v[24:27], v[140:143], v[180:183], v[24:27]
	v_mfma_f32_16x16x32_bf16 v[12:15], v[132:135], v[202:205], v[12:15]
	v_mfma_f32_16x16x32_bf16 v[8:11], v[140:143], v[202:205], v[8:11]
	s_setprio 0
	s_setprio 1
	v_mfma_f32_16x16x32_bf16 v[52:55], v[144:147], v[160:163], 0
	v_mfma_f32_16x16x32_bf16 v[48:51], v[152:155], v[160:163], 0
	v_mfma_f32_16x16x32_bf16 v[36:39], v[144:147], v[168:171], 0
	v_mfma_f32_16x16x32_bf16 v[32:35], v[152:155], v[168:171], 0
	v_mfma_f32_16x16x32_bf16 v[20:23], v[144:147], v[176:179], 0
	v_mfma_f32_16x16x32_bf16 v[16:19], v[152:155], v[176:179], 0
	v_mfma_f32_16x16x32_bf16 v[4:7], v[144:147], v[198:201], 0
	v_mfma_f32_16x16x32_bf16 v[0:3], v[152:155], v[198:201], 0
	v_mfma_f32_16x16x32_bf16 v[52:55], v[148:151], v[164:167], v[52:55]
	v_mfma_f32_16x16x32_bf16 v[48:51], v[156:159], v[164:167], v[48:51]
	v_mfma_f32_16x16x32_bf16 v[36:39], v[148:151], v[172:175], v[36:39]
	v_mfma_f32_16x16x32_bf16 v[32:35], v[156:159], v[172:175], v[32:35]
	v_mfma_f32_16x16x32_bf16 v[20:23], v[148:151], v[180:183], v[20:23]
	v_mfma_f32_16x16x32_bf16 v[16:19], v[156:159], v[180:183], v[16:19]
	v_mfma_f32_16x16x32_bf16 v[4:7], v[148:151], v[202:205], v[4:7]
	v_mfma_f32_16x16x32_bf16 v[0:3], v[156:159], v[202:205], v[0:3]
	s_setprio 0
	s_barrier
	s_add_i32 s59, 0, 0x18000
	s_add_i32 s60, 0, 0x1c000
	v_add_u32_e32 v140, s59, v232
	v_add_u32_e32 v156, s60, v232
	ds_read_b128 v[124:127], v140
	ds_read_b128 v[132:135], v140 offset:1024
	ds_read_b128 v[136:139], v140 offset:2048
	ds_read_b128 v[140:143], v140 offset:3072
	ds_read_b128 v[144:147], v156
	ds_read_b128 v[148:151], v156 offset:1024
	ds_read_b128 v[152:155], v156 offset:2048
	ds_read_b128 v[156:159], v156 offset:3072
	s_add_u32 s46, s46, 0xb0000
	s_addc_u32 s47, s47, 0
	s_mov_b32 m0, s28
	v_lshl_add_u64 v[214:215], s[46:47], 0, v[184:185]
	ds_read_b128 v[160:163], v236 offset:32768
	ds_read_b128 v[164:167], v236 offset:33792
	ds_read_b128 v[168:171], v236 offset:34816
	ds_read_b128 v[172:175], v236 offset:35840
	ds_read_b128 v[176:179], v236 offset:36864
	ds_read_b128 v[180:183], v236 offset:37888
	ds_read_b128 v[198:201], v236 offset:38912
	ds_read_b128 v[202:205], v236 offset:39936
	global_load_lds_dwordx4 v[214:215], off
	v_lshl_add_u64 v[214:215], s[46:47], 0, v[188:189]
	s_mov_b32 m0, s29
	s_nop 0
	global_load_lds_dwordx4 v[214:215], off
	s_waitcnt vmcnt(8)
	s_waitcnt lgkmcnt(0)
	s_barrier
	s_setprio 1
	s_waitcnt lgkmcnt(0)
	v_mfma_f32_16x16x32_bf16 v[128:131], v[124:127], v[160:163], v[128:131]
	v_mfma_f32_16x16x32_bf16 v[120:123], v[136:139], v[160:163], v[120:123]
	v_mfma_f32_16x16x32_bf16 v[108:111], v[124:127], v[168:171], v[108:111]
	v_mfma_f32_16x16x32_bf16 v[104:107], v[136:139], v[168:171], v[104:107]
	v_mfma_f32_16x16x32_bf16 v[92:95], v[124:127], v[176:179], v[92:95]
	v_mfma_f32_16x16x32_bf16 v[88:91], v[136:139], v[176:179], v[88:91]
	v_mfma_f32_16x16x32_bf16 v[76:79], v[124:127], v[198:201], v[76:79]
	v_mfma_f32_16x16x32_bf16 v[72:75], v[136:139], v[198:201], v[72:75]
	v_mfma_f32_16x16x32_bf16 v[128:131], v[132:135], v[164:167], v[128:131]
	v_mfma_f32_16x16x32_bf16 v[120:123], v[140:143], v[164:167], v[120:123]
	v_mfma_f32_16x16x32_bf16 v[108:111], v[132:135], v[172:175], v[108:111]
	v_mfma_f32_16x16x32_bf16 v[104:107], v[140:143], v[172:175], v[104:107]
	v_mfma_f32_16x16x32_bf16 v[92:95], v[132:135], v[180:183], v[92:95]
	v_mfma_f32_16x16x32_bf16 v[88:91], v[140:143], v[180:183], v[88:91]
	v_mfma_f32_16x16x32_bf16 v[76:79], v[132:135], v[202:205], v[76:79]
	v_mfma_f32_16x16x32_bf16 v[72:75], v[140:143], v[202:205], v[72:75]
	s_setprio 0
	s_setprio 1
	v_mfma_f32_16x16x32_bf16 v[116:119], v[144:147], v[160:163], v[116:119]
	v_mfma_f32_16x16x32_bf16 v[112:115], v[152:155], v[160:163], v[112:115]
	v_mfma_f32_16x16x32_bf16 v[100:103], v[144:147], v[168:171], v[100:103]
	v_mfma_f32_16x16x32_bf16 v[96:99], v[152:155], v[168:171], v[96:99]
	v_mfma_f32_16x16x32_bf16 v[84:87], v[144:147], v[176:179], v[84:87]
	v_mfma_f32_16x16x32_bf16 v[80:83], v[152:155], v[176:179], v[80:83]
	v_mfma_f32_16x16x32_bf16 v[68:71], v[144:147], v[198:201], v[68:71]
	v_mfma_f32_16x16x32_bf16 v[64:67], v[152:155], v[198:201], v[64:67]
	v_mfma_f32_16x16x32_bf16 v[116:119], v[148:151], v[164:167], v[116:119]
	v_mfma_f32_16x16x32_bf16 v[112:115], v[156:159], v[164:167], v[112:115]
	v_mfma_f32_16x16x32_bf16 v[100:103], v[148:151], v[172:175], v[100:103]
	v_mfma_f32_16x16x32_bf16 v[96:99], v[156:159], v[172:175], v[96:99]
	v_mfma_f32_16x16x32_bf16 v[84:87], v[148:151], v[180:183], v[84:87]
	v_mfma_f32_16x16x32_bf16 v[80:83], v[156:159], v[180:183], v[80:83]
	v_mfma_f32_16x16x32_bf16 v[68:71], v[148:151], v[202:205], v[68:71]
	v_mfma_f32_16x16x32_bf16 v[64:67], v[156:159], v[202:205], v[64:67]
	s_setprio 0
	s_barrier
; #define PG8_STAGE(bufoff, gbase, voff) do { _Pragma("unroll") for (int _i = 0; _i < 2; ++_i) \
;         __builtin_amdgcn_global_load_lds((const unsigned*)((const char*)(gbase) + (voff)[_i]), (PG8_LAS unsigned*)(lds + (bufoff) + ldsw + _i * 8192), 16, 0, 0); } while (0)
; #define PG8_LDA(dst, b, h) do { _Pragma("unroll") for (int m = 0; m < 4; ++m) _Pragma("unroll") for (int k = 0; k < 2; ++k) dst[m][k] = *(const PG8_LAS bf16x8*)(lds + PG8_SA(b, h) + aoff + m * 2048 + k * 1024); } while (0)
; #define PG8_MMA(ai, bj, At, Bt) do { __builtin_amdgcn_s_setprio(1); _Pragma("unroll") for (int m = 0; m < 4; ++m) _Pragma("unroll") for (int n = 0; n < 2; ++n) _Pragma("unroll") for (int k = 0; k < 2; ++k) \
;         acc[ai][bj][m][n] = __builtin_amdgcn_mfma_f32_16x16x32_bf16(Bt[n][k], At[m][k], acc[ai][bj][m][n], 0, 0, 0); __builtin_amdgcn_s_setprio(0); } while (0)
; #define PG8_WAIT_V(n) asm volatile("s_waitcnt vmcnt(" #n ")" ::: "memory")
; #define PG8_WAIT_L(n) asm volatile("s_waitcnt lgkmcnt(" #n ")" ::: "memory")
; #define PG8_BAR __builtin_amdgcn_s_barrier()
; #define PG8_SCHED __builtin_amdgcn_sched_barrier(0)
; template <class Epi, class Sched, bool ALIGN_EPI = false, bool SP2 = false>
; __device__ __forceinline__ void gemm_phase(PG8_LAS unsigned char* lds, const Gemm g, const Sched& S, const Epi& E) {
;     ...
;             PG8_LDA(At, 1, 1); PG8_STAGE(PG8_SB(1, 0), b3, voffB); PG8_STAGE(PG8_SB(1, 1), b3 + hstep, voffB); PG8_STAGE(PG8_SA(1, 0), a3, voffA);
;             PG8_WAIT_V(8); PG8_WAIT_L(0); PG8_BAR; PG8_MMA(1, 0, At, B0); PG8_MMA(1, 1, At, B1); PG8_BAR; PG8_SCHED;
	s_add_i32 s46, s59, s25
	v_lshl_add_u64 v[206:207], v[206:207], 0, s[20:21]
	s_mov_b32 m0, s46
	ds_read_b128 v[160:163], v236 offset:49152
	ds_read_b128 v[164:167], v236 offset:50176
	ds_read_b128 v[168:171], v236 offset:51200
	ds_read_b128 v[172:175], v236 offset:52224
	ds_read_b128 v[176:179], v236 offset:53248
	ds_read_b128 v[180:183], v236 offset:54272
	ds_read_b128 v[198:201], v236 offset:55296
	ds_read_b128 v[202:205], v236 offset:56320
	global_load_lds_dwordx4 v[206:207], off
	s_add_i32 m0, s46, 0x2000
	s_add_u32 s44, s44, 0xb0080
	v_lshl_add_u64 v[206:207], v[208:209], 0, s[20:21]
	s_addc_u32 s45, s45, 0
	s_add_i32 s46, s60, s25
	global_load_lds_dwordx4 v[206:207], off
	v_lshl_add_u64 v[206:207], s[44:45], 0, v[186:187]
	s_mov_b32 m0, s46
	s_nop 0
	global_load_lds_dwordx4 v[206:207], off
	v_lshl_add_u64 v[206:207], s[44:45], 0, v[190:191]
	s_add_i32 m0, s46, 0x2000
	s_nop 0
	global_load_lds_dwordx4 v[206:207], off
	v_lshl_add_u64 v[206:207], v[210:211], 0, s[20:21]
	s_mov_b32 m0, s31
	s_nop 0
	global_load_lds_dwordx4 v[206:207], off
	v_lshl_add_u64 v[206:207], v[212:213], 0, s[20:21]
	s_mov_b32 m0, s33
	s_nop 0
	global_load_lds_dwordx4 v[206:207], off
	s_waitcnt vmcnt(8)
	s_waitcnt lgkmcnt(0)
	s_barrier
	s_setprio 1
	s_waitcnt lgkmcnt(0)
	v_mfma_f32_16x16x32_bf16 v[60:63], v[124:127], v[160:163], v[60:63]
	v_mfma_f32_16x16x32_bf16 v[56:59], v[136:139], v[160:163], v[56:59]
	v_mfma_f32_16x16x32_bf16 v[44:47], v[124:127], v[168:171], v[44:47]
	v_mfma_f32_16x16x32_bf16 v[40:43], v[136:139], v[168:171], v[40:43]
	v_mfma_f32_16x16x32_bf16 v[28:31], v[124:127], v[176:179], v[28:31]
	v_mfma_f32_16x16x32_bf16 v[24:27], v[136:139], v[176:179], v[24:27]
	v_mfma_f32_16x16x32_bf16 v[12:15], v[124:127], v[198:201], v[12:15]
	v_mfma_f32_16x16x32_bf16 v[8:11], v[136:139], v[198:201], v[8:11]
	v_mfma_f32_16x16x32_bf16 v[60:63], v[132:135], v[164:167], v[60:63]
	v_mfma_f32_16x16x32_bf16 v[56:59], v[140:143], v[164:167], v[56:59]
	v_mfma_f32_16x16x32_bf16 v[44:47], v[132:135], v[172:175], v[44:47]
	v_mfma_f32_16x16x32_bf16 v[40:43], v[140:143], v[172:175], v[40:43]
	v_mfma_f32_16x16x32_bf16 v[28:31], v[132:135], v[180:183], v[28:31]
	v_mfma_f32_16x16x32_bf16 v[24:27], v[140:143], v[180:183], v[24:27]
	v_mfma_f32_16x16x32_bf16 v[12:15], v[132:135], v[202:205], v[12:15]
	v_mfma_f32_16x16x32_bf16 v[8:11], v[140:143], v[202:205], v[8:11]
	s_setprio 0
	s_setprio 1
	v_mfma_f32_16x16x32_bf16 v[52:55], v[144:147], v[160:163], v[52:55]
	v_mfma_f32_16x16x32_bf16 v[48:51], v[152:155], v[160:163], v[48:51]
	v_mfma_f32_16x16x32_bf16 v[36:39], v[144:147], v[168:171], v[36:39]
	v_mfma_f32_16x16x32_bf16 v[32:35], v[152:155], v[168:171], v[32:35]
	v_mfma_f32_16x16x32_bf16 v[20:23], v[144:147], v[176:179], v[20:23]
	v_mfma_f32_16x16x32_bf16 v[16:19], v[152:155], v[176:179], v[16:19]
	v_mfma_f32_16x16x32_bf16 v[4:7], v[144:147], v[198:201], v[4:7]
	v_mfma_f32_16x16x32_bf16 v[0:3], v[152:155], v[198:201], v[0:3]
	v_mfma_f32_16x16x32_bf16 v[52:55], v[148:151], v[164:167], v[52:55]
	v_mfma_f32_16x16x32_bf16 v[48:51], v[156:159], v[164:167], v[48:51]
	v_mfma_f32_16x16x32_bf16 v[36:39], v[148:151], v[172:175], v[36:39]
	v_mfma_f32_16x16x32_bf16 v[32:35], v[156:159], v[172:175], v[32:35]
	v_mfma_f32_16x16x32_bf16 v[20:23], v[148:151], v[180:183], v[20:23]
	v_mfma_f32_16x16x32_bf16 v[16:19], v[156:159], v[180:183], v[16:19]
	v_mfma_f32_16x16x32_bf16 v[4:7], v[148:151], v[202:205], v[4:7]
	v_mfma_f32_16x16x32_bf16 v[0:3], v[156:159], v[202:205], v[0:3]
	s_setprio 0
	s_barrier
	s_add_i32 s58, s58, 2
	s_add_u32 s42, s42, 0x100
	s_addc_u32 s43, s43, 0
	s_add_u32 s56, s56, 0x100
	s_addc_u32 s57, s57, 0
	s_cmp_gt_u32 s58, 41

; #define PG8_STAGE(bufoff, gbase, voff) do { _Pragma("unroll") for (int _i = 0; _i < 2; ++_i) \
;         __builtin_amdgcn_global_load_lds((const unsigned*)((const char*)(gbase) + (voff)[_i]), (PG8_LAS unsigned*)(lds + (bufoff) + ldsw + _i * 8192), 16, 0, 0); } while (0)
; #define PG8_LDA(dst, b, h) do { _Pragma("unroll") for (int m = 0; m < 4; ++m) _Pragma("unroll") for (int k = 0; k < 2; ++k) dst[m][k] = *(const PG8_LAS bf16x8*)(lds + PG8_SA(b, h) + aoff + m * 2048 + k * 1024); } while (0)
; #define PG8_LDB(dst, b, h) do { _Pragma("unroll") for (int n = 0; n < 2; ++n) _Pragma("unroll") for (int k = 0; k < 2; ++k) dst[n][k] = *(const PG8_LAS bf16x8*)(lds + PG8_SB(b, h) + boff + n * 2048 + k * 1024); } while (0)
; #define PG8_WAIT_V(n) asm volatile("s_waitcnt vmcnt(" #n ")" ::: "memory")
; #define PG8_WAIT_L(n) asm volatile("s_waitcnt lgkmcnt(" #n ")" ::: "memory")
; #define PG8_BAR __builtin_amdgcn_s_barrier()
; #define PG8_SCHED __builtin_amdgcn_sched_barrier(0)
; template <class Epi, class Sched, bool ALIGN_EPI = false, bool SP2 = false>
; __device__ __forceinline__ void gemm_phase(PG8_LAS unsigned char* lds, const Gemm g, const Sched& S, const Epi& E) {
;     ...
;         const char* nA = has_next ? (const char*)g.A + (size_t)nxt.pm * tstep : cA; const char* nB = has_next ? (const char*)g.Bt + (size_t)nxt.pn * tstep : cB;
;         for (int t = 0; t < nt; t += 2) {
;             const bool last = (t == nt - 2);
;             const char* a1 = cA + (size_t)(t + 1) * kstep;
;             const char* a2 = last ? nA : cA + (size_t)(t + 2) * kstep; const char* b2 = last ? nB : cB + (size_t)(t + 2) * kstep;
;             const char* a3 = a2 + kstep; const char* b3 = b2 + kstep;
;             if (last && has_next) S.a_ready(nxt);
;             if constexpr (SP2) {
;             PG8_LDB(B0, 0, 0); PG8_LDB(B1, 0, 1); PG8_SCHED; PG8_LDA(At, 0, 0); PG8_STAGE(PG8_SA(1, 1), a1 + hstep, voffA);
;             PG8_WAIT_V(8); PG8_WAIT_L(0); PG8_BAR; PG8_MMA(0, 0, At, B0); PG8_MMA(0, 1, At, B1); PG8_BAR; PG8_SCHED;
;             PG8_LDA(At, 0, 1); PG8_STAGE(PG8_SB(0, 0), b2, voffB); PG8_STAGE(PG8_SB(0, 1), b2 + hstep, voffB); PG8_STAGE(PG8_SA(0, 0), a2, voffA);
;             PG8_WAIT_V(8); PG8_WAIT_L(0); PG8_BAR; PG8_MMA(1, 0, At, B0); PG8_MMA(1, 1, At, B1); PG8_BAR; PG8_SCHED;
.LBB0_659:
	s_ashr_i32 s37, s36, 31
	s_lshl_b64 s[40:41], s[36:37], 19
	s_add_u32 s40, s70, s40
	s_addc_u32 s41, s71, s41
	s_and_b64 s[42:43], s[38:39], exec
	s_cselect_b32 s5, s41, s1
	s_cselect_b32 s37, s40, s0
	s_ashr_i32 s21, s20, 31
	s_lshl_b64 s[42:43], s[20:21], 19
	s_add_u32 s42, s23, s42
	s_addc_u32 s43, s24, s43
	s_and_b64 s[48:49], s[38:39], exec
	s_cselect_b32 s21, s43, s47
	s_cselect_b32 s45, s42, s46
	s_add_u32 s0, s0, 0x40080
	s_addc_u32 s1, s1, 0
	s_add_u32 s50, s46, 0x100
	s_addc_u32 s51, s47, 0
	s_mov_b32 s59, -2
	ds_read_b128 v[146:149], v165
	ds_read_b128 v[150:153], v165 offset:1024
	ds_read_b128 v[154:157], v165 offset:2048
	ds_read_b128 v[170:173], v165 offset:3072
	ds_read_b128 v[174:177], v166
	ds_read_b128 v[178:181], v166 offset:1024
	ds_read_b128 v[182:185], v166 offset:2048
	ds_read_b128 v[186:189], v166 offset:3072
	s_add_u32 s46, s0, 0xfffc0080
	s_addc_u32 s47, s1, -1
	s_cmp_eq_u32 s59, 12
	s_cselect_b32 s49, s5, s47
	s_cselect_b32 s48, s37, s46
	s_cselect_b32 s47, s21, s51
	s_cselect_b32 s46, s45, s50
	v_lshl_add_u64 v[158:159], s[0:1], 0, v[140:141]
	s_add_i32 m0, s26, 0xc000
	ds_read_b128 v[190:193], v167
	ds_read_b128 v[194:197], v167 offset:1024
	ds_read_b128 v[198:201], v167 offset:2048
	ds_read_b128 v[202:205], v167 offset:3072
	ds_read_b128 v[206:209], v167 offset:4096
	ds_read_b128 v[210:213], v167 offset:5120
	ds_read_b128 v[214:217], v167 offset:6144
	ds_read_b128 v[218:221], v167 offset:7168
	global_load_lds_dwordx4 v[158:159], off
	v_lshl_add_u64 v[158:159], s[0:1], 0, v[142:143]
	s_add_i32 m0, s26, 0xe000
	s_nop 0
	global_load_lds_dwordx4 v[158:159], off
	s_waitcnt vmcnt(8)
	s_waitcnt lgkmcnt(0)
	s_barrier
	s_setprio 1
	s_waitcnt lgkmcnt(0)
	v_mfma_f32_16x16x32_bf16 v[124:127], v[146:149], v[190:193], 0
	v_mfma_f32_16x16x32_bf16 v[120:123], v[154:157], v[190:193], 0
	v_mfma_f32_16x16x32_bf16 v[108:111], v[146:149], v[198:201], 0
	v_mfma_f32_16x16x32_bf16 v[104:107], v[154:157], v[198:201], 0
	v_mfma_f32_16x16x32_bf16 v[92:95], v[146:149], v[206:209], 0
	v_mfma_f32_16x16x32_bf16 v[88:91], v[154:157], v[206:209], 0
	v_mfma_f32_16x16x32_bf16 v[76:79], v[146:149], v[214:217], 0
	v_mfma_f32_16x16x32_bf16 v[72:75], v[154:157], v[214:217], 0
	v_mfma_f32_16x16x32_bf16 v[124:127], v[150:153], v[194:197], v[124:127]
	v_mfma_f32_16x16x32_bf16 v[120:123], v[170:173], v[194:197], v[120:123]
	v_mfma_f32_16x16x32_bf16 v[108:111], v[150:153], v[202:205], v[108:111]
	v_mfma_f32_16x16x32_bf16 v[104:107], v[170:173], v[202:205], v[104:107]
	v_mfma_f32_16x16x32_bf16 v[92:95], v[150:153], v[210:213], v[92:95]
	v_mfma_f32_16x16x32_bf16 v[88:91], v[170:173], v[210:213], v[88:91]
	v_mfma_f32_16x16x32_bf16 v[76:79], v[150:153], v[218:221], v[76:79]
	v_mfma_f32_16x16x32_bf16 v[72:75], v[170:173], v[218:221], v[72:75]
	s_setprio 0
	s_setprio 1
	v_mfma_f32_16x16x32_bf16 v[116:119], v[174:177], v[190:193], 0
	v_mfma_f32_16x16x32_bf16 v[112:115], v[182:185], v[190:193], 0
	v_mfma_f32_16x16x32_bf16 v[100:103], v[174:177], v[198:201], 0
	v_mfma_f32_16x16x32_bf16 v[96:99], v[182:185], v[198:201], 0
	v_mfma_f32_16x16x32_bf16 v[84:87], v[174:177], v[206:209], 0
	v_mfma_f32_16x16x32_bf16 v[80:83], v[182:185], v[206:209], 0
	v_mfma_f32_16x16x32_bf16 v[68:71], v[174:177], v[214:217], 0
	v_mfma_f32_16x16x32_bf16 v[64:67], v[182:185], v[214:217], 0
	v_mfma_f32_16x16x32_bf16 v[116:119], v[178:181], v[194:197], v[116:119]
	v_mfma_f32_16x16x32_bf16 v[112:115], v[186:189], v[194:197], v[112:115]
	v_mfma_f32_16x16x32_bf16 v[100:103], v[178:181], v[202:205], v[100:103]
	v_mfma_f32_16x16x32_bf16 v[96:99], v[186:189], v[202:205], v[96:99]
	v_mfma_f32_16x16x32_bf16 v[84:87], v[178:181], v[210:213], v[84:87]
	v_mfma_f32_16x16x32_bf16 v[80:83], v[186:189], v[210:213], v[80:83]
	v_mfma_f32_16x16x32_bf16 v[68:71], v[178:181], v[218:221], v[68:71]
	v_mfma_f32_16x16x32_bf16 v[64:67], v[186:189], v[218:221], v[64:67]
	s_setprio 0
	s_barrier
	s_add_i32 s60, s56, s25
	v_lshl_add_u64 v[158:159], s[46:47], 0, v[130:131]
	s_mov_b32 m0, s60
	ds_read_b128 v[190:193], v167 offset:16384
	ds_read_b128 v[194:197], v167 offset:17408
	ds_read_b128 v[198:201], v167 offset:18432
	ds_read_b128 v[202:205], v167 offset:19456
	ds_read_b128 v[206:209], v167 offset:20480
	ds_read_b128 v[210:213], v167 offset:21504
	ds_read_b128 v[214:217], v167 offset:22528
	ds_read_b128 v[218:221], v167 offset:23552
	global_load_lds_dwordx4 v[158:159], off
	s_add_i32 m0, s60, 0x2000
	s_add_u32 s60, s46, 0x40000
	v_lshl_add_u64 v[162:163], s[46:47], 0, v[134:135]
	s_addc_u32 s61, s47, 0
	s_add_i32 s62, s57, s25
	global_load_lds_dwordx4 v[162:163], off
	v_lshl_add_u64 v[222:223], s[60:61], 0, v[130:131]
	s_mov_b32 m0, s62
	v_lshl_add_u64 v[224:225], s[48:49], 0, v[132:133]
	global_load_lds_dwordx4 v[222:223], off
	v_lshl_add_u64 v[222:223], s[60:61], 0, v[134:135]
	s_add_i32 m0, s62, 0x2000
	s_nop 0
	global_load_lds_dwordx4 v[222:223], off
	v_lshl_add_u64 v[222:223], s[48:49], 0, v[128:129]
	s_mov_b32 m0, s26
	s_nop 0
	global_load_lds_dwordx4 v[222:223], off
	s_mov_b32 m0, s27
	s_nop 0
	global_load_lds_dwordx4 v[224:225], off
	s_cmp_lg_i32 s59, -2
	s_cbranch_scc1 .Lrsc_a_pl
	v_lshrrev_b32_e32 v250, 6, v230
	v_lshlrev_b32_e32 v250, 11, v250
	v_and_b32_e32 v251, 63, v230
	v_lshl_or_b32 v250, v251, 4, v250
	v_lshl_add_u32 v250, s44, 14, v250
	v_readfirstlane_b32 s98, v230
	s_lshr_b32 s98, s98, 6
	s_lshl_b32 s98, s98, 11
	s_add_i32 m0, s98, 0x20000
	s_add_u32 s100, s70, 0x3f000000
	s_addc_u32 s101, s71, 0
	global_load_lds_dwordx4 v250, s[100:101]
	global_load_lds_dwordx4 v250, s[100:101] offset:1024
	s_waitcnt vmcnt(10)
	s_branch .Lrsc_b_pl

; #define PG8_STAGE(bufoff, gbase, voff) do { _Pragma("unroll") for (int _i = 0; _i < 2; ++_i) \
;         __builtin_amdgcn_global_load_lds((const unsigned*)((const char*)(gbase) + (voff)[_i]), (PG8_LAS unsigned*)(lds + (bufoff) + ldsw + _i * 8192), 16, 0, 0); } while (0)
; #define PG8_LDA(dst, b, h) do { _Pragma("unroll") for (int m = 0; m < 4; ++m) _Pragma("unroll") for (int k = 0; k < 2; ++k) dst[m][k] = *(const PG8_LAS bf16x8*)(lds + PG8_SA(b, h) + aoff + m * 2048 + k * 1024); } while (0)
; #define PG8_LDB(dst, b, h) do { _Pragma("unroll") for (int n = 0; n < 2; ++n) _Pragma("unroll") for (int k = 0; k < 2; ++k) dst[n][k] = *(const PG8_LAS bf16x8*)(lds + PG8_SB(b, h) + boff + n * 2048 + k * 1024); } while (0)
; #define PG8_MMA(ai, bj, At, Bt) do { __builtin_amdgcn_s_setprio(1); _Pragma("unroll") for (int m = 0; m < 4; ++m) _Pragma("unroll") for (int n = 0; n < 2; ++n) _Pragma("unroll") for (int k = 0; k < 2; ++k) \
;         acc[ai][bj][m][n] = __builtin_amdgcn_mfma_f32_16x16x32_bf16(Bt[n][k], At[m][k], acc[ai][bj][m][n], 0, 0, 0); __builtin_amdgcn_s_setprio(0); } while (0)
; #define PG8_WAIT_V(n) asm volatile("s_waitcnt vmcnt(" #n ")" ::: "memory")
; #define PG8_WAIT_L(n) asm volatile("s_waitcnt lgkmcnt(" #n ")" ::: "memory")
; #define PG8_BAR __builtin_amdgcn_s_barrier()
; #define PG8_SCHED __builtin_amdgcn_sched_barrier(0)
; template <class Epi, class Sched, bool ALIGN_EPI = false, bool SP2 = false>
; __device__ __forceinline__ void gemm_phase(PG8_LAS unsigned char* lds, const Gemm g, const Sched& S, const Epi& E) {
;     ...
;             PG8_WAIT_V(8); PG8_WAIT_L(0); PG8_BAR; PG8_MMA(1, 0, At, B0); PG8_MMA(1, 1, At, B1); PG8_BAR; PG8_SCHED;
;             PG8_LDB(B0, 1, 0); PG8_LDB(B1, 1, 1); PG8_SCHED; PG8_LDA(At, 1, 0); PG8_STAGE(PG8_SA(0, 1), a2 + hstep, voffA);
;             PG8_WAIT_V(8); PG8_WAIT_L(0); PG8_BAR; PG8_MMA(0, 0, At, B0); PG8_MMA(0, 1, At, B1); PG8_BAR; PG8_SCHED;
.Lrsc_b_pl:
	s_waitcnt lgkmcnt(0)
	s_barrier
	s_setprio 1
	s_waitcnt lgkmcnt(0)
	v_mfma_f32_16x16x32_bf16 v[60:63], v[146:149], v[190:193], 0
	v_mfma_f32_16x16x32_bf16 v[56:59], v[154:157], v[190:193], 0
	v_mfma_f32_16x16x32_bf16 v[44:47], v[146:149], v[198:201], 0
	v_mfma_f32_16x16x32_bf16 v[40:43], v[154:157], v[198:201], 0
	v_mfma_f32_16x16x32_bf16 v[28:31], v[146:149], v[206:209], 0
	v_mfma_f32_16x16x32_bf16 v[24:27], v[154:157], v[206:209], 0
	v_mfma_f32_16x16x32_bf16 v[12:15], v[146:149], v[214:217], 0
	v_mfma_f32_16x16x32_bf16 v[8:11], v[154:157], v[214:217], 0
	v_mfma_f32_16x16x32_bf16 v[60:63], v[150:153], v[194:197], v[60:63]
	v_mfma_f32_16x16x32_bf16 v[56:59], v[170:173], v[194:197], v[56:59]
	v_mfma_f32_16x16x32_bf16 v[44:47], v[150:153], v[202:205], v[44:47]
	v_mfma_f32_16x16x32_bf16 v[40:43], v[170:173], v[202:205], v[40:43]
	v_mfma_f32_16x16x32_bf16 v[28:31], v[150:153], v[210:213], v[28:31]
	v_mfma_f32_16x16x32_bf16 v[24:27], v[170:173], v[210:213], v[24:27]
	v_mfma_f32_16x16x32_bf16 v[12:15], v[150:153], v[218:221], v[12:15]
	v_mfma_f32_16x16x32_bf16 v[8:11], v[170:173], v[218:221], v[8:11]
	s_setprio 0
	s_setprio 1
	v_mfma_f32_16x16x32_bf16 v[52:55], v[174:177], v[190:193], 0
	v_mfma_f32_16x16x32_bf16 v[48:51], v[182:185], v[190:193], 0
	v_mfma_f32_16x16x32_bf16 v[36:39], v[174:177], v[198:201], 0
	v_mfma_f32_16x16x32_bf16 v[32:35], v[182:185], v[198:201], 0
	v_mfma_f32_16x16x32_bf16 v[20:23], v[174:177], v[206:209], 0
	v_mfma_f32_16x16x32_bf16 v[16:19], v[182:185], v[206:209], 0
	v_mfma_f32_16x16x32_bf16 v[4:7], v[174:177], v[214:217], 0
	v_mfma_f32_16x16x32_bf16 v[0:3], v[182:185], v[214:217], 0
	v_mfma_f32_16x16x32_bf16 v[52:55], v[178:181], v[194:197], v[52:55]
	v_mfma_f32_16x16x32_bf16 v[48:51], v[186:189], v[194:197], v[48:51]
	v_mfma_f32_16x16x32_bf16 v[36:39], v[178:181], v[202:205], v[36:39]
	v_mfma_f32_16x16x32_bf16 v[32:35], v[186:189], v[202:205], v[32:35]
	v_mfma_f32_16x16x32_bf16 v[20:23], v[178:181], v[210:213], v[20:23]
	v_mfma_f32_16x16x32_bf16 v[16:19], v[186:189], v[210:213], v[16:19]
	v_mfma_f32_16x16x32_bf16 v[4:7], v[178:181], v[218:221], v[4:7]
	v_mfma_f32_16x16x32_bf16 v[0:3], v[186:189], v[218:221], v[0:3]
	s_setprio 0
	s_barrier
	s_add_i32 s60, 0, 0x18000
	v_add_u32_e32 v160, s60, v164
	s_add_i32 s61, 0, 0x1c000
	ds_read_b128 v[146:149], v160
	ds_read_b128 v[150:153], v160 offset:1024
	ds_read_b128 v[154:157], v160 offset:2048
	ds_read_b128 v[170:173], v160 offset:3072
	v_add_u32_e32 v160, s61, v164
	ds_read_b128 v[174:177], v160
	ds_read_b128 v[178:181], v160 offset:1024
	ds_read_b128 v[182:185], v160 offset:2048
	ds_read_b128 v[186:189], v160 offset:3072
	s_add_u32 s48, s48, 0x40000
	s_addc_u32 s49, s49, 0
	s_mov_b32 m0, s28
	v_lshl_add_u64 v[226:227], s[48:49], 0, v[128:129]
	ds_read_b128 v[190:193], v167 offset:32768
	ds_read_b128 v[194:197], v167 offset:33792
	ds_read_b128 v[198:201], v167 offset:34816
	ds_read_b128 v[202:205], v167 offset:35840
	ds_read_b128 v[206:209], v167 offset:36864
	ds_read_b128 v[210:213], v167 offset:37888
	ds_read_b128 v[214:217], v167 offset:38912
	ds_read_b128 v[218:221], v167 offset:39936
	global_load_lds_dwordx4 v[226:227], off
	v_lshl_add_u64 v[226:227], s[48:49], 0, v[132:133]
	s_mov_b32 m0, s29
	s_nop 0
	global_load_lds_dwordx4 v[226:227], off
	s_cmp_lg_i32 s59, -2
	s_cbranch_scc1 .Lrsc_c_pl
	s_waitcnt vmcnt(10)
	s_branch .Lrsc_d_pl

; #define PG8_STAGE(bufoff, gbase, voff) do { _Pragma("unroll") for (int _i = 0; _i < 2; ++_i) \
;         __builtin_amdgcn_global_load_lds((const unsigned*)((const char*)(gbase) + (voff)[_i]), (PG8_LAS unsigned*)(lds + (bufoff) + ldsw + _i * 8192), 16, 0, 0); } while (0)
; #define PG8_LDA(dst, b, h) do { _Pragma("unroll") for (int m = 0; m < 4; ++m) _Pragma("unroll") for (int k = 0; k < 2; ++k) dst[m][k] = *(const PG8_LAS bf16x8*)(lds + PG8_SA(b, h) + aoff + m * 2048 + k * 1024); } while (0)
; #define PG8_MMA(ai, bj, At, Bt) do { __builtin_amdgcn_s_setprio(1); _Pragma("unroll") for (int m = 0; m < 4; ++m) _Pragma("unroll") for (int n = 0; n < 2; ++n) _Pragma("unroll") for (int k = 0; k < 2; ++k) \
;         acc[ai][bj][m][n] = __builtin_amdgcn_mfma_f32_16x16x32_bf16(Bt[n][k], At[m][k], acc[ai][bj][m][n], 0, 0, 0); __builtin_amdgcn_s_setprio(0); } while (0)
; #define PG8_WAIT_V(n) asm volatile("s_waitcnt vmcnt(" #n ")" ::: "memory")
; #define PG8_WAIT_L(n) asm volatile("s_waitcnt lgkmcnt(" #n ")" ::: "memory")
; #define PG8_BAR __builtin_amdgcn_s_barrier()
; #define PG8_SCHED __builtin_amdgcn_sched_barrier(0)
; template <class Epi, class Sched, bool ALIGN_EPI = false, bool SP2 = false>
; __device__ __forceinline__ void gemm_phase(PG8_LAS unsigned char* lds, const Gemm g, const Sched& S, const Epi& E) {
;     ...
;             PG8_WAIT_V(8); PG8_WAIT_L(0); PG8_BAR; PG8_MMA(0, 0, At, B0); PG8_MMA(0, 1, At, B1); PG8_BAR; PG8_SCHED;
;             PG8_LDA(At, 1, 1); PG8_STAGE(PG8_SB(1, 0), b3, voffB); PG8_STAGE(PG8_SB(1, 1), b3 + hstep, voffB); PG8_STAGE(PG8_SA(1, 0), a3, voffA);
;             PG8_WAIT_V(8); PG8_WAIT_L(0); PG8_BAR; PG8_MMA(1, 0, At, B0); PG8_MMA(1, 1, At, B1); PG8_BAR; PG8_SCHED;
.Lrsc_d_pl:
	s_waitcnt lgkmcnt(0)
	s_barrier
	s_setprio 1
	s_waitcnt lgkmcnt(0)
	v_mfma_f32_16x16x32_bf16 v[124:127], v[146:149], v[190:193], v[124:127]
	v_mfma_f32_16x16x32_bf16 v[120:123], v[154:157], v[190:193], v[120:123]
	v_mfma_f32_16x16x32_bf16 v[108:111], v[146:149], v[198:201], v[108:111]
	v_mfma_f32_16x16x32_bf16 v[104:107], v[154:157], v[198:201], v[104:107]
	v_mfma_f32_16x16x32_bf16 v[92:95], v[146:149], v[206:209], v[92:95]
	v_mfma_f32_16x16x32_bf16 v[88:91], v[154:157], v[206:209], v[88:91]
	v_mfma_f32_16x16x32_bf16 v[76:79], v[146:149], v[214:217], v[76:79]
	v_mfma_f32_16x16x32_bf16 v[72:75], v[154:157], v[214:217], v[72:75]
	v_mfma_f32_16x16x32_bf16 v[124:127], v[150:153], v[194:197], v[124:127]
	v_mfma_f32_16x16x32_bf16 v[120:123], v[170:173], v[194:197], v[120:123]
	v_mfma_f32_16x16x32_bf16 v[108:111], v[150:153], v[202:205], v[108:111]
	v_mfma_f32_16x16x32_bf16 v[104:107], v[170:173], v[202:205], v[104:107]
	v_mfma_f32_16x16x32_bf16 v[92:95], v[150:153], v[210:213], v[92:95]
	v_mfma_f32_16x16x32_bf16 v[88:91], v[170:173], v[210:213], v[88:91]
	v_mfma_f32_16x16x32_bf16 v[76:79], v[150:153], v[218:221], v[76:79]
	v_mfma_f32_16x16x32_bf16 v[72:75], v[170:173], v[218:221], v[72:75]
	s_setprio 0
	s_setprio 1
	v_mfma_f32_16x16x32_bf16 v[116:119], v[174:177], v[190:193], v[116:119]
	v_mfma_f32_16x16x32_bf16 v[112:115], v[182:185], v[190:193], v[112:115]
	v_mfma_f32_16x16x32_bf16 v[100:103], v[174:177], v[198:201], v[100:103]
	v_mfma_f32_16x16x32_bf16 v[96:99], v[182:185], v[198:201], v[96:99]
	v_mfma_f32_16x16x32_bf16 v[84:87], v[174:177], v[206:209], v[84:87]
	v_mfma_f32_16x16x32_bf16 v[80:83], v[182:185], v[206:209], v[80:83]
	v_mfma_f32_16x16x32_bf16 v[68:71], v[174:177], v[214:217], v[68:71]
	v_mfma_f32_16x16x32_bf16 v[64:67], v[182:185], v[214:217], v[64:67]
	v_mfma_f32_16x16x32_bf16 v[116:119], v[178:181], v[194:197], v[116:119]
	v_mfma_f32_16x16x32_bf16 v[112:115], v[186:189], v[194:197], v[112:115]
	v_mfma_f32_16x16x32_bf16 v[100:103], v[178:181], v[202:205], v[100:103]
	v_mfma_f32_16x16x32_bf16 v[96:99], v[186:189], v[202:205], v[96:99]
	v_mfma_f32_16x16x32_bf16 v[84:87], v[178:181], v[210:213], v[84:87]
	v_mfma_f32_16x16x32_bf16 v[80:83], v[186:189], v[210:213], v[80:83]
	v_mfma_f32_16x16x32_bf16 v[68:71], v[178:181], v[218:221], v[68:71]
	v_mfma_f32_16x16x32_bf16 v[64:67], v[186:189], v[218:221], v[64:67]
	s_setprio 0
	s_barrier
	s_add_i32 s48, s60, s25
	v_lshl_add_u64 v[158:159], v[158:159], 0, s[16:17]
	s_mov_b32 m0, s48
	ds_read_b128 v[190:193], v167 offset:49152
	ds_read_b128 v[194:197], v167 offset:50176
	ds_read_b128 v[198:201], v167 offset:51200
	ds_read_b128 v[202:205], v167 offset:52224
	ds_read_b128 v[206:209], v167 offset:53248
	ds_read_b128 v[210:213], v167 offset:54272
	ds_read_b128 v[214:217], v167 offset:55296
	ds_read_b128 v[218:221], v167 offset:56320
	global_load_lds_dwordx4 v[158:159], off
	s_add_i32 m0, s48, 0x2000
	s_add_u32 s46, s46, 0x40080
	v_lshl_add_u64 v[158:159], v[162:163], 0, s[16:17]
	s_addc_u32 s47, s47, 0
	s_add_i32 s48, s61, s25
	global_load_lds_dwordx4 v[158:159], off
	v_lshl_add_u64 v[158:159], s[46:47], 0, v[130:131]
	s_mov_b32 m0, s48
	s_nop 0
	global_load_lds_dwordx4 v[158:159], off
	v_lshl_add_u64 v[158:159], s[46:47], 0, v[134:135]
	s_add_i32 m0, s48, 0x2000
	s_nop 0
	global_load_lds_dwordx4 v[158:159], off
	v_lshl_add_u64 v[158:159], v[222:223], 0, s[16:17]
	s_mov_b32 m0, s31
	s_nop 0
	global_load_lds_dwordx4 v[158:159], off
	v_lshl_add_u64 v[158:159], v[224:225], 0, s[16:17]
	s_mov_b32 m0, s33
	s_nop 0
	global_load_lds_dwordx4 v[158:159], off
	s_waitcnt vmcnt(8)
	s_waitcnt lgkmcnt(0)
	s_barrier
	s_setprio 1
	s_waitcnt lgkmcnt(0)
	v_mfma_f32_16x16x32_bf16 v[60:63], v[146:149], v[190:193], v[60:63]
	v_mfma_f32_16x16x32_bf16 v[56:59], v[154:157], v[190:193], v[56:59]
	v_mfma_f32_16x16x32_bf16 v[44:47], v[146:149], v[198:201], v[44:47]
	v_mfma_f32_16x16x32_bf16 v[40:43], v[154:157], v[198:201], v[40:43]
	v_mfma_f32_16x16x32_bf16 v[28:31], v[146:149], v[206:209], v[28:31]
	v_mfma_f32_16x16x32_bf16 v[24:27], v[154:157], v[206:209], v[24:27]
	v_mfma_f32_16x16x32_bf16 v[12:15], v[146:149], v[214:217], v[12:15]
	v_mfma_f32_16x16x32_bf16 v[8:11], v[154:157], v[214:217], v[8:11]
	v_mfma_f32_16x16x32_bf16 v[60:63], v[150:153], v[194:197], v[60:63]
	v_mfma_f32_16x16x32_bf16 v[56:59], v[170:173], v[194:197], v[56:59]
	v_mfma_f32_16x16x32_bf16 v[44:47], v[150:153], v[202:205], v[44:47]
	v_mfma_f32_16x16x32_bf16 v[40:43], v[170:173], v[202:205], v[40:43]
	v_mfma_f32_16x16x32_bf16 v[28:31], v[150:153], v[210:213], v[28:31]
	v_mfma_f32_16x16x32_bf16 v[24:27], v[170:173], v[210:213], v[24:27]
	v_mfma_f32_16x16x32_bf16 v[12:15], v[150:153], v[218:221], v[12:15]
	v_mfma_f32_16x16x32_bf16 v[8:11], v[170:173], v[218:221], v[8:11]
	s_setprio 0
	s_setprio 1
	v_mfma_f32_16x16x32_bf16 v[52:55], v[174:177], v[190:193], v[52:55]
	v_mfma_f32_16x16x32_bf16 v[48:51], v[182:185], v[190:193], v[48:51]
	v_mfma_f32_16x16x32_bf16 v[36:39], v[174:177], v[198:201], v[36:39]
	v_mfma_f32_16x16x32_bf16 v[32:35], v[182:185], v[198:201], v[32:35]
	v_mfma_f32_16x16x32_bf16 v[20:23], v[174:177], v[206:209], v[20:23]
	v_mfma_f32_16x16x32_bf16 v[16:19], v[182:185], v[206:209], v[16:19]
	v_mfma_f32_16x16x32_bf16 v[4:7], v[174:177], v[214:217], v[4:7]
	v_mfma_f32_16x16x32_bf16 v[0:3], v[182:185], v[214:217], v[0:3]
	v_mfma_f32_16x16x32_bf16 v[52:55], v[178:181], v[194:197], v[52:55]
	v_mfma_f32_16x16x32_bf16 v[48:51], v[186:189], v[194:197], v[48:51]
	v_mfma_f32_16x16x32_bf16 v[36:39], v[178:181], v[202:205], v[36:39]
	v_mfma_f32_16x16x32_bf16 v[32:35], v[186:189], v[202:205], v[32:35]
	v_mfma_f32_16x16x32_bf16 v[20:23], v[178:181], v[210:213], v[20:23]
	v_mfma_f32_16x16x32_bf16 v[16:19], v[186:189], v[210:213], v[16:19]
	v_mfma_f32_16x16x32_bf16 v[4:7], v[178:181], v[218:221], v[4:7]
	v_mfma_f32_16x16x32_bf16 v[0:3], v[186:189], v[218:221], v[0:3]
	s_setprio 0
	s_barrier
	s_add_i32 s59, s59, 2
	s_add_u32 s0, s0, 0x100
	s_addc_u32 s1, s1, 0
	s_add_u32 s50, s50, 0x100
	s_addc_u32 s51, s51, 0
	s_cmp_gt_u32 s59, 13
; #define PG8_STAGE(bufoff, gbase, voff) do { _Pragma("unroll") for (int _i = 0; _i < 2; ++_i) \
;         __builtin_amdgcn_global_load_lds((const unsigned*)((const char*)(gbase) + (voff)[_i]), (PG8_LAS unsigned*)(lds + (bufoff) + ldsw + _i * 8192), 16, 0, 0); } while (0)
; #define PG8_LDA(dst, b, h) do { _Pragma("unroll") for (int m = 0; m < 4; ++m) _Pragma("unroll") for (int k = 0; k < 2; ++k) dst[m][k] = *(const PG8_LAS bf16x8*)(lds + PG8_SA(b, h) + aoff + m * 2048 + k * 1024); } while (0)
; #define PG8_LDB(dst, b, h) do { _Pragma("unroll") for (int n = 0; n < 2; ++n) _Pragma("unroll") for (int k = 0; k < 2; ++k) dst[n][k] = *(const PG8_LAS bf16x8*)(lds + PG8_SB(b, h) + boff + n * 2048 + k * 1024); } while (0)
; #define PG8_MMA(ai, bj, At, Bt) do { __builtin_amdgcn_s_setprio(1); _Pragma("unroll") for (int m = 0; m < 4; ++m) _Pragma("unroll") for (int n = 0; n < 2; ++n) _Pragma("unroll") for (int k = 0; k < 2; ++k) \
;         acc[ai][bj][m][n] = __builtin_amdgcn_mfma_f32_16x16x32_bf16(Bt[n][k], At[m][k], acc[ai][bj][m][n], 0, 0, 0); __builtin_amdgcn_s_setprio(0); } while (0)
; #define PG8_WAIT_V(n) asm volatile("s_waitcnt vmcnt(" #n ")" ::: "memory")
; #define PG8_WAIT_L(n) asm volatile("s_waitcnt lgkmcnt(" #n ")" ::: "memory")
; #define PG8_BAR __builtin_amdgcn_s_barrier()
; #define PG8_SCHED __builtin_amdgcn_sched_barrier(0)
; template <class Epi, class Sched, bool ALIGN_EPI = false, bool SP2 = false>
; __device__ __forceinline__ void gemm_phase(PG8_LAS unsigned char* lds, const Gemm g, const Sched& S, const Epi& E) {
;     ...
;             PG8_LDB(B0, 0, 0); PG8_LDB(B1, 0, 1); PG8_SCHED; PG8_LDA(At, 0, 0); PG8_STAGE(PG8_SA(1, 1), a1 + hstep, voffA);
;             PG8_WAIT_V(8); PG8_WAIT_L(0); PG8_BAR; PG8_MMA(0, 0, At, B0); PG8_MMA(0, 1, At, B1); PG8_BAR; PG8_SCHED;
;             PG8_LDA(At, 0, 1); PG8_STAGE(PG8_SB(0, 0), b2, voffB); PG8_STAGE(PG8_SB(0, 1), b2 + hstep, voffB); PG8_STAGE(PG8_SA(0, 0), a2, voffA);
;             PG8_WAIT_V(8); PG8_WAIT_L(0); PG8_BAR; PG8_MMA(1, 0, At, B0); PG8_MMA(1, 1, At, B1); PG8_BAR; PG8_SCHED;
.LBB0_660:
	ds_read_b128 v[146:149], v165
	ds_read_b128 v[150:153], v165 offset:1024
	ds_read_b128 v[154:157], v165 offset:2048
	ds_read_b128 v[170:173], v165 offset:3072
	ds_read_b128 v[174:177], v166
	ds_read_b128 v[178:181], v166 offset:1024
	ds_read_b128 v[182:185], v166 offset:2048
	ds_read_b128 v[186:189], v166 offset:3072
	s_add_u32 s46, s0, 0xfffc0080
	s_addc_u32 s47, s1, -1
	s_cmp_eq_u32 s59, 12
	s_cselect_b32 s49, s5, s47
	s_cselect_b32 s48, s37, s46
	s_cselect_b32 s47, s21, s51
	s_cselect_b32 s46, s45, s50
	v_lshl_add_u64 v[158:159], s[0:1], 0, v[140:141]
	s_add_i32 m0, s26, 0xc000
	ds_read_b128 v[190:193], v167
	ds_read_b128 v[194:197], v167 offset:1024
	ds_read_b128 v[198:201], v167 offset:2048
	ds_read_b128 v[202:205], v167 offset:3072
	ds_read_b128 v[206:209], v167 offset:4096
	ds_read_b128 v[210:213], v167 offset:5120
	ds_read_b128 v[214:217], v167 offset:6144
	ds_read_b128 v[218:221], v167 offset:7168
	global_load_lds_dwordx4 v[158:159], off
	v_lshl_add_u64 v[158:159], s[0:1], 0, v[142:143]
	s_add_i32 m0, s26, 0xe000
	s_nop 0
	global_load_lds_dwordx4 v[158:159], off
	s_waitcnt vmcnt(8)
	s_waitcnt lgkmcnt(0)
	s_barrier
	s_setprio 1
	s_waitcnt lgkmcnt(0)
	v_mfma_f32_16x16x32_bf16 v[124:127], v[146:149], v[190:193], v[124:127]
	v_mfma_f32_16x16x32_bf16 v[120:123], v[154:157], v[190:193], v[120:123]
	v_mfma_f32_16x16x32_bf16 v[108:111], v[146:149], v[198:201], v[108:111]
	v_mfma_f32_16x16x32_bf16 v[104:107], v[154:157], v[198:201], v[104:107]
	v_mfma_f32_16x16x32_bf16 v[92:95], v[146:149], v[206:209], v[92:95]
	v_mfma_f32_16x16x32_bf16 v[88:91], v[154:157], v[206:209], v[88:91]
	v_mfma_f32_16x16x32_bf16 v[76:79], v[146:149], v[214:217], v[76:79]
	v_mfma_f32_16x16x32_bf16 v[72:75], v[154:157], v[214:217], v[72:75]
	v_mfma_f32_16x16x32_bf16 v[124:127], v[150:153], v[194:197], v[124:127]
	v_mfma_f32_16x16x32_bf16 v[120:123], v[170:173], v[194:197], v[120:123]
	v_mfma_f32_16x16x32_bf16 v[108:111], v[150:153], v[202:205], v[108:111]
	v_mfma_f32_16x16x32_bf16 v[104:107], v[170:173], v[202:205], v[104:107]
	v_mfma_f32_16x16x32_bf16 v[92:95], v[150:153], v[210:213], v[92:95]
	v_mfma_f32_16x16x32_bf16 v[88:91], v[170:173], v[210:213], v[88:91]
	v_mfma_f32_16x16x32_bf16 v[76:79], v[150:153], v[218:221], v[76:79]
	v_mfma_f32_16x16x32_bf16 v[72:75], v[170:173], v[218:221], v[72:75]
	s_setprio 0
	s_setprio 1
	v_mfma_f32_16x16x32_bf16 v[116:119], v[174:177], v[190:193], v[116:119]
	v_mfma_f32_16x16x32_bf16 v[112:115], v[182:185], v[190:193], v[112:115]
	v_mfma_f32_16x16x32_bf16 v[100:103], v[174:177], v[198:201], v[100:103]
	v_mfma_f32_16x16x32_bf16 v[96:99], v[182:185], v[198:201], v[96:99]
	v_mfma_f32_16x16x32_bf16 v[84:87], v[174:177], v[206:209], v[84:87]
	v_mfma_f32_16x16x32_bf16 v[80:83], v[182:185], v[206:209], v[80:83]
	v_mfma_f32_16x16x32_bf16 v[68:71], v[174:177], v[214:217], v[68:71]
	v_mfma_f32_16x16x32_bf16 v[64:67], v[182:185], v[214:217], v[64:67]
	v_mfma_f32_16x16x32_bf16 v[116:119], v[178:181], v[194:197], v[116:119]
	v_mfma_f32_16x16x32_bf16 v[112:115], v[186:189], v[194:197], v[112:115]
	v_mfma_f32_16x16x32_bf16 v[100:103], v[178:181], v[202:205], v[100:103]
	v_mfma_f32_16x16x32_bf16 v[96:99], v[186:189], v[202:205], v[96:99]
	v_mfma_f32_16x16x32_bf16 v[84:87], v[178:181], v[210:213], v[84:87]
	v_mfma_f32_16x16x32_bf16 v[80:83], v[186:189], v[210:213], v[80:83]
	v_mfma_f32_16x16x32_bf16 v[68:71], v[178:181], v[218:221], v[68:71]
	v_mfma_f32_16x16x32_bf16 v[64:67], v[186:189], v[218:221], v[64:67]
	s_setprio 0
	s_barrier
	s_add_i32 s60, s56, s25
	v_lshl_add_u64 v[158:159], s[46:47], 0, v[130:131]
	s_mov_b32 m0, s60
	ds_read_b128 v[190:193], v167 offset:16384
	ds_read_b128 v[194:197], v167 offset:17408
	ds_read_b128 v[198:201], v167 offset:18432
	ds_read_b128 v[202:205], v167 offset:19456
	ds_read_b128 v[206:209], v167 offset:20480
	ds_read_b128 v[210:213], v167 offset:21504
	ds_read_b128 v[214:217], v167 offset:22528
	ds_read_b128 v[218:221], v167 offset:23552
	global_load_lds_dwordx4 v[158:159], off
	s_add_i32 m0, s60, 0x2000
	s_add_u32 s60, s46, 0x40000
	v_lshl_add_u64 v[162:163], s[46:47], 0, v[134:135]
	s_addc_u32 s61, s47, 0
	s_add_i32 s62, s57, s25
	global_load_lds_dwordx4 v[162:163], off
	v_lshl_add_u64 v[222:223], s[60:61], 0, v[130:131]
	s_mov_b32 m0, s62
	v_lshl_add_u64 v[224:225], s[48:49], 0, v[132:133]
	global_load_lds_dwordx4 v[222:223], off
	v_lshl_add_u64 v[222:223], s[60:61], 0, v[134:135]
	s_add_i32 m0, s62, 0x2000
	s_nop 0
	global_load_lds_dwordx4 v[222:223], off
	v_lshl_add_u64 v[222:223], s[48:49], 0, v[128:129]
	s_mov_b32 m0, s26
	s_nop 0
	global_load_lds_dwordx4 v[222:223], off
	s_mov_b32 m0, s27
	s_nop 0
	global_load_lds_dwordx4 v[224:225], off
	s_cmp_lg_i32 s59, -2
	s_cbranch_scc1 .Lrsc_a
	v_lshrrev_b32_e32 v250, 6, v230
	v_lshlrev_b32_e32 v250, 11, v250
	v_and_b32_e32 v251, 63, v230
	v_lshl_or_b32 v250, v251, 4, v250
	v_lshl_add_u32 v250, s44, 14, v250
	v_readfirstlane_b32 s98, v230
	s_lshr_b32 s98, s98, 6
	s_lshl_b32 s98, s98, 11
	s_add_i32 m0, s98, 0x20000
	s_add_u32 s100, s70, 0x3f000000
	s_addc_u32 s101, s71, 0
	global_load_lds_dwordx4 v250, s[100:101]
	global_load_lds_dwordx4 v250, s[100:101] offset:1024
	s_waitcnt vmcnt(10)
	s_branch .Lrsc_b

; #define PG8_STAGE(bufoff, gbase, voff) do { _Pragma("unroll") for (int _i = 0; _i < 2; ++_i) \
;         __builtin_amdgcn_global_load_lds((const unsigned*)((const char*)(gbase) + (voff)[_i]), (PG8_LAS unsigned*)(lds + (bufoff) + ldsw + _i * 8192), 16, 0, 0); } while (0)
; #define PG8_LDA(dst, b, h) do { _Pragma("unroll") for (int m = 0; m < 4; ++m) _Pragma("unroll") for (int k = 0; k < 2; ++k) dst[m][k] = *(const PG8_LAS bf16x8*)(lds + PG8_SA(b, h) + aoff + m * 2048 + k * 1024); } while (0)
; #define PG8_LDB(dst, b, h) do { _Pragma("unroll") for (int n = 0; n < 2; ++n) _Pragma("unroll") for (int k = 0; k < 2; ++k) dst[n][k] = *(const PG8_LAS bf16x8*)(lds + PG8_SB(b, h) + boff + n * 2048 + k * 1024); } while (0)
; #define PG8_WAIT_V(n) asm volatile("s_waitcnt vmcnt(" #n ")" ::: "memory")
; #define PG8_WAIT_L(n) asm volatile("s_waitcnt lgkmcnt(" #n ")" ::: "memory")
; #define PG8_BAR __builtin_amdgcn_s_barrier()
; #define PG8_SCHED __builtin_amdgcn_sched_barrier(0)
; template <class Epi, class Sched, bool ALIGN_EPI = false, bool SP2 = false>
; __device__ __forceinline__ void gemm_phase(PG8_LAS unsigned char* lds, const Gemm g, const Sched& S, const Epi& E) {
;     ...
;         const char* nA = has_next ? (const char*)g.A + (size_t)nxt.pm * tstep : cA; const char* nB = has_next ? (const char*)g.Bt + (size_t)nxt.pn * tstep : cB;
;         for (int t = 0; t < nt; t += 2) {
;             const bool last = (t == nt - 2);
;             const char* a1 = cA + (size_t)(t + 1) * kstep;
;             const char* a2 = last ? nA : cA + (size_t)(t + 2) * kstep; const char* b2 = last ? nB : cB + (size_t)(t + 2) * kstep;
;             const char* a3 = a2 + kstep; const char* b3 = b2 + kstep;
;             if (last && has_next) S.a_ready(nxt);
;             if constexpr (SP2) {
;             PG8_LDB(B0, 0, 0); PG8_LDB(B1, 0, 1); PG8_SCHED; PG8_LDA(At, 0, 0); PG8_STAGE(PG8_SA(1, 1), a1 + hstep, voffA);
;             PG8_WAIT_V(8); PG8_WAIT_L(0); PG8_BAR; PG8_MMA(0, 0, At, B0); PG8_MMA(0, 1, At, B1); PG8_BAR; PG8_SCHED;
;             PG8_LDA(At, 0, 1); PG8_STAGE(PG8_SB(0, 0), b2, voffB); PG8_STAGE(PG8_SB(0, 1), b2 + hstep, voffB); PG8_STAGE(PG8_SA(0, 0), a2, voffA);
;             PG8_WAIT_V(8); PG8_WAIT_L(0); PG8_BAR; PG8_MMA(1, 0, At, B0); PG8_MMA(1, 1, At, B1); PG8_BAR; PG8_SCHED;
.LBB0_887:
	s_ashr_i32 s23, s22, 31
	s_lshl_b64 s[26:27], s[22:23], 19
	s_add_u32 s26, s68, s26
	s_addc_u32 s27, s69, s27
	s_and_b64 s[28:29], s[24:25], exec
	s_cselect_b32 s23, s27, s37
	s_cselect_b32 s31, s26, s36
	s_ashr_i32 s21, s20, 31
	s_lshl_b64 s[28:29], s[20:21], 19
	s_add_u32 s28, s42, s28
	s_addc_u32 s29, s43, s29
	s_and_b64 s[40:41], s[24:25], exec
	s_cselect_b32 s21, s29, s39
	s_cselect_b32 s58, s28, s38
	s_add_u32 s36, s36, 0x40080
	s_addc_u32 s37, s37, 0
	s_add_u32 s59, s38, 0x100
	s_addc_u32 s60, s39, 0
	s_mov_b32 s61, -2
	s_waitcnt lgkmcnt(0)
	ds_read_b128 v[124:127], v234
	ds_read_b128 v[132:135], v234 offset:1024
	ds_read_b128 v[136:139], v234 offset:2048
	ds_read_b128 v[140:143], v234 offset:3072
	ds_read_b128 v[144:147], v235
	ds_read_b128 v[148:151], v235 offset:1024
	ds_read_b128 v[152:155], v235 offset:2048
	ds_read_b128 v[156:159], v235 offset:3072
	s_add_u32 s38, s36, 0xfffc0080
	s_addc_u32 s39, s37, -1
	s_cmp_eq_u32 s61, 12
	s_cselect_b32 s41, s23, s39
	s_cselect_b32 s40, s31, s38
	s_cselect_b32 s39, s21, s60
	s_cselect_b32 s38, s58, s59
	v_lshl_add_u64 v[206:207], s[36:37], 0, v[192:193]
	s_add_i32 m0, s45, 0xc000
	ds_read_b128 v[160:163], v236
	ds_read_b128 v[164:167], v236 offset:1024
	ds_read_b128 v[168:171], v236 offset:2048
	ds_read_b128 v[172:175], v236 offset:3072
	ds_read_b128 v[176:179], v236 offset:4096
	ds_read_b128 v[180:183], v236 offset:5120
	ds_read_b128 v[198:201], v236 offset:6144
	ds_read_b128 v[202:205], v236 offset:7168
	global_load_lds_dwordx4 v[206:207], off
	v_lshl_add_u64 v[206:207], s[36:37], 0, v[194:195]
	s_add_i32 m0, s45, 0xe000
	s_nop 0
	global_load_lds_dwordx4 v[206:207], off
	s_waitcnt vmcnt(8)
	s_waitcnt lgkmcnt(0)
	s_barrier
	s_setprio 1
	s_waitcnt lgkmcnt(0)
	v_mfma_f32_16x16x32_bf16 v[128:131], v[124:127], v[160:163], 0
	v_mfma_f32_16x16x32_bf16 v[120:123], v[136:139], v[160:163], 0
	v_mfma_f32_16x16x32_bf16 v[108:111], v[124:127], v[168:171], 0
	v_mfma_f32_16x16x32_bf16 v[104:107], v[136:139], v[168:171], 0
	v_mfma_f32_16x16x32_bf16 v[92:95], v[124:127], v[176:179], 0
	v_mfma_f32_16x16x32_bf16 v[88:91], v[136:139], v[176:179], 0
	v_mfma_f32_16x16x32_bf16 v[76:79], v[124:127], v[198:201], 0
	v_mfma_f32_16x16x32_bf16 v[72:75], v[136:139], v[198:201], 0
	v_mfma_f32_16x16x32_bf16 v[128:131], v[132:135], v[164:167], v[128:131]
	v_mfma_f32_16x16x32_bf16 v[120:123], v[140:143], v[164:167], v[120:123]
	v_mfma_f32_16x16x32_bf16 v[108:111], v[132:135], v[172:175], v[108:111]
	v_mfma_f32_16x16x32_bf16 v[104:107], v[140:143], v[172:175], v[104:107]
	v_mfma_f32_16x16x32_bf16 v[92:95], v[132:135], v[180:183], v[92:95]
	v_mfma_f32_16x16x32_bf16 v[88:91], v[140:143], v[180:183], v[88:91]
	v_mfma_f32_16x16x32_bf16 v[76:79], v[132:135], v[202:205], v[76:79]
	v_mfma_f32_16x16x32_bf16 v[72:75], v[140:143], v[202:205], v[72:75]
	s_setprio 0
	s_setprio 1
	v_mfma_f32_16x16x32_bf16 v[116:119], v[144:147], v[160:163], 0
	v_mfma_f32_16x16x32_bf16 v[112:115], v[152:155], v[160:163], 0
	v_mfma_f32_16x16x32_bf16 v[100:103], v[144:147], v[168:171], 0
	v_mfma_f32_16x16x32_bf16 v[96:99], v[152:155], v[168:171], 0
	v_mfma_f32_16x16x32_bf16 v[84:87], v[144:147], v[176:179], 0
	v_mfma_f32_16x16x32_bf16 v[80:83], v[152:155], v[176:179], 0
	v_mfma_f32_16x16x32_bf16 v[68:71], v[144:147], v[198:201], 0
	v_mfma_f32_16x16x32_bf16 v[64:67], v[152:155], v[198:201], 0
	v_mfma_f32_16x16x32_bf16 v[116:119], v[148:151], v[164:167], v[116:119]
	v_mfma_f32_16x16x32_bf16 v[112:115], v[156:159], v[164:167], v[112:115]
	v_mfma_f32_16x16x32_bf16 v[100:103], v[148:151], v[172:175], v[100:103]
	v_mfma_f32_16x16x32_bf16 v[96:99], v[156:159], v[172:175], v[96:99]
	v_mfma_f32_16x16x32_bf16 v[84:87], v[148:151], v[180:183], v[84:87]
	v_mfma_f32_16x16x32_bf16 v[80:83], v[156:159], v[180:183], v[80:83]
	v_mfma_f32_16x16x32_bf16 v[68:71], v[148:151], v[202:205], v[68:71]
	v_mfma_f32_16x16x32_bf16 v[64:67], v[156:159], v[202:205], v[64:67]
	s_setprio 0
	s_barrier
	s_add_i32 s62, s55, s44
	v_lshl_add_u64 v[206:207], s[38:39], 0, v[186:187]
	s_mov_b32 m0, s62
	ds_read_b128 v[160:163], v236 offset:16384
	ds_read_b128 v[164:167], v236 offset:17408
	ds_read_b128 v[168:171], v236 offset:18432
	ds_read_b128 v[172:175], v236 offset:19456
	ds_read_b128 v[176:179], v236 offset:20480
	ds_read_b128 v[180:183], v236 offset:21504
	ds_read_b128 v[198:201], v236 offset:22528
	ds_read_b128 v[202:205], v236 offset:23552
	global_load_lds_dwordx4 v[206:207], off
	s_add_i32 m0, s62, 0x2000
	s_add_u32 s62, s38, 0x40000
	v_lshl_add_u64 v[208:209], s[38:39], 0, v[190:191]
	s_addc_u32 s63, s39, 0
	s_add_i32 s64, s56, s44
	global_load_lds_dwordx4 v[208:209], off
	v_lshl_add_u64 v[210:211], s[62:63], 0, v[186:187]
	s_mov_b32 m0, s64
	v_lshl_add_u64 v[212:213], s[40:41], 0, v[188:189]
	global_load_lds_dwordx4 v[210:211], off
	v_lshl_add_u64 v[210:211], s[62:63], 0, v[190:191]
	s_add_i32 m0, s64, 0x2000
	s_nop 0
	global_load_lds_dwordx4 v[210:211], off
	v_lshl_add_u64 v[210:211], s[40:41], 0, v[184:185]
	s_mov_b32 m0, s45
	s_nop 0
	global_load_lds_dwordx4 v[210:211], off
	s_mov_b32 m0, s46
	s_nop 0
	global_load_lds_dwordx4 v[212:213], off
	s_waitcnt vmcnt(8)
	s_waitcnt lgkmcnt(0)
	s_barrier
; #define PG8_STAGE(bufoff, gbase, voff) do { _Pragma("unroll") for (int _i = 0; _i < 2; ++_i) \
;         __builtin_amdgcn_global_load_lds((const unsigned*)((const char*)(gbase) + (voff)[_i]), (PG8_LAS unsigned*)(lds + (bufoff) + ldsw + _i * 8192), 16, 0, 0); } while (0)
; #define PG8_LDA(dst, b, h) do { _Pragma("unroll") for (int m = 0; m < 4; ++m) _Pragma("unroll") for (int k = 0; k < 2; ++k) dst[m][k] = *(const PG8_LAS bf16x8*)(lds + PG8_SA(b, h) + aoff + m * 2048 + k * 1024); } while (0)
; #define PG8_LDB(dst, b, h) do { _Pragma("unroll") for (int n = 0; n < 2; ++n) _Pragma("unroll") for (int k = 0; k < 2; ++k) dst[n][k] = *(const PG8_LAS bf16x8*)(lds + PG8_SB(b, h) + boff + n * 2048 + k * 1024); } while (0)
; #define PG8_MMA(ai, bj, At, Bt) do { __builtin_amdgcn_s_setprio(1); _Pragma("unroll") for (int m = 0; m < 4; ++m) _Pragma("unroll") for (int n = 0; n < 2; ++n) _Pragma("unroll") for (int k = 0; k < 2; ++k) \
;         acc[ai][bj][m][n] = __builtin_amdgcn_mfma_f32_16x16x32_bf16(Bt[n][k], At[m][k], acc[ai][bj][m][n], 0, 0, 0); __builtin_amdgcn_s_setprio(0); } while (0)
; #define PG8_WAIT_V(n) asm volatile("s_waitcnt vmcnt(" #n ")" ::: "memory")
; #define PG8_WAIT_L(n) asm volatile("s_waitcnt lgkmcnt(" #n ")" ::: "memory")
; #define PG8_BAR __builtin_amdgcn_s_barrier()
; #define PG8_SCHED __builtin_amdgcn_sched_barrier(0)
; template <class Epi, class Sched, bool ALIGN_EPI = false, bool SP2 = false>
; __device__ __forceinline__ void gemm_phase(PG8_LAS unsigned char* lds, const Gemm g, const Sched& S, const Epi& E) {
;     ...
;             PG8_WAIT_V(8); PG8_WAIT_L(0); PG8_BAR; PG8_MMA(1, 0, At, B0); PG8_MMA(1, 1, At, B1); PG8_BAR; PG8_SCHED;
;             PG8_LDB(B0, 1, 0); PG8_LDB(B1, 1, 1); PG8_SCHED; PG8_LDA(At, 1, 0); PG8_STAGE(PG8_SA(0, 1), a2 + hstep, voffA);
;             PG8_WAIT_V(8); PG8_WAIT_L(0); PG8_BAR; PG8_MMA(0, 0, At, B0); PG8_MMA(0, 1, At, B1); PG8_BAR; PG8_SCHED;
	s_setprio 1
	s_waitcnt lgkmcnt(0)
	v_mfma_f32_16x16x32_bf16 v[60:63], v[124:127], v[160:163], 0
	v_mfma_f32_16x16x32_bf16 v[56:59], v[136:139], v[160:163], 0
	v_mfma_f32_16x16x32_bf16 v[44:47], v[124:127], v[168:171], 0
	v_mfma_f32_16x16x32_bf16 v[40:43], v[136:139], v[168:171], 0
	v_mfma_f32_16x16x32_bf16 v[28:31], v[124:127], v[176:179], 0
	v_mfma_f32_16x16x32_bf16 v[24:27], v[136:139], v[176:179], 0
	v_mfma_f32_16x16x32_bf16 v[12:15], v[124:127], v[198:201], 0
	v_mfma_f32_16x16x32_bf16 v[8:11], v[136:139], v[198:201], 0
	v_mfma_f32_16x16x32_bf16 v[60:63], v[132:135], v[164:167], v[60:63]
	v_mfma_f32_16x16x32_bf16 v[56:59], v[140:143], v[164:167], v[56:59]
	v_mfma_f32_16x16x32_bf16 v[44:47], v[132:135], v[172:175], v[44:47]
	v_mfma_f32_16x16x32_bf16 v[40:43], v[140:143], v[172:175], v[40:43]
	v_mfma_f32_16x16x32_bf16 v[28:31], v[132:135], v[180:183], v[28:31]
	v_mfma_f32_16x16x32_bf16 v[24:27], v[140:143], v[180:183], v[24:27]
	v_mfma_f32_16x16x32_bf16 v[12:15], v[132:135], v[202:205], v[12:15]
	v_mfma_f32_16x16x32_bf16 v[8:11], v[140:143], v[202:205], v[8:11]
	s_setprio 0
	s_setprio 1
	v_mfma_f32_16x16x32_bf16 v[52:55], v[144:147], v[160:163], 0
	v_mfma_f32_16x16x32_bf16 v[48:51], v[152:155], v[160:163], 0
	v_mfma_f32_16x16x32_bf16 v[36:39], v[144:147], v[168:171], 0
	v_mfma_f32_16x16x32_bf16 v[32:35], v[152:155], v[168:171], 0
	v_mfma_f32_16x16x32_bf16 v[20:23], v[144:147], v[176:179], 0
	v_mfma_f32_16x16x32_bf16 v[16:19], v[152:155], v[176:179], 0
	v_mfma_f32_16x16x32_bf16 v[4:7], v[144:147], v[198:201], 0
	v_mfma_f32_16x16x32_bf16 v[0:3], v[152:155], v[198:201], 0
	v_mfma_f32_16x16x32_bf16 v[52:55], v[148:151], v[164:167], v[52:55]
	v_mfma_f32_16x16x32_bf16 v[48:51], v[156:159], v[164:167], v[48:51]
	v_mfma_f32_16x16x32_bf16 v[36:39], v[148:151], v[172:175], v[36:39]
	v_mfma_f32_16x16x32_bf16 v[32:35], v[156:159], v[172:175], v[32:35]
	v_mfma_f32_16x16x32_bf16 v[20:23], v[148:151], v[180:183], v[20:23]
	v_mfma_f32_16x16x32_bf16 v[16:19], v[156:159], v[180:183], v[16:19]
	v_mfma_f32_16x16x32_bf16 v[4:7], v[148:151], v[202:205], v[4:7]
	v_mfma_f32_16x16x32_bf16 v[0:3], v[156:159], v[202:205], v[0:3]
	s_setprio 0
	s_barrier
	s_add_i32 s62, 0, 0x18000
	s_add_i32 s63, 0, 0x1c000
	v_add_u32_e32 v140, s62, v232
	v_add_u32_e32 v156, s63, v232
	ds_read_b128 v[124:127], v140
	ds_read_b128 v[132:135], v140 offset:1024
	ds_read_b128 v[136:139], v140 offset:2048
	ds_read_b128 v[140:143], v140 offset:3072
	ds_read_b128 v[144:147], v156
	ds_read_b128 v[148:151], v156 offset:1024
	ds_read_b128 v[152:155], v156 offset:2048
	ds_read_b128 v[156:159], v156 offset:3072
	s_add_u32 s40, s40, 0x40000
	s_addc_u32 s41, s41, 0
	s_mov_b32 m0, s47
	v_lshl_add_u64 v[214:215], s[40:41], 0, v[184:185]
	ds_read_b128 v[160:163], v236 offset:32768
	ds_read_b128 v[164:167], v236 offset:33792
	ds_read_b128 v[168:171], v236 offset:34816
	ds_read_b128 v[172:175], v236 offset:35840
	ds_read_b128 v[176:179], v236 offset:36864
	ds_read_b128 v[180:183], v236 offset:37888
	ds_read_b128 v[198:201], v236 offset:38912
	ds_read_b128 v[202:205], v236 offset:39936
	global_load_lds_dwordx4 v[214:215], off
	v_lshl_add_u64 v[214:215], s[40:41], 0, v[188:189]
	s_mov_b32 m0, s48
	s_nop 0
	global_load_lds_dwordx4 v[214:215], off
	s_waitcnt vmcnt(8)
	s_waitcnt lgkmcnt(0)
	s_barrier
	s_setprio 1
	s_waitcnt lgkmcnt(0)
	v_mfma_f32_16x16x32_bf16 v[128:131], v[124:127], v[160:163], v[128:131]
	v_mfma_f32_16x16x32_bf16 v[120:123], v[136:139], v[160:163], v[120:123]
	v_mfma_f32_16x16x32_bf16 v[108:111], v[124:127], v[168:171], v[108:111]
	v_mfma_f32_16x16x32_bf16 v[104:107], v[136:139], v[168:171], v[104:107]
	v_mfma_f32_16x16x32_bf16 v[92:95], v[124:127], v[176:179], v[92:95]
	v_mfma_f32_16x16x32_bf16 v[88:91], v[136:139], v[176:179], v[88:91]
	v_mfma_f32_16x16x32_bf16 v[76:79], v[124:127], v[198:201], v[76:79]
	v_mfma_f32_16x16x32_bf16 v[72:75], v[136:139], v[198:201], v[72:75]
	v_mfma_f32_16x16x32_bf16 v[128:131], v[132:135], v[164:167], v[128:131]
	v_mfma_f32_16x16x32_bf16 v[120:123], v[140:143], v[164:167], v[120:123]
	v_mfma_f32_16x16x32_bf16 v[108:111], v[132:135], v[172:175], v[108:111]
	v_mfma_f32_16x16x32_bf16 v[104:107], v[140:143], v[172:175], v[104:107]
	v_mfma_f32_16x16x32_bf16 v[92:95], v[132:135], v[180:183], v[92:95]
	v_mfma_f32_16x16x32_bf16 v[88:91], v[140:143], v[180:183], v[88:91]
	v_mfma_f32_16x16x32_bf16 v[76:79], v[132:135], v[202:205], v[76:79]
	v_mfma_f32_16x16x32_bf16 v[72:75], v[140:143], v[202:205], v[72:75]
	s_setprio 0
	s_setprio 1
	v_mfma_f32_16x16x32_bf16 v[116:119], v[144:147], v[160:163], v[116:119]
	v_mfma_f32_16x16x32_bf16 v[112:115], v[152:155], v[160:163], v[112:115]
	v_mfma_f32_16x16x32_bf16 v[100:103], v[144:147], v[168:171], v[100:103]
	v_mfma_f32_16x16x32_bf16 v[96:99], v[152:155], v[168:171], v[96:99]
	v_mfma_f32_16x16x32_bf16 v[84:87], v[144:147], v[176:179], v[84:87]
	v_mfma_f32_16x16x32_bf16 v[80:83], v[152:155], v[176:179], v[80:83]
	v_mfma_f32_16x16x32_bf16 v[68:71], v[144:147], v[198:201], v[68:71]
	v_mfma_f32_16x16x32_bf16 v[64:67], v[152:155], v[198:201], v[64:67]
	v_mfma_f32_16x16x32_bf16 v[116:119], v[148:151], v[164:167], v[116:119]
	v_mfma_f32_16x16x32_bf16 v[112:115], v[156:159], v[164:167], v[112:115]
	v_mfma_f32_16x16x32_bf16 v[100:103], v[148:151], v[172:175], v[100:103]
	v_mfma_f32_16x16x32_bf16 v[96:99], v[156:159], v[172:175], v[96:99]
	v_mfma_f32_16x16x32_bf16 v[84:87], v[148:151], v[180:183], v[84:87]
	v_mfma_f32_16x16x32_bf16 v[80:83], v[156:159], v[180:183], v[80:83]
	v_mfma_f32_16x16x32_bf16 v[68:71], v[148:151], v[202:205], v[68:71]
	v_mfma_f32_16x16x32_bf16 v[64:67], v[156:159], v[202:205], v[64:67]
	s_setprio 0
	s_barrier
; #define PG8_STAGE(bufoff, gbase, voff) do { _Pragma("unroll") for (int _i = 0; _i < 2; ++_i) \
;         __builtin_amdgcn_global_load_lds((const unsigned*)((const char*)(gbase) + (voff)[_i]), (PG8_LAS unsigned*)(lds + (bufoff) + ldsw + _i * 8192), 16, 0, 0); } while (0)
; #define PG8_LDA(dst, b, h) do { _Pragma("unroll") for (int m = 0; m < 4; ++m) _Pragma("unroll") for (int k = 0; k < 2; ++k) dst[m][k] = *(const PG8_LAS bf16x8*)(lds + PG8_SA(b, h) + aoff + m * 2048 + k * 1024); } while (0)
; #define PG8_MMA(ai, bj, At, Bt) do { __builtin_amdgcn_s_setprio(1); _Pragma("unroll") for (int m = 0; m < 4; ++m) _Pragma("unroll") for (int n = 0; n < 2; ++n) _Pragma("unroll") for (int k = 0; k < 2; ++k) \
;         acc[ai][bj][m][n] = __builtin_amdgcn_mfma_f32_16x16x32_bf16(Bt[n][k], At[m][k], acc[ai][bj][m][n], 0, 0, 0); __builtin_amdgcn_s_setprio(0); } while (0)
; #define PG8_WAIT_V(n) asm volatile("s_waitcnt vmcnt(" #n ")" ::: "memory")
; #define PG8_WAIT_L(n) asm volatile("s_waitcnt lgkmcnt(" #n ")" ::: "memory")
; #define PG8_BAR __builtin_amdgcn_s_barrier()
; #define PG8_SCHED __builtin_amdgcn_sched_barrier(0)
; template <class Epi, class Sched, bool ALIGN_EPI = false, bool SP2 = false>
; __device__ __forceinline__ void gemm_phase(PG8_LAS unsigned char* lds, const Gemm g, const Sched& S, const Epi& E) {
;     ...
;             PG8_LDA(At, 1, 1); PG8_STAGE(PG8_SB(1, 0), b3, voffB); PG8_STAGE(PG8_SB(1, 1), b3 + hstep, voffB); PG8_STAGE(PG8_SA(1, 0), a3, voffA);
;             PG8_WAIT_V(8); PG8_WAIT_L(0); PG8_BAR; PG8_MMA(1, 0, At, B0); PG8_MMA(1, 1, At, B1); PG8_BAR; PG8_SCHED;
	s_add_i32 s40, s62, s44
	v_lshl_add_u64 v[206:207], v[206:207], 0, s[16:17]
	s_mov_b32 m0, s40
	ds_read_b128 v[160:163], v236 offset:49152
	ds_read_b128 v[164:167], v236 offset:50176
	ds_read_b128 v[168:171], v236 offset:51200
	ds_read_b128 v[172:175], v236 offset:52224
	ds_read_b128 v[176:179], v236 offset:53248
	ds_read_b128 v[180:183], v236 offset:54272
	ds_read_b128 v[198:201], v236 offset:55296
	ds_read_b128 v[202:205], v236 offset:56320
	global_load_lds_dwordx4 v[206:207], off
	s_add_i32 m0, s40, 0x2000
	s_add_u32 s38, s38, 0x40080
	v_lshl_add_u64 v[206:207], v[208:209], 0, s[16:17]
	s_addc_u32 s39, s39, 0
	s_add_i32 s40, s63, s44
	global_load_lds_dwordx4 v[206:207], off
	v_lshl_add_u64 v[206:207], s[38:39], 0, v[186:187]
	s_mov_b32 m0, s40
	s_nop 0
	global_load_lds_dwordx4 v[206:207], off
	v_lshl_add_u64 v[206:207], s[38:39], 0, v[190:191]
	s_add_i32 m0, s40, 0x2000
	s_nop 0
	global_load_lds_dwordx4 v[206:207], off
	v_lshl_add_u64 v[206:207], v[210:211], 0, s[16:17]
	s_mov_b32 m0, s50
	s_nop 0
	global_load_lds_dwordx4 v[206:207], off
	v_lshl_add_u64 v[206:207], v[212:213], 0, s[16:17]
	s_mov_b32 m0, s51
	s_nop 0
	global_load_lds_dwordx4 v[206:207], off
	s_waitcnt vmcnt(8)
	s_waitcnt lgkmcnt(0)
	s_barrier
	s_setprio 1
	s_waitcnt lgkmcnt(0)
	v_mfma_f32_16x16x32_bf16 v[60:63], v[124:127], v[160:163], v[60:63]
	v_mfma_f32_16x16x32_bf16 v[56:59], v[136:139], v[160:163], v[56:59]
	v_mfma_f32_16x16x32_bf16 v[44:47], v[124:127], v[168:171], v[44:47]
	v_mfma_f32_16x16x32_bf16 v[40:43], v[136:139], v[168:171], v[40:43]
	v_mfma_f32_16x16x32_bf16 v[28:31], v[124:127], v[176:179], v[28:31]
	v_mfma_f32_16x16x32_bf16 v[24:27], v[136:139], v[176:179], v[24:27]
	v_mfma_f32_16x16x32_bf16 v[12:15], v[124:127], v[198:201], v[12:15]
	v_mfma_f32_16x16x32_bf16 v[8:11], v[136:139], v[198:201], v[8:11]
	v_mfma_f32_16x16x32_bf16 v[60:63], v[132:135], v[164:167], v[60:63]
	v_mfma_f32_16x16x32_bf16 v[56:59], v[140:143], v[164:167], v[56:59]
	v_mfma_f32_16x16x32_bf16 v[44:47], v[132:135], v[172:175], v[44:47]
	v_mfma_f32_16x16x32_bf16 v[40:43], v[140:143], v[172:175], v[40:43]
	v_mfma_f32_16x16x32_bf16 v[28:31], v[132:135], v[180:183], v[28:31]
	v_mfma_f32_16x16x32_bf16 v[24:27], v[140:143], v[180:183], v[24:27]
	v_mfma_f32_16x16x32_bf16 v[12:15], v[132:135], v[202:205], v[12:15]
	v_mfma_f32_16x16x32_bf16 v[8:11], v[140:143], v[202:205], v[8:11]
	s_setprio 0
	s_setprio 1
	v_mfma_f32_16x16x32_bf16 v[52:55], v[144:147], v[160:163], v[52:55]
	v_mfma_f32_16x16x32_bf16 v[48:51], v[152:155], v[160:163], v[48:51]
	v_mfma_f32_16x16x32_bf16 v[36:39], v[144:147], v[168:171], v[36:39]
	v_mfma_f32_16x16x32_bf16 v[32:35], v[152:155], v[168:171], v[32:35]
	v_mfma_f32_16x16x32_bf16 v[20:23], v[144:147], v[176:179], v[20:23]
	v_mfma_f32_16x16x32_bf16 v[16:19], v[152:155], v[176:179], v[16:19]
	v_mfma_f32_16x16x32_bf16 v[4:7], v[144:147], v[198:201], v[4:7]
	v_mfma_f32_16x16x32_bf16 v[0:3], v[152:155], v[198:201], v[0:3]
	v_mfma_f32_16x16x32_bf16 v[52:55], v[148:151], v[164:167], v[52:55]
	v_mfma_f32_16x16x32_bf16 v[48:51], v[156:159], v[164:167], v[48:51]
	v_mfma_f32_16x16x32_bf16 v[36:39], v[148:151], v[172:175], v[36:39]
	v_mfma_f32_16x16x32_bf16 v[32:35], v[156:159], v[172:175], v[32:35]
	v_mfma_f32_16x16x32_bf16 v[20:23], v[148:151], v[180:183], v[20:23]
	v_mfma_f32_16x16x32_bf16 v[16:19], v[156:159], v[180:183], v[16:19]
	v_mfma_f32_16x16x32_bf16 v[4:7], v[148:151], v[202:205], v[4:7]
	v_mfma_f32_16x16x32_bf16 v[0:3], v[156:159], v[202:205], v[0:3]
	s_setprio 0
	s_barrier
	s_add_i32 s61, s61, 2
	s_add_u32 s36, s36, 0x100
	s_addc_u32 s37, s37, 0
	s_add_u32 s59, s59, 0x100
	s_addc_u32 s60, s60, 0
	s_cmp_gt_u32 s61, 13

; #define PG8_STAGE(bufoff, gbase, voff) do { _Pragma("unroll") for (int _i = 0; _i < 2; ++_i) \
;         __builtin_amdgcn_global_load_lds((const unsigned*)((const char*)(gbase) + (voff)[_i]), (PG8_LAS unsigned*)(lds + (bufoff) + ldsw + _i * 8192), 16, 0, 0); } while (0)
; #define PG8_LDA(dst, b, h) do { _Pragma("unroll") for (int m = 0; m < 4; ++m) _Pragma("unroll") for (int k = 0; k < 2; ++k) dst[m][k] = *(const PG8_LAS bf16x8*)(lds + PG8_SA(b, h) + aoff + m * 2048 + k * 1024); } while (0)
; #define PG8_LDB(dst, b, h) do { _Pragma("unroll") for (int n = 0; n < 2; ++n) _Pragma("unroll") for (int k = 0; k < 2; ++k) dst[n][k] = *(const PG8_LAS bf16x8*)(lds + PG8_SB(b, h) + boff + n * 2048 + k * 1024); } while (0)
; #define PG8_WAIT_V(n) asm volatile("s_waitcnt vmcnt(" #n ")" ::: "memory")
; #define PG8_WAIT_L(n) asm volatile("s_waitcnt lgkmcnt(" #n ")" ::: "memory")
; #define PG8_BAR __builtin_amdgcn_s_barrier()
; #define PG8_SCHED __builtin_amdgcn_sched_barrier(0)
; template <class Epi, class Sched, bool ALIGN_EPI = false, bool SP2 = false>
; __device__ __forceinline__ void gemm_phase(PG8_LAS unsigned char* lds, const Gemm g, const Sched& S, const Epi& E) {
;     ...
;         const char* nA = has_next ? (const char*)g.A + (size_t)nxt.pm * tstep : cA; const char* nB = has_next ? (const char*)g.Bt + (size_t)nxt.pn * tstep : cB;
;         for (int t = 0; t < nt; t += 2) {
;             const bool last = (t == nt - 2);
;             const char* a1 = cA + (size_t)(t + 1) * kstep;
;             const char* a2 = last ? nA : cA + (size_t)(t + 2) * kstep; const char* b2 = last ? nB : cB + (size_t)(t + 2) * kstep;
;             const char* a3 = a2 + kstep; const char* b3 = b2 + kstep;
;             if (last && has_next) S.a_ready(nxt);
;             if constexpr (SP2) {
;             PG8_LDB(B0, 0, 0); PG8_LDB(B1, 0, 1); PG8_SCHED; PG8_LDA(At, 0, 0); PG8_STAGE(PG8_SA(1, 1), a1 + hstep, voffA);
;             PG8_WAIT_V(8); PG8_WAIT_L(0); PG8_BAR; PG8_MMA(0, 0, At, B0); PG8_MMA(0, 1, At, B1); PG8_BAR; PG8_SCHED;
;             PG8_LDA(At, 0, 1); PG8_STAGE(PG8_SB(0, 0), b2, voffB); PG8_STAGE(PG8_SB(0, 1), b2 + hstep, voffB); PG8_STAGE(PG8_SA(0, 0), a2, voffA);
;             PG8_WAIT_V(8); PG8_WAIT_L(0); PG8_BAR; PG8_MMA(1, 0, At, B0); PG8_MMA(1, 1, At, B1); PG8_BAR; PG8_SCHED;
.LBB0_976:
	s_ashr_i32 s21, s20, 31
	s_lshl_b64 s[24:25], s[20:21], 19
	s_add_u32 s24, s70, s24
	s_addc_u32 s25, s71, s25
	s_and_b64 s[26:27], s[22:23], exec
	s_cselect_b32 s21, s25, s39
	s_cselect_b32 s54, s24, s38
	s_ashr_i32 s19, s18, 31
	s_lshl_b64 s[26:27], s[18:19], 19
	s_add_u32 s26, s41, s26
	s_addc_u32 s27, s42, s27
	s_and_b64 s[34:35], s[22:23], exec
	s_cselect_b32 s19, s27, s37
	s_cselect_b32 s55, s26, s36
	s_add_u32 s34, s38, 0x40080
	s_addc_u32 s35, s39, 0
	s_add_u32 s56, s36, 0x100
	s_addc_u32 s57, s37, 0
	s_mov_b32 s58, -2
	ds_read_b128 v[144:147], v161
	ds_read_b128 v[170:173], v161 offset:1024
	ds_read_b128 v[178:181], v161 offset:2048
	ds_read_b128 v[182:185], v161 offset:3072
	ds_read_b128 v[186:189], v165
	ds_read_b128 v[190:193], v165 offset:1024
	ds_read_b128 v[194:197], v165 offset:2048
	ds_read_b128 v[198:201], v165 offset:3072
	s_add_u32 s36, s34, 0xfffc0080
	s_addc_u32 s37, s35, -1
	s_cmp_eq_u32 s58, 12
	s_cselect_b32 s39, s21, s37
	s_cselect_b32 s38, s54, s36
	s_cselect_b32 s37, s19, s57
	s_cselect_b32 s36, s55, s56
	v_lshl_add_u64 v[150:151], s[34:35], 0, v[138:139]
	s_add_i32 m0, s29, 0xc000
	ds_read_b128 v[202:205], v169
	ds_read_b128 v[206:209], v169 offset:1024
	ds_read_b128 v[210:213], v169 offset:2048
	ds_read_b128 v[214:217], v169 offset:3072
	ds_read_b128 v[218:221], v169 offset:4096
	ds_read_b128 v[222:225], v169 offset:5120
	ds_read_b128 v[226:229], v169 offset:6144
	ds_read_b128 v[232:235], v169 offset:7168
	global_load_lds_dwordx4 v[150:151], off
	v_lshl_add_u64 v[150:151], s[34:35], 0, v[140:141]
	s_add_i32 m0, s29, 0xe000
	s_nop 0
	global_load_lds_dwordx4 v[150:151], off
	s_waitcnt vmcnt(8)
	s_waitcnt lgkmcnt(0)
	s_barrier
	s_setprio 1
	s_waitcnt lgkmcnt(0)
	v_mfma_f32_16x16x32_bf16 v[124:127], v[144:147], v[202:205], 0
	v_mfma_f32_16x16x32_bf16 v[116:119], v[178:181], v[202:205], 0
	v_mfma_f32_16x16x32_bf16 v[108:111], v[144:147], v[210:213], 0
	v_mfma_f32_16x16x32_bf16 v[100:103], v[178:181], v[210:213], 0
	v_mfma_f32_16x16x32_bf16 v[92:95], v[144:147], v[218:221], 0
	v_mfma_f32_16x16x32_bf16 v[84:87], v[178:181], v[218:221], 0
	v_mfma_f32_16x16x32_bf16 v[76:79], v[144:147], v[226:229], 0
	v_mfma_f32_16x16x32_bf16 v[68:71], v[178:181], v[226:229], 0
	v_mfma_f32_16x16x32_bf16 v[124:127], v[170:173], v[206:209], v[124:127]
	v_mfma_f32_16x16x32_bf16 v[116:119], v[182:185], v[206:209], v[116:119]
	v_mfma_f32_16x16x32_bf16 v[108:111], v[170:173], v[214:217], v[108:111]
	v_mfma_f32_16x16x32_bf16 v[100:103], v[182:185], v[214:217], v[100:103]
	v_mfma_f32_16x16x32_bf16 v[92:95], v[170:173], v[222:225], v[92:95]
	v_mfma_f32_16x16x32_bf16 v[84:87], v[182:185], v[222:225], v[84:87]
	v_mfma_f32_16x16x32_bf16 v[76:79], v[170:173], v[232:235], v[76:79]
	v_mfma_f32_16x16x32_bf16 v[68:71], v[182:185], v[232:235], v[68:71]
	s_setprio 0
	s_setprio 1
	v_mfma_f32_16x16x32_bf16 v[120:123], v[186:189], v[202:205], 0
	v_mfma_f32_16x16x32_bf16 v[112:115], v[194:197], v[202:205], 0
	v_mfma_f32_16x16x32_bf16 v[104:107], v[186:189], v[210:213], 0
	v_mfma_f32_16x16x32_bf16 v[96:99], v[194:197], v[210:213], 0
	v_mfma_f32_16x16x32_bf16 v[88:91], v[186:189], v[218:221], 0
	v_mfma_f32_16x16x32_bf16 v[80:83], v[194:197], v[218:221], 0
	v_mfma_f32_16x16x32_bf16 v[72:75], v[186:189], v[226:229], 0
	v_mfma_f32_16x16x32_bf16 v[64:67], v[194:197], v[226:229], 0
	v_mfma_f32_16x16x32_bf16 v[120:123], v[190:193], v[206:209], v[120:123]
	v_mfma_f32_16x16x32_bf16 v[112:115], v[198:201], v[206:209], v[112:115]
	v_mfma_f32_16x16x32_bf16 v[104:107], v[190:193], v[214:217], v[104:107]
	v_mfma_f32_16x16x32_bf16 v[96:99], v[198:201], v[214:217], v[96:99]
	v_mfma_f32_16x16x32_bf16 v[88:91], v[190:193], v[222:225], v[88:91]
	v_mfma_f32_16x16x32_bf16 v[80:83], v[198:201], v[222:225], v[80:83]
	v_mfma_f32_16x16x32_bf16 v[72:75], v[190:193], v[232:235], v[72:75]
	v_mfma_f32_16x16x32_bf16 v[64:67], v[198:201], v[232:235], v[64:67]
	s_setprio 0
	s_barrier
	s_add_i32 s59, s50, s43
	v_lshl_add_u64 v[150:151], s[36:37], 0, v[130:131]
	s_mov_b32 m0, s59
	ds_read_b128 v[202:205], v169 offset:16384
	ds_read_b128 v[206:209], v169 offset:17408
	ds_read_b128 v[210:213], v169 offset:18432
	ds_read_b128 v[214:217], v169 offset:19456
	ds_read_b128 v[218:221], v169 offset:20480
	ds_read_b128 v[222:225], v169 offset:21504
	ds_read_b128 v[226:229], v169 offset:22528
	ds_read_b128 v[232:235], v169 offset:23552
	global_load_lds_dwordx4 v[150:151], off
	s_add_i32 m0, s59, 0x2000
	s_add_u32 s60, s36, 0x40000
	v_lshl_add_u64 v[154:155], s[36:37], 0, v[134:135]
	s_addc_u32 s61, s37, 0
	s_add_i32 s59, s51, s43
	global_load_lds_dwordx4 v[154:155], off
	v_lshl_add_u64 v[158:159], s[60:61], 0, v[130:131]
	s_mov_b32 m0, s59
	v_lshl_add_u64 v[162:163], s[38:39], 0, v[132:133]
	global_load_lds_dwordx4 v[158:159], off
	v_lshl_add_u64 v[158:159], s[60:61], 0, v[134:135]
	s_add_i32 m0, s59, 0x2000
	s_nop 0
	global_load_lds_dwordx4 v[158:159], off
	v_lshl_add_u64 v[158:159], s[38:39], 0, v[128:129]
	s_mov_b32 m0, s29
	s_nop 0
	global_load_lds_dwordx4 v[158:159], off
	s_mov_b32 m0, s31
	s_nop 0
	global_load_lds_dwordx4 v[162:163], off
	s_cmp_lg_i32 s58, -2
	s_cbranch_scc1 .Lrsb_a_pl
	v_lshrrev_b32_e32 v250, 6, v230
	v_lshlrev_b32_e32 v250, 11, v250
	v_and_b32_e32 v251, 63, v230
	v_lshl_or_b32 v250, v251, 4, v250
	v_lshl_add_u32 v250, s30, 14, v250
	v_readfirstlane_b32 s98, v230
	s_lshr_b32 s98, s98, 6
	s_lshl_b32 s98, s98, 11
	s_add_i32 m0, s98, 0x20000
	s_add_u32 s100, s70, 0x3f000000
	s_addc_u32 s101, s71, 0
	global_load_lds_dwordx4 v250, s[100:101]
	global_load_lds_dwordx4 v250, s[100:101] offset:1024
	s_waitcnt vmcnt(10)
	s_branch .Lrsb_b_pl

; #define PG8_STAGE(bufoff, gbase, voff) do { _Pragma("unroll") for (int _i = 0; _i < 2; ++_i) \
;         __builtin_amdgcn_global_load_lds((const unsigned*)((const char*)(gbase) + (voff)[_i]), (PG8_LAS unsigned*)(lds + (bufoff) + ldsw + _i * 8192), 16, 0, 0); } while (0)
; #define PG8_LDA(dst, b, h) do { _Pragma("unroll") for (int m = 0; m < 4; ++m) _Pragma("unroll") for (int k = 0; k < 2; ++k) dst[m][k] = *(const PG8_LAS bf16x8*)(lds + PG8_SA(b, h) + aoff + m * 2048 + k * 1024); } while (0)
; #define PG8_LDB(dst, b, h) do { _Pragma("unroll") for (int n = 0; n < 2; ++n) _Pragma("unroll") for (int k = 0; k < 2; ++k) dst[n][k] = *(const PG8_LAS bf16x8*)(lds + PG8_SB(b, h) + boff + n * 2048 + k * 1024); } while (0)
; #define PG8_MMA(ai, bj, At, Bt) do { __builtin_amdgcn_s_setprio(1); _Pragma("unroll") for (int m = 0; m < 4; ++m) _Pragma("unroll") for (int n = 0; n < 2; ++n) _Pragma("unroll") for (int k = 0; k < 2; ++k) \
;         acc[ai][bj][m][n] = __builtin_amdgcn_mfma_f32_16x16x32_bf16(Bt[n][k], At[m][k], acc[ai][bj][m][n], 0, 0, 0); __builtin_amdgcn_s_setprio(0); } while (0)
; #define PG8_WAIT_V(n) asm volatile("s_waitcnt vmcnt(" #n ")" ::: "memory")
; #define PG8_WAIT_L(n) asm volatile("s_waitcnt lgkmcnt(" #n ")" ::: "memory")
; #define PG8_BAR __builtin_amdgcn_s_barrier()
; #define PG8_SCHED __builtin_amdgcn_sched_barrier(0)
; template <class Epi, class Sched, bool ALIGN_EPI = false, bool SP2 = false>
; __device__ __forceinline__ void gemm_phase(PG8_LAS unsigned char* lds, const Gemm g, const Sched& S, const Epi& E) {
;     ...
;             PG8_WAIT_V(8); PG8_WAIT_L(0); PG8_BAR; PG8_MMA(1, 0, At, B0); PG8_MMA(1, 1, At, B1); PG8_BAR; PG8_SCHED;
;             PG8_LDB(B0, 1, 0); PG8_LDB(B1, 1, 1); PG8_SCHED; PG8_LDA(At, 1, 0); PG8_STAGE(PG8_SA(0, 1), a2 + hstep, voffA);
;             PG8_WAIT_V(8); PG8_WAIT_L(0); PG8_BAR; PG8_MMA(0, 0, At, B0); PG8_MMA(0, 1, At, B1); PG8_BAR; PG8_SCHED;
.Lrsb_b_pl:
	s_waitcnt lgkmcnt(0)
	s_barrier
	s_setprio 1
	s_waitcnt lgkmcnt(0)
	v_mfma_f32_16x16x32_bf16 v[60:63], v[144:147], v[202:205], 0
	v_mfma_f32_16x16x32_bf16 v[52:55], v[178:181], v[202:205], 0
	v_mfma_f32_16x16x32_bf16 v[44:47], v[144:147], v[210:213], 0
	v_mfma_f32_16x16x32_bf16 v[36:39], v[178:181], v[210:213], 0
	v_mfma_f32_16x16x32_bf16 v[28:31], v[144:147], v[218:221], 0
	v_mfma_f32_16x16x32_bf16 v[20:23], v[178:181], v[218:221], 0
	v_mfma_f32_16x16x32_bf16 v[12:15], v[144:147], v[226:229], 0
	v_mfma_f32_16x16x32_bf16 v[4:7], v[178:181], v[226:229], 0
	v_mfma_f32_16x16x32_bf16 v[60:63], v[170:173], v[206:209], v[60:63]
	v_mfma_f32_16x16x32_bf16 v[52:55], v[182:185], v[206:209], v[52:55]
	v_mfma_f32_16x16x32_bf16 v[44:47], v[170:173], v[214:217], v[44:47]
	v_mfma_f32_16x16x32_bf16 v[36:39], v[182:185], v[214:217], v[36:39]
	v_mfma_f32_16x16x32_bf16 v[28:31], v[170:173], v[222:225], v[28:31]
	v_mfma_f32_16x16x32_bf16 v[20:23], v[182:185], v[222:225], v[20:23]
	v_mfma_f32_16x16x32_bf16 v[12:15], v[170:173], v[232:235], v[12:15]
	v_mfma_f32_16x16x32_bf16 v[4:7], v[182:185], v[232:235], v[4:7]
	s_setprio 0
	s_setprio 1
	v_mfma_f32_16x16x32_bf16 v[56:59], v[186:189], v[202:205], 0
	v_mfma_f32_16x16x32_bf16 v[48:51], v[194:197], v[202:205], 0
	v_mfma_f32_16x16x32_bf16 v[40:43], v[186:189], v[210:213], 0
	v_mfma_f32_16x16x32_bf16 v[32:35], v[194:197], v[210:213], 0
	v_mfma_f32_16x16x32_bf16 v[24:27], v[186:189], v[218:221], 0
	v_mfma_f32_16x16x32_bf16 v[16:19], v[194:197], v[218:221], 0
	v_mfma_f32_16x16x32_bf16 v[8:11], v[186:189], v[226:229], 0
	v_mfma_f32_16x16x32_bf16 v[0:3], v[194:197], v[226:229], 0
	v_mfma_f32_16x16x32_bf16 v[56:59], v[190:193], v[206:209], v[56:59]
	v_mfma_f32_16x16x32_bf16 v[48:51], v[198:201], v[206:209], v[48:51]
	v_mfma_f32_16x16x32_bf16 v[40:43], v[190:193], v[214:217], v[40:43]
	v_mfma_f32_16x16x32_bf16 v[32:35], v[198:201], v[214:217], v[32:35]
	v_mfma_f32_16x16x32_bf16 v[24:27], v[190:193], v[222:225], v[24:27]
	v_mfma_f32_16x16x32_bf16 v[16:19], v[198:201], v[222:225], v[16:19]
	v_mfma_f32_16x16x32_bf16 v[8:11], v[190:193], v[232:235], v[8:11]
	v_mfma_f32_16x16x32_bf16 v[0:3], v[198:201], v[232:235], v[0:3]
	s_setprio 0
	s_barrier
	s_add_i32 s59, 0, 0x18000
	v_add_u32_e32 v148, s59, v153
	s_add_i32 s60, 0, 0x1c000
	ds_read_b128 v[144:147], v148
	ds_read_b128 v[170:173], v148 offset:1024
	ds_read_b128 v[178:181], v148 offset:2048
	ds_read_b128 v[182:185], v148 offset:3072
	v_add_u32_e32 v148, s60, v153
	ds_read_b128 v[186:189], v148
	ds_read_b128 v[190:193], v148 offset:1024
	ds_read_b128 v[194:197], v148 offset:2048
	ds_read_b128 v[198:201], v148 offset:3072
	s_add_u32 s38, s38, 0x40000
	s_addc_u32 s39, s39, 0
	s_mov_b32 m0, s45
	v_lshl_add_u64 v[166:167], s[38:39], 0, v[128:129]
	ds_read_b128 v[202:205], v169 offset:32768
	ds_read_b128 v[206:209], v169 offset:33792
	ds_read_b128 v[210:213], v169 offset:34816
	ds_read_b128 v[214:217], v169 offset:35840
	ds_read_b128 v[218:221], v169 offset:36864
	ds_read_b128 v[222:225], v169 offset:37888
	ds_read_b128 v[226:229], v169 offset:38912
	ds_read_b128 v[232:235], v169 offset:39936
	global_load_lds_dwordx4 v[166:167], off
	v_lshl_add_u64 v[166:167], s[38:39], 0, v[132:133]
	s_mov_b32 m0, s46
	s_nop 0
	global_load_lds_dwordx4 v[166:167], off
	s_cmp_lg_i32 s58, -2
	s_cbranch_scc1 .Lrsb_c_pl
	s_waitcnt vmcnt(10)
	s_branch .Lrsb_d_pl

; #define PG8_STAGE(bufoff, gbase, voff) do { _Pragma("unroll") for (int _i = 0; _i < 2; ++_i) \
;         __builtin_amdgcn_global_load_lds((const unsigned*)((const char*)(gbase) + (voff)[_i]), (PG8_LAS unsigned*)(lds + (bufoff) + ldsw + _i * 8192), 16, 0, 0); } while (0)
; #define PG8_LDA(dst, b, h) do { _Pragma("unroll") for (int m = 0; m < 4; ++m) _Pragma("unroll") for (int k = 0; k < 2; ++k) dst[m][k] = *(const PG8_LAS bf16x8*)(lds + PG8_SA(b, h) + aoff + m * 2048 + k * 1024); } while (0)
; #define PG8_MMA(ai, bj, At, Bt) do { __builtin_amdgcn_s_setprio(1); _Pragma("unroll") for (int m = 0; m < 4; ++m) _Pragma("unroll") for (int n = 0; n < 2; ++n) _Pragma("unroll") for (int k = 0; k < 2; ++k) \
;         acc[ai][bj][m][n] = __builtin_amdgcn_mfma_f32_16x16x32_bf16(Bt[n][k], At[m][k], acc[ai][bj][m][n], 0, 0, 0); __builtin_amdgcn_s_setprio(0); } while (0)
; #define PG8_WAIT_V(n) asm volatile("s_waitcnt vmcnt(" #n ")" ::: "memory")
; #define PG8_WAIT_L(n) asm volatile("s_waitcnt lgkmcnt(" #n ")" ::: "memory")
; #define PG8_BAR __builtin_amdgcn_s_barrier()
; #define PG8_SCHED __builtin_amdgcn_sched_barrier(0)
; template <class Epi, class Sched, bool ALIGN_EPI = false, bool SP2 = false>
; __device__ __forceinline__ void gemm_phase(PG8_LAS unsigned char* lds, const Gemm g, const Sched& S, const Epi& E) {
;     ...
;             PG8_WAIT_V(8); PG8_WAIT_L(0); PG8_BAR; PG8_MMA(0, 0, At, B0); PG8_MMA(0, 1, At, B1); PG8_BAR; PG8_SCHED;
;             PG8_LDA(At, 1, 1); PG8_STAGE(PG8_SB(1, 0), b3, voffB); PG8_STAGE(PG8_SB(1, 1), b3 + hstep, voffB); PG8_STAGE(PG8_SA(1, 0), a3, voffA);
;             PG8_WAIT_V(8); PG8_WAIT_L(0); PG8_BAR; PG8_MMA(1, 0, At, B0); PG8_MMA(1, 1, At, B1); PG8_BAR; PG8_SCHED;
.Lrsb_d_pl:
	s_waitcnt lgkmcnt(0)
	s_barrier
	s_setprio 1
	s_waitcnt lgkmcnt(0)
	v_mfma_f32_16x16x32_bf16 v[124:127], v[144:147], v[202:205], v[124:127]
	v_mfma_f32_16x16x32_bf16 v[116:119], v[178:181], v[202:205], v[116:119]
	v_mfma_f32_16x16x32_bf16 v[108:111], v[144:147], v[210:213], v[108:111]
	v_mfma_f32_16x16x32_bf16 v[100:103], v[178:181], v[210:213], v[100:103]
	v_mfma_f32_16x16x32_bf16 v[92:95], v[144:147], v[218:221], v[92:95]
	v_mfma_f32_16x16x32_bf16 v[84:87], v[178:181], v[218:221], v[84:87]
	v_mfma_f32_16x16x32_bf16 v[76:79], v[144:147], v[226:229], v[76:79]
	v_mfma_f32_16x16x32_bf16 v[68:71], v[178:181], v[226:229], v[68:71]
	v_mfma_f32_16x16x32_bf16 v[124:127], v[170:173], v[206:209], v[124:127]
	v_mfma_f32_16x16x32_bf16 v[116:119], v[182:185], v[206:209], v[116:119]
	v_mfma_f32_16x16x32_bf16 v[108:111], v[170:173], v[214:217], v[108:111]
	v_mfma_f32_16x16x32_bf16 v[100:103], v[182:185], v[214:217], v[100:103]
	v_mfma_f32_16x16x32_bf16 v[92:95], v[170:173], v[222:225], v[92:95]
	v_mfma_f32_16x16x32_bf16 v[84:87], v[182:185], v[222:225], v[84:87]
	v_mfma_f32_16x16x32_bf16 v[76:79], v[170:173], v[232:235], v[76:79]
	v_mfma_f32_16x16x32_bf16 v[68:71], v[182:185], v[232:235], v[68:71]
	s_setprio 0
	s_setprio 1
	v_mfma_f32_16x16x32_bf16 v[120:123], v[186:189], v[202:205], v[120:123]
	v_mfma_f32_16x16x32_bf16 v[112:115], v[194:197], v[202:205], v[112:115]
	v_mfma_f32_16x16x32_bf16 v[104:107], v[186:189], v[210:213], v[104:107]
	v_mfma_f32_16x16x32_bf16 v[96:99], v[194:197], v[210:213], v[96:99]
	v_mfma_f32_16x16x32_bf16 v[88:91], v[186:189], v[218:221], v[88:91]
	v_mfma_f32_16x16x32_bf16 v[80:83], v[194:197], v[218:221], v[80:83]
	v_mfma_f32_16x16x32_bf16 v[72:75], v[186:189], v[226:229], v[72:75]
	v_mfma_f32_16x16x32_bf16 v[64:67], v[194:197], v[226:229], v[64:67]
	v_mfma_f32_16x16x32_bf16 v[120:123], v[190:193], v[206:209], v[120:123]
	v_mfma_f32_16x16x32_bf16 v[112:115], v[198:201], v[206:209], v[112:115]
	v_mfma_f32_16x16x32_bf16 v[104:107], v[190:193], v[214:217], v[104:107]
	v_mfma_f32_16x16x32_bf16 v[96:99], v[198:201], v[214:217], v[96:99]
	v_mfma_f32_16x16x32_bf16 v[88:91], v[190:193], v[222:225], v[88:91]
	v_mfma_f32_16x16x32_bf16 v[80:83], v[198:201], v[222:225], v[80:83]
	v_mfma_f32_16x16x32_bf16 v[72:75], v[190:193], v[232:235], v[72:75]
	v_mfma_f32_16x16x32_bf16 v[64:67], v[198:201], v[232:235], v[64:67]
	s_setprio 0
	s_barrier
	s_add_i32 s38, s59, s43
	v_lshl_add_u64 v[150:151], v[150:151], 0, s[12:13]
	s_mov_b32 m0, s38
	ds_read_b128 v[202:205], v169 offset:49152
	ds_read_b128 v[206:209], v169 offset:50176
	ds_read_b128 v[210:213], v169 offset:51200
	ds_read_b128 v[214:217], v169 offset:52224
	ds_read_b128 v[218:221], v169 offset:53248
	ds_read_b128 v[222:225], v169 offset:54272
	ds_read_b128 v[226:229], v169 offset:55296
	ds_read_b128 v[232:235], v169 offset:56320
	global_load_lds_dwordx4 v[150:151], off
	s_add_i32 m0, s38, 0x2000
	s_add_u32 s36, s36, 0x40080
	v_lshl_add_u64 v[150:151], v[154:155], 0, s[12:13]
	s_addc_u32 s37, s37, 0
	s_add_i32 s38, s60, s43
	global_load_lds_dwordx4 v[150:151], off
	v_lshl_add_u64 v[150:151], s[36:37], 0, v[130:131]
	s_mov_b32 m0, s38
	s_nop 0
	global_load_lds_dwordx4 v[150:151], off
	v_lshl_add_u64 v[150:151], s[36:37], 0, v[134:135]
	s_add_i32 m0, s38, 0x2000
	s_nop 0
	global_load_lds_dwordx4 v[150:151], off
	v_lshl_add_u64 v[150:151], v[158:159], 0, s[12:13]
	s_mov_b32 m0, s47
	s_nop 0
	global_load_lds_dwordx4 v[150:151], off
	v_lshl_add_u64 v[150:151], v[162:163], 0, s[12:13]
	s_mov_b32 m0, s48
	s_nop 0
	global_load_lds_dwordx4 v[150:151], off
	s_waitcnt vmcnt(8)
	s_waitcnt lgkmcnt(0)
	s_barrier
	s_setprio 1
	s_waitcnt lgkmcnt(0)
	v_mfma_f32_16x16x32_bf16 v[60:63], v[144:147], v[202:205], v[60:63]
	v_mfma_f32_16x16x32_bf16 v[52:55], v[178:181], v[202:205], v[52:55]
	v_mfma_f32_16x16x32_bf16 v[44:47], v[144:147], v[210:213], v[44:47]
	v_mfma_f32_16x16x32_bf16 v[36:39], v[178:181], v[210:213], v[36:39]
	v_mfma_f32_16x16x32_bf16 v[28:31], v[144:147], v[218:221], v[28:31]
	v_mfma_f32_16x16x32_bf16 v[20:23], v[178:181], v[218:221], v[20:23]
	v_mfma_f32_16x16x32_bf16 v[12:15], v[144:147], v[226:229], v[12:15]
	v_mfma_f32_16x16x32_bf16 v[4:7], v[178:181], v[226:229], v[4:7]
	v_mfma_f32_16x16x32_bf16 v[60:63], v[170:173], v[206:209], v[60:63]
	v_mfma_f32_16x16x32_bf16 v[52:55], v[182:185], v[206:209], v[52:55]
	v_mfma_f32_16x16x32_bf16 v[44:47], v[170:173], v[214:217], v[44:47]
	v_mfma_f32_16x16x32_bf16 v[36:39], v[182:185], v[214:217], v[36:39]
	v_mfma_f32_16x16x32_bf16 v[28:31], v[170:173], v[222:225], v[28:31]
	v_mfma_f32_16x16x32_bf16 v[20:23], v[182:185], v[222:225], v[20:23]
	v_mfma_f32_16x16x32_bf16 v[12:15], v[170:173], v[232:235], v[12:15]
	v_mfma_f32_16x16x32_bf16 v[4:7], v[182:185], v[232:235], v[4:7]
	s_setprio 0
	s_setprio 1
	v_mfma_f32_16x16x32_bf16 v[56:59], v[186:189], v[202:205], v[56:59]
	v_mfma_f32_16x16x32_bf16 v[48:51], v[194:197], v[202:205], v[48:51]
	v_mfma_f32_16x16x32_bf16 v[40:43], v[186:189], v[210:213], v[40:43]
	v_mfma_f32_16x16x32_bf16 v[32:35], v[194:197], v[210:213], v[32:35]
	v_mfma_f32_16x16x32_bf16 v[24:27], v[186:189], v[218:221], v[24:27]
	v_mfma_f32_16x16x32_bf16 v[16:19], v[194:197], v[218:221], v[16:19]
	v_mfma_f32_16x16x32_bf16 v[8:11], v[186:189], v[226:229], v[8:11]
	v_mfma_f32_16x16x32_bf16 v[0:3], v[194:197], v[226:229], v[0:3]
	v_mfma_f32_16x16x32_bf16 v[56:59], v[190:193], v[206:209], v[56:59]
	v_mfma_f32_16x16x32_bf16 v[48:51], v[198:201], v[206:209], v[48:51]
	v_mfma_f32_16x16x32_bf16 v[40:43], v[190:193], v[214:217], v[40:43]
	v_mfma_f32_16x16x32_bf16 v[32:35], v[198:201], v[214:217], v[32:35]
	v_mfma_f32_16x16x32_bf16 v[24:27], v[190:193], v[222:225], v[24:27]
	v_mfma_f32_16x16x32_bf16 v[16:19], v[198:201], v[222:225], v[16:19]
	v_mfma_f32_16x16x32_bf16 v[8:11], v[190:193], v[232:235], v[8:11]
	v_mfma_f32_16x16x32_bf16 v[0:3], v[198:201], v[232:235], v[0:3]
	s_setprio 0
	s_barrier
	s_add_i32 s58, s58, 2
	s_add_u32 s34, s34, 0x100
	s_addc_u32 s35, s35, 0
	s_add_u32 s56, s56, 0x100
	s_addc_u32 s57, s57, 0
	s_cmp_gt_u32 s58, 13
; #define PG8_STAGE(bufoff, gbase, voff) do { _Pragma("unroll") for (int _i = 0; _i < 2; ++_i) \
;         __builtin_amdgcn_global_load_lds((const unsigned*)((const char*)(gbase) + (voff)[_i]), (PG8_LAS unsigned*)(lds + (bufoff) + ldsw + _i * 8192), 16, 0, 0); } while (0)
; #define PG8_LDA(dst, b, h) do { _Pragma("unroll") for (int m = 0; m < 4; ++m) _Pragma("unroll") for (int k = 0; k < 2; ++k) dst[m][k] = *(const PG8_LAS bf16x8*)(lds + PG8_SA(b, h) + aoff + m * 2048 + k * 1024); } while (0)
; #define PG8_LDB(dst, b, h) do { _Pragma("unroll") for (int n = 0; n < 2; ++n) _Pragma("unroll") for (int k = 0; k < 2; ++k) dst[n][k] = *(const PG8_LAS bf16x8*)(lds + PG8_SB(b, h) + boff + n * 2048 + k * 1024); } while (0)
; #define PG8_MMA(ai, bj, At, Bt) do { __builtin_amdgcn_s_setprio(1); _Pragma("unroll") for (int m = 0; m < 4; ++m) _Pragma("unroll") for (int n = 0; n < 2; ++n) _Pragma("unroll") for (int k = 0; k < 2; ++k) \
;         acc[ai][bj][m][n] = __builtin_amdgcn_mfma_f32_16x16x32_bf16(Bt[n][k], At[m][k], acc[ai][bj][m][n], 0, 0, 0); __builtin_amdgcn_s_setprio(0); } while (0)
; #define PG8_WAIT_V(n) asm volatile("s_waitcnt vmcnt(" #n ")" ::: "memory")
; #define PG8_WAIT_L(n) asm volatile("s_waitcnt lgkmcnt(" #n ")" ::: "memory")
; #define PG8_BAR __builtin_amdgcn_s_barrier()
; #define PG8_SCHED __builtin_amdgcn_sched_barrier(0)
; template <class Epi, class Sched, bool ALIGN_EPI = false, bool SP2 = false>
; __device__ __forceinline__ void gemm_phase(PG8_LAS unsigned char* lds, const Gemm g, const Sched& S, const Epi& E) {
;     ...
;             PG8_LDB(B0, 0, 0); PG8_LDB(B1, 0, 1); PG8_SCHED; PG8_LDA(At, 0, 0); PG8_STAGE(PG8_SA(1, 1), a1 + hstep, voffA);
;             PG8_WAIT_V(8); PG8_WAIT_L(0); PG8_BAR; PG8_MMA(0, 0, At, B0); PG8_MMA(0, 1, At, B1); PG8_BAR; PG8_SCHED;
;             PG8_LDA(At, 0, 1); PG8_STAGE(PG8_SB(0, 0), b2, voffB); PG8_STAGE(PG8_SB(0, 1), b2 + hstep, voffB); PG8_STAGE(PG8_SA(0, 0), a2, voffA);
;             PG8_WAIT_V(8); PG8_WAIT_L(0); PG8_BAR; PG8_MMA(1, 0, At, B0); PG8_MMA(1, 1, At, B1); PG8_BAR; PG8_SCHED;
.LBB0_977:
	ds_read_b128 v[144:147], v161
	ds_read_b128 v[170:173], v161 offset:1024
	ds_read_b128 v[178:181], v161 offset:2048
	ds_read_b128 v[182:185], v161 offset:3072
	ds_read_b128 v[186:189], v165
	ds_read_b128 v[190:193], v165 offset:1024
	ds_read_b128 v[194:197], v165 offset:2048
	ds_read_b128 v[198:201], v165 offset:3072
	s_add_u32 s36, s34, 0xfffc0080
	s_addc_u32 s37, s35, -1
	s_cmp_eq_u32 s58, 12
	s_cselect_b32 s39, s21, s37
	s_cselect_b32 s38, s54, s36
	s_cselect_b32 s37, s19, s57
	s_cselect_b32 s36, s55, s56
	v_lshl_add_u64 v[150:151], s[34:35], 0, v[138:139]
	s_add_i32 m0, s29, 0xc000
	ds_read_b128 v[202:205], v169
	ds_read_b128 v[206:209], v169 offset:1024
	ds_read_b128 v[210:213], v169 offset:2048
	ds_read_b128 v[214:217], v169 offset:3072
	ds_read_b128 v[218:221], v169 offset:4096
	ds_read_b128 v[222:225], v169 offset:5120
	ds_read_b128 v[226:229], v169 offset:6144
	ds_read_b128 v[232:235], v169 offset:7168
	global_load_lds_dwordx4 v[150:151], off
	v_lshl_add_u64 v[150:151], s[34:35], 0, v[140:141]
	s_add_i32 m0, s29, 0xe000
	s_nop 0
	global_load_lds_dwordx4 v[150:151], off
	s_waitcnt vmcnt(8)
	s_waitcnt lgkmcnt(0)
	s_barrier
	s_setprio 1
	s_waitcnt lgkmcnt(0)
	v_mfma_f32_16x16x32_bf16 v[124:127], v[144:147], v[202:205], v[124:127]
	v_mfma_f32_16x16x32_bf16 v[116:119], v[178:181], v[202:205], v[116:119]
	v_mfma_f32_16x16x32_bf16 v[108:111], v[144:147], v[210:213], v[108:111]
	v_mfma_f32_16x16x32_bf16 v[100:103], v[178:181], v[210:213], v[100:103]
	v_mfma_f32_16x16x32_bf16 v[92:95], v[144:147], v[218:221], v[92:95]
	v_mfma_f32_16x16x32_bf16 v[84:87], v[178:181], v[218:221], v[84:87]
	v_mfma_f32_16x16x32_bf16 v[76:79], v[144:147], v[226:229], v[76:79]
	v_mfma_f32_16x16x32_bf16 v[68:71], v[178:181], v[226:229], v[68:71]
	v_mfma_f32_16x16x32_bf16 v[124:127], v[170:173], v[206:209], v[124:127]
	v_mfma_f32_16x16x32_bf16 v[116:119], v[182:185], v[206:209], v[116:119]
	v_mfma_f32_16x16x32_bf16 v[108:111], v[170:173], v[214:217], v[108:111]
	v_mfma_f32_16x16x32_bf16 v[100:103], v[182:185], v[214:217], v[100:103]
	v_mfma_f32_16x16x32_bf16 v[92:95], v[170:173], v[222:225], v[92:95]
	v_mfma_f32_16x16x32_bf16 v[84:87], v[182:185], v[222:225], v[84:87]
	v_mfma_f32_16x16x32_bf16 v[76:79], v[170:173], v[232:235], v[76:79]
	v_mfma_f32_16x16x32_bf16 v[68:71], v[182:185], v[232:235], v[68:71]
	s_setprio 0
	s_setprio 1
	v_mfma_f32_16x16x32_bf16 v[120:123], v[186:189], v[202:205], v[120:123]
	v_mfma_f32_16x16x32_bf16 v[112:115], v[194:197], v[202:205], v[112:115]
	v_mfma_f32_16x16x32_bf16 v[104:107], v[186:189], v[210:213], v[104:107]
	v_mfma_f32_16x16x32_bf16 v[96:99], v[194:197], v[210:213], v[96:99]
	v_mfma_f32_16x16x32_bf16 v[88:91], v[186:189], v[218:221], v[88:91]
	v_mfma_f32_16x16x32_bf16 v[80:83], v[194:197], v[218:221], v[80:83]
	v_mfma_f32_16x16x32_bf16 v[72:75], v[186:189], v[226:229], v[72:75]
	v_mfma_f32_16x16x32_bf16 v[64:67], v[194:197], v[226:229], v[64:67]
	v_mfma_f32_16x16x32_bf16 v[120:123], v[190:193], v[206:209], v[120:123]
	v_mfma_f32_16x16x32_bf16 v[112:115], v[198:201], v[206:209], v[112:115]
	v_mfma_f32_16x16x32_bf16 v[104:107], v[190:193], v[214:217], v[104:107]
	v_mfma_f32_16x16x32_bf16 v[96:99], v[198:201], v[214:217], v[96:99]
	v_mfma_f32_16x16x32_bf16 v[88:91], v[190:193], v[222:225], v[88:91]
	v_mfma_f32_16x16x32_bf16 v[80:83], v[198:201], v[222:225], v[80:83]
	v_mfma_f32_16x16x32_bf16 v[72:75], v[190:193], v[232:235], v[72:75]
	v_mfma_f32_16x16x32_bf16 v[64:67], v[198:201], v[232:235], v[64:67]
	s_setprio 0
	s_barrier
	s_add_i32 s59, s50, s43
	v_lshl_add_u64 v[150:151], s[36:37], 0, v[130:131]
	s_mov_b32 m0, s59
	ds_read_b128 v[202:205], v169 offset:16384
	ds_read_b128 v[206:209], v169 offset:17408
	ds_read_b128 v[210:213], v169 offset:18432
	ds_read_b128 v[214:217], v169 offset:19456
	ds_read_b128 v[218:221], v169 offset:20480
	ds_read_b128 v[222:225], v169 offset:21504
	ds_read_b128 v[226:229], v169 offset:22528
	ds_read_b128 v[232:235], v169 offset:23552
	global_load_lds_dwordx4 v[150:151], off
	s_add_i32 m0, s59, 0x2000
	s_add_u32 s60, s36, 0x40000
	v_lshl_add_u64 v[154:155], s[36:37], 0, v[134:135]
	s_addc_u32 s61, s37, 0
	s_add_i32 s59, s51, s43
	global_load_lds_dwordx4 v[154:155], off
	v_lshl_add_u64 v[158:159], s[60:61], 0, v[130:131]
	s_mov_b32 m0, s59
	v_lshl_add_u64 v[162:163], s[38:39], 0, v[132:133]
	global_load_lds_dwordx4 v[158:159], off
	v_lshl_add_u64 v[158:159], s[60:61], 0, v[134:135]
	s_add_i32 m0, s59, 0x2000
	s_nop 0
	global_load_lds_dwordx4 v[158:159], off
	v_lshl_add_u64 v[158:159], s[38:39], 0, v[128:129]
	s_mov_b32 m0, s29
	s_nop 0
	global_load_lds_dwordx4 v[158:159], off
	s_mov_b32 m0, s31
	s_nop 0
	global_load_lds_dwordx4 v[162:163], off
	s_cmp_lg_i32 s58, -2
	s_cbranch_scc1 .Lrsb_a
	v_lshrrev_b32_e32 v250, 6, v230
	v_lshlrev_b32_e32 v250, 11, v250
	v_and_b32_e32 v251, 63, v230
	v_lshl_or_b32 v250, v251, 4, v250
	v_lshl_add_u32 v250, s30, 14, v250
	v_readfirstlane_b32 s98, v230
	s_lshr_b32 s98, s98, 6
	s_lshl_b32 s98, s98, 11
	s_add_i32 m0, s98, 0x20000
	s_add_u32 s100, s70, 0x3f000000
	s_addc_u32 s101, s71, 0
	global_load_lds_dwordx4 v250, s[100:101]
	global_load_lds_dwordx4 v250, s[100:101] offset:1024
	s_waitcnt vmcnt(10)
	s_branch .Lrsb_b

; #define PG8_STAGE(bufoff, gbase, voff) do { _Pragma("unroll") for (int _i = 0; _i < 2; ++_i) \
;         __builtin_amdgcn_global_load_lds((const unsigned*)((const char*)(gbase) + (voff)[_i]), (PG8_LAS unsigned*)(lds + (bufoff) + ldsw + _i * 8192), 16, 0, 0); } while (0)
; #define PG8_LDA(dst, b, h) do { _Pragma("unroll") for (int m = 0; m < 4; ++m) _Pragma("unroll") for (int k = 0; k < 2; ++k) dst[m][k] = *(const PG8_LAS bf16x8*)(lds + PG8_SA(b, h) + aoff + m * 2048 + k * 1024); } while (0)
; #define PG8_LDB(dst, b, h) do { _Pragma("unroll") for (int n = 0; n < 2; ++n) _Pragma("unroll") for (int k = 0; k < 2; ++k) dst[n][k] = *(const PG8_LAS bf16x8*)(lds + PG8_SB(b, h) + boff + n * 2048 + k * 1024); } while (0)
; #define PG8_MMA(ai, bj, At, Bt) do { __builtin_amdgcn_s_setprio(1); _Pragma("unroll") for (int m = 0; m < 4; ++m) _Pragma("unroll") for (int n = 0; n < 2; ++n) _Pragma("unroll") for (int k = 0; k < 2; ++k) \
;         acc[ai][bj][m][n] = __builtin_amdgcn_mfma_f32_16x16x32_bf16(Bt[n][k], At[m][k], acc[ai][bj][m][n], 0, 0, 0); __builtin_amdgcn_s_setprio(0); } while (0)
; #define PG8_WAIT_V(n) asm volatile("s_waitcnt vmcnt(" #n ")" ::: "memory")
; #define PG8_WAIT_L(n) asm volatile("s_waitcnt lgkmcnt(" #n ")" ::: "memory")
; #define PG8_BAR __builtin_amdgcn_s_barrier()
; #define PG8_SCHED __builtin_amdgcn_sched_barrier(0)
; template <class Epi, class Sched, bool ALIGN_EPI = false, bool SP2 = false>
; __device__ __forceinline__ void gemm_phase(PG8_LAS unsigned char* lds, const Gemm g, const Sched& S, const Epi& E) {
;     ...
;             const char* a2 = last ? nA : cA + (size_t)(t + 2) * kstep; const char* b2 = last ? nB : cB + (size_t)(t + 2) * kstep;
;             const char* a3 = a2 + kstep; const char* b3 = b2 + kstep;
;             if (last && has_next) S.a_ready(nxt);
;             if constexpr (SP2) {
;             PG8_LDB(B0, 0, 0); PG8_LDB(B1, 0, 1); PG8_SCHED; PG8_LDA(At, 0, 0); PG8_STAGE(PG8_SA(1, 1), a1 + hstep, voffA);
;             PG8_WAIT_V(8); PG8_WAIT_L(0); PG8_BAR; PG8_MMA(0, 0, At, B0); PG8_MMA(0, 1, At, B1); PG8_BAR; PG8_SCHED;
;             PG8_LDA(At, 0, 1); PG8_STAGE(PG8_SB(0, 0), b2, voffB); PG8_STAGE(PG8_SB(0, 1), b2 + hstep, voffB); PG8_STAGE(PG8_SA(0, 0), a2, voffA);
;             PG8_WAIT_V(8); PG8_WAIT_L(0); PG8_BAR; PG8_MMA(1, 0, At, B0); PG8_MMA(1, 1, At, B1); PG8_BAR; PG8_SCHED;
.LBB0_1061:
	s_add_u32 s16, s16, 0xb0080
	s_addc_u32 s17, s17, 0
	s_add_u32 s41, s18, 0x100
	s_addc_u32 s42, s19, 0
	s_mov_b32 s43, -2
	ds_read_b128 v[128:131], v189
	ds_read_b128 v[132:135], v189 offset:1024
	ds_read_b128 v[136:139], v189 offset:2048
	ds_read_b128 v[140:143], v189 offset:3072
	ds_read_b128 v[144:147], v190
	ds_read_b128 v[148:151], v190 offset:1024
	ds_read_b128 v[152:155], v190 offset:2048
	ds_read_b128 v[156:159], v190 offset:3072
	s_add_u32 s18, s16, 0xfff50080
	s_addc_u32 s19, s17, -1
	s_cmp_eq_u32 s43, 40
	s_cselect_b32 s21, s13, s19
	s_cselect_b32 s20, s12, s18
	s_cselect_b32 s19, s15, s42
	s_cselect_b32 s18, s14, s41
	v_lshl_add_u64 v[212:213], s[16:17], 0, v[168:169]
	s_add_i32 m0, s26, 0xc000
	ds_read_b128 v[174:177], v191
	ds_read_b128 v[178:181], v191 offset:1024
	ds_read_b128 v[182:185], v191 offset:2048
	ds_read_b128 v[192:195], v191 offset:3072
	ds_read_b128 v[196:199], v191 offset:4096
	ds_read_b128 v[200:203], v191 offset:5120
	ds_read_b128 v[204:207], v191 offset:6144
	ds_read_b128 v[208:211], v191 offset:7168
	global_load_lds_dwordx4 v[212:213], off
	v_lshl_add_u64 v[212:213], s[16:17], 0, v[170:171]
	s_add_i32 m0, s26, 0xe000
	s_nop 0
	global_load_lds_dwordx4 v[212:213], off
	s_waitcnt vmcnt(8)
	s_waitcnt lgkmcnt(0)
	s_barrier
	s_setprio 1
	s_waitcnt lgkmcnt(0)
	v_mfma_f32_16x16x32_bf16 v[124:127], v[128:131], v[174:177], 0
	v_mfma_f32_16x16x32_bf16 v[120:123], v[136:139], v[174:177], 0
	v_mfma_f32_16x16x32_bf16 v[116:119], v[128:131], v[182:185], 0
	v_mfma_f32_16x16x32_bf16 v[104:107], v[136:139], v[182:185], 0
	v_mfma_f32_16x16x32_bf16 v[96:99], v[128:131], v[196:199], 0
	v_mfma_f32_16x16x32_bf16 v[88:91], v[136:139], v[196:199], 0
	v_mfma_f32_16x16x32_bf16 v[80:83], v[128:131], v[204:207], 0
	v_mfma_f32_16x16x32_bf16 v[72:75], v[136:139], v[204:207], 0
	v_mfma_f32_16x16x32_bf16 v[124:127], v[132:135], v[178:181], v[124:127]
	v_mfma_f32_16x16x32_bf16 v[120:123], v[140:143], v[178:181], v[120:123]
	v_mfma_f32_16x16x32_bf16 v[116:119], v[132:135], v[192:195], v[116:119]
	v_mfma_f32_16x16x32_bf16 v[104:107], v[140:143], v[192:195], v[104:107]
	v_mfma_f32_16x16x32_bf16 v[96:99], v[132:135], v[200:203], v[96:99]
	v_mfma_f32_16x16x32_bf16 v[88:91], v[140:143], v[200:203], v[88:91]
	v_mfma_f32_16x16x32_bf16 v[80:83], v[132:135], v[208:211], v[80:83]
	v_mfma_f32_16x16x32_bf16 v[72:75], v[140:143], v[208:211], v[72:75]
	s_setprio 0
	s_setprio 1
	v_mfma_f32_16x16x32_bf16 v[112:115], v[144:147], v[174:177], 0
	v_mfma_f32_16x16x32_bf16 v[108:111], v[152:155], v[174:177], 0
	v_mfma_f32_16x16x32_bf16 v[100:103], v[144:147], v[182:185], 0
	v_mfma_f32_16x16x32_bf16 v[92:95], v[152:155], v[182:185], 0
	v_mfma_f32_16x16x32_bf16 v[84:87], v[144:147], v[196:199], 0
	v_mfma_f32_16x16x32_bf16 v[76:79], v[152:155], v[196:199], 0
	v_mfma_f32_16x16x32_bf16 v[68:71], v[144:147], v[204:207], 0
	v_mfma_f32_16x16x32_bf16 v[64:67], v[152:155], v[204:207], 0
	v_mfma_f32_16x16x32_bf16 v[112:115], v[148:151], v[178:181], v[112:115]
	v_mfma_f32_16x16x32_bf16 v[108:111], v[156:159], v[178:181], v[108:111]
	v_mfma_f32_16x16x32_bf16 v[100:103], v[148:151], v[192:195], v[100:103]
	v_mfma_f32_16x16x32_bf16 v[92:95], v[156:159], v[192:195], v[92:95]
	v_mfma_f32_16x16x32_bf16 v[84:87], v[148:151], v[200:203], v[84:87]
	v_mfma_f32_16x16x32_bf16 v[76:79], v[156:159], v[200:203], v[76:79]
	v_mfma_f32_16x16x32_bf16 v[68:71], v[148:151], v[208:211], v[68:71]
	v_mfma_f32_16x16x32_bf16 v[64:67], v[156:159], v[208:211], v[64:67]
	s_setprio 0
	s_barrier
	s_add_i32 s44, s35, s25
	v_lshl_add_u64 v[212:213], s[18:19], 0, v[162:163]
	s_mov_b32 m0, s44
	ds_read_b128 v[174:177], v191 offset:16384
	ds_read_b128 v[178:181], v191 offset:17408
	ds_read_b128 v[182:185], v191 offset:18432
	ds_read_b128 v[192:195], v191 offset:19456
	ds_read_b128 v[196:199], v191 offset:20480
	ds_read_b128 v[200:203], v191 offset:21504
	ds_read_b128 v[204:207], v191 offset:22528
	ds_read_b128 v[208:211], v191 offset:23552
	global_load_lds_dwordx4 v[212:213], off
	s_add_i32 m0, s44, 0x2000
	s_add_u32 s44, s18, 0xb0000
	v_lshl_add_u64 v[214:215], s[18:19], 0, v[166:167]
	s_addc_u32 s45, s19, 0
	s_add_i32 s46, s36, s25
	global_load_lds_dwordx4 v[214:215], off
	v_lshl_add_u64 v[216:217], s[44:45], 0, v[162:163]
	s_mov_b32 m0, s46
	v_lshl_add_u64 v[218:219], s[20:21], 0, v[164:165]
	global_load_lds_dwordx4 v[216:217], off
	v_lshl_add_u64 v[216:217], s[44:45], 0, v[166:167]
	s_add_i32 m0, s46, 0x2000
	s_nop 0
	global_load_lds_dwordx4 v[216:217], off
	v_lshl_add_u64 v[216:217], s[20:21], 0, v[160:161]
	s_mov_b32 m0, s26
	s_nop 0
	global_load_lds_dwordx4 v[216:217], off
	s_mov_b32 m0, s27
	s_nop 0
	global_load_lds_dwordx4 v[218:219], off
	s_waitcnt vmcnt(8)
	s_waitcnt lgkmcnt(0)
	s_barrier
; #define PG8_STAGE(bufoff, gbase, voff) do { _Pragma("unroll") for (int _i = 0; _i < 2; ++_i) \
;         __builtin_amdgcn_global_load_lds((const unsigned*)((const char*)(gbase) + (voff)[_i]), (PG8_LAS unsigned*)(lds + (bufoff) + ldsw + _i * 8192), 16, 0, 0); } while (0)
; #define PG8_LDA(dst, b, h) do { _Pragma("unroll") for (int m = 0; m < 4; ++m) _Pragma("unroll") for (int k = 0; k < 2; ++k) dst[m][k] = *(const PG8_LAS bf16x8*)(lds + PG8_SA(b, h) + aoff + m * 2048 + k * 1024); } while (0)
; #define PG8_LDB(dst, b, h) do { _Pragma("unroll") for (int n = 0; n < 2; ++n) _Pragma("unroll") for (int k = 0; k < 2; ++k) dst[n][k] = *(const PG8_LAS bf16x8*)(lds + PG8_SB(b, h) + boff + n * 2048 + k * 1024); } while (0)
; #define PG8_MMA(ai, bj, At, Bt) do { __builtin_amdgcn_s_setprio(1); _Pragma("unroll") for (int m = 0; m < 4; ++m) _Pragma("unroll") for (int n = 0; n < 2; ++n) _Pragma("unroll") for (int k = 0; k < 2; ++k) \
;         acc[ai][bj][m][n] = __builtin_amdgcn_mfma_f32_16x16x32_bf16(Bt[n][k], At[m][k], acc[ai][bj][m][n], 0, 0, 0); __builtin_amdgcn_s_setprio(0); } while (0)
; #define PG8_WAIT_V(n) asm volatile("s_waitcnt vmcnt(" #n ")" ::: "memory")
; #define PG8_WAIT_L(n) asm volatile("s_waitcnt lgkmcnt(" #n ")" ::: "memory")
; #define PG8_BAR __builtin_amdgcn_s_barrier()
; #define PG8_SCHED __builtin_amdgcn_sched_barrier(0)
; template <class Epi, class Sched, bool ALIGN_EPI = false, bool SP2 = false>
; __device__ __forceinline__ void gemm_phase(PG8_LAS unsigned char* lds, const Gemm g, const Sched& S, const Epi& E) {
;     ...
;             PG8_WAIT_V(8); PG8_WAIT_L(0); PG8_BAR; PG8_MMA(1, 0, At, B0); PG8_MMA(1, 1, At, B1); PG8_BAR; PG8_SCHED;
;             PG8_LDB(B0, 1, 0); PG8_LDB(B1, 1, 1); PG8_SCHED; PG8_LDA(At, 1, 0); PG8_STAGE(PG8_SA(0, 1), a2 + hstep, voffA);
;             PG8_WAIT_V(8); PG8_WAIT_L(0); PG8_BAR; PG8_MMA(0, 0, At, B0); PG8_MMA(0, 1, At, B1); PG8_BAR; PG8_SCHED;
	s_setprio 1
	s_waitcnt lgkmcnt(0)
	v_mfma_f32_16x16x32_bf16 v[60:63], v[128:131], v[174:177], 0
	v_mfma_f32_16x16x32_bf16 v[56:59], v[136:139], v[174:177], 0
	v_mfma_f32_16x16x32_bf16 v[48:51], v[128:131], v[182:185], 0
	v_mfma_f32_16x16x32_bf16 v[40:43], v[136:139], v[182:185], 0
	v_mfma_f32_16x16x32_bf16 v[32:35], v[128:131], v[196:199], 0
	v_mfma_f32_16x16x32_bf16 v[24:27], v[136:139], v[196:199], 0
	v_mfma_f32_16x16x32_bf16 v[16:19], v[128:131], v[204:207], 0
	v_mfma_f32_16x16x32_bf16 v[8:11], v[136:139], v[204:207], 0
	v_mfma_f32_16x16x32_bf16 v[60:63], v[132:135], v[178:181], v[60:63]
	v_mfma_f32_16x16x32_bf16 v[56:59], v[140:143], v[178:181], v[56:59]
	v_mfma_f32_16x16x32_bf16 v[48:51], v[132:135], v[192:195], v[48:51]
	v_mfma_f32_16x16x32_bf16 v[40:43], v[140:143], v[192:195], v[40:43]
	v_mfma_f32_16x16x32_bf16 v[32:35], v[132:135], v[200:203], v[32:35]
	v_mfma_f32_16x16x32_bf16 v[24:27], v[140:143], v[200:203], v[24:27]
	v_mfma_f32_16x16x32_bf16 v[16:19], v[132:135], v[208:211], v[16:19]
	v_mfma_f32_16x16x32_bf16 v[8:11], v[140:143], v[208:211], v[8:11]
	s_setprio 0
	s_setprio 1
	v_mfma_f32_16x16x32_bf16 v[52:55], v[144:147], v[174:177], 0
	v_mfma_f32_16x16x32_bf16 v[44:47], v[152:155], v[174:177], 0
	v_mfma_f32_16x16x32_bf16 v[36:39], v[144:147], v[182:185], 0
	v_mfma_f32_16x16x32_bf16 v[28:31], v[152:155], v[182:185], 0
	v_mfma_f32_16x16x32_bf16 v[20:23], v[144:147], v[196:199], 0
	v_mfma_f32_16x16x32_bf16 v[12:15], v[152:155], v[196:199], 0
	v_mfma_f32_16x16x32_bf16 v[4:7], v[144:147], v[204:207], 0
	v_mfma_f32_16x16x32_bf16 v[0:3], v[152:155], v[204:207], 0
	v_mfma_f32_16x16x32_bf16 v[52:55], v[148:151], v[178:181], v[52:55]
	v_mfma_f32_16x16x32_bf16 v[44:47], v[156:159], v[178:181], v[44:47]
	v_mfma_f32_16x16x32_bf16 v[36:39], v[148:151], v[192:195], v[36:39]
	v_mfma_f32_16x16x32_bf16 v[28:31], v[156:159], v[192:195], v[28:31]
	v_mfma_f32_16x16x32_bf16 v[20:23], v[148:151], v[200:203], v[20:23]
	v_mfma_f32_16x16x32_bf16 v[12:15], v[156:159], v[200:203], v[12:15]
	v_mfma_f32_16x16x32_bf16 v[4:7], v[148:151], v[208:211], v[4:7]
	v_mfma_f32_16x16x32_bf16 v[0:3], v[156:159], v[208:211], v[0:3]
	s_setprio 0
	s_barrier
	s_add_i32 s44, 0, 0x18000
	s_add_i32 s45, 0, 0x1c000
	v_add_u32_e32 v140, s44, v187
	v_add_u32_e32 v156, s45, v187
	ds_read_b128 v[128:131], v140
	ds_read_b128 v[132:135], v140 offset:1024
	ds_read_b128 v[136:139], v140 offset:2048
	ds_read_b128 v[140:143], v140 offset:3072
	ds_read_b128 v[144:147], v156
	ds_read_b128 v[148:151], v156 offset:1024
	ds_read_b128 v[152:155], v156 offset:2048
	ds_read_b128 v[156:159], v156 offset:3072
	s_add_u32 s20, s20, 0xb0000
	s_addc_u32 s21, s21, 0
	s_mov_b32 m0, s28
	v_lshl_add_u64 v[220:221], s[20:21], 0, v[160:161]
	ds_read_b128 v[174:177], v191 offset:32768
	ds_read_b128 v[178:181], v191 offset:33792
	ds_read_b128 v[182:185], v191 offset:34816
	ds_read_b128 v[192:195], v191 offset:35840
	ds_read_b128 v[196:199], v191 offset:36864
	ds_read_b128 v[200:203], v191 offset:37888
	ds_read_b128 v[204:207], v191 offset:38912
	ds_read_b128 v[208:211], v191 offset:39936
	global_load_lds_dwordx4 v[220:221], off
	v_lshl_add_u64 v[220:221], s[20:21], 0, v[164:165]
	s_mov_b32 m0, s29
	s_nop 0
	global_load_lds_dwordx4 v[220:221], off
	s_waitcnt vmcnt(8)
	s_waitcnt lgkmcnt(0)
	s_barrier
	s_setprio 1
	s_waitcnt lgkmcnt(0)
	v_mfma_f32_16x16x32_bf16 v[124:127], v[128:131], v[174:177], v[124:127]
	v_mfma_f32_16x16x32_bf16 v[120:123], v[136:139], v[174:177], v[120:123]
	v_mfma_f32_16x16x32_bf16 v[116:119], v[128:131], v[182:185], v[116:119]
	v_mfma_f32_16x16x32_bf16 v[104:107], v[136:139], v[182:185], v[104:107]
	v_mfma_f32_16x16x32_bf16 v[96:99], v[128:131], v[196:199], v[96:99]
	v_mfma_f32_16x16x32_bf16 v[88:91], v[136:139], v[196:199], v[88:91]
	v_mfma_f32_16x16x32_bf16 v[80:83], v[128:131], v[204:207], v[80:83]
	v_mfma_f32_16x16x32_bf16 v[72:75], v[136:139], v[204:207], v[72:75]
	v_mfma_f32_16x16x32_bf16 v[124:127], v[132:135], v[178:181], v[124:127]
	v_mfma_f32_16x16x32_bf16 v[120:123], v[140:143], v[178:181], v[120:123]
	v_mfma_f32_16x16x32_bf16 v[116:119], v[132:135], v[192:195], v[116:119]
	v_mfma_f32_16x16x32_bf16 v[104:107], v[140:143], v[192:195], v[104:107]
	v_mfma_f32_16x16x32_bf16 v[96:99], v[132:135], v[200:203], v[96:99]
	v_mfma_f32_16x16x32_bf16 v[88:91], v[140:143], v[200:203], v[88:91]
	v_mfma_f32_16x16x32_bf16 v[80:83], v[132:135], v[208:211], v[80:83]
	v_mfma_f32_16x16x32_bf16 v[72:75], v[140:143], v[208:211], v[72:75]
	s_setprio 0
	s_setprio 1
	v_mfma_f32_16x16x32_bf16 v[112:115], v[144:147], v[174:177], v[112:115]
	v_mfma_f32_16x16x32_bf16 v[108:111], v[152:155], v[174:177], v[108:111]
	v_mfma_f32_16x16x32_bf16 v[100:103], v[144:147], v[182:185], v[100:103]
	v_mfma_f32_16x16x32_bf16 v[92:95], v[152:155], v[182:185], v[92:95]
	v_mfma_f32_16x16x32_bf16 v[84:87], v[144:147], v[196:199], v[84:87]
	v_mfma_f32_16x16x32_bf16 v[76:79], v[152:155], v[196:199], v[76:79]
	v_mfma_f32_16x16x32_bf16 v[68:71], v[144:147], v[204:207], v[68:71]
	v_mfma_f32_16x16x32_bf16 v[64:67], v[152:155], v[204:207], v[64:67]
	v_mfma_f32_16x16x32_bf16 v[112:115], v[148:151], v[178:181], v[112:115]
	v_mfma_f32_16x16x32_bf16 v[108:111], v[156:159], v[178:181], v[108:111]
	v_mfma_f32_16x16x32_bf16 v[100:103], v[148:151], v[192:195], v[100:103]
	v_mfma_f32_16x16x32_bf16 v[92:95], v[156:159], v[192:195], v[92:95]
	v_mfma_f32_16x16x32_bf16 v[84:87], v[148:151], v[200:203], v[84:87]
	v_mfma_f32_16x16x32_bf16 v[76:79], v[156:159], v[200:203], v[76:79]
	v_mfma_f32_16x16x32_bf16 v[68:71], v[148:151], v[208:211], v[68:71]
	v_mfma_f32_16x16x32_bf16 v[64:67], v[156:159], v[208:211], v[64:67]
	s_setprio 0
	s_barrier
; #define PG8_STAGE(bufoff, gbase, voff) do { _Pragma("unroll") for (int _i = 0; _i < 2; ++_i) \
;         __builtin_amdgcn_global_load_lds((const unsigned*)((const char*)(gbase) + (voff)[_i]), (PG8_LAS unsigned*)(lds + (bufoff) + ldsw + _i * 8192), 16, 0, 0); } while (0)
; #define PG8_LDA(dst, b, h) do { _Pragma("unroll") for (int m = 0; m < 4; ++m) _Pragma("unroll") for (int k = 0; k < 2; ++k) dst[m][k] = *(const PG8_LAS bf16x8*)(lds + PG8_SA(b, h) + aoff + m * 2048 + k * 1024); } while (0)
; #define PG8_MMA(ai, bj, At, Bt) do { __builtin_amdgcn_s_setprio(1); _Pragma("unroll") for (int m = 0; m < 4; ++m) _Pragma("unroll") for (int n = 0; n < 2; ++n) _Pragma("unroll") for (int k = 0; k < 2; ++k) \
;         acc[ai][bj][m][n] = __builtin_amdgcn_mfma_f32_16x16x32_bf16(Bt[n][k], At[m][k], acc[ai][bj][m][n], 0, 0, 0); __builtin_amdgcn_s_setprio(0); } while (0)
; #define PG8_WAIT_V(n) asm volatile("s_waitcnt vmcnt(" #n ")" ::: "memory")
; #define PG8_WAIT_L(n) asm volatile("s_waitcnt lgkmcnt(" #n ")" ::: "memory")
; #define PG8_BAR __builtin_amdgcn_s_barrier()
; #define PG8_SCHED __builtin_amdgcn_sched_barrier(0)
; template <class Epi, class Sched, bool ALIGN_EPI = false, bool SP2 = false>
; __device__ __forceinline__ void gemm_phase(PG8_LAS unsigned char* lds, const Gemm g, const Sched& S, const Epi& E) {
;     ...
;             PG8_LDA(At, 1, 1); PG8_STAGE(PG8_SB(1, 0), b3, voffB); PG8_STAGE(PG8_SB(1, 1), b3 + hstep, voffB); PG8_STAGE(PG8_SA(1, 0), a3, voffA);
;             PG8_WAIT_V(8); PG8_WAIT_L(0); PG8_BAR; PG8_MMA(1, 0, At, B0); PG8_MMA(1, 1, At, B1); PG8_BAR; PG8_SCHED;
	s_add_i32 s20, s44, s25
	v_lshl_add_u64 v[212:213], v[212:213], 0, s[8:9]
	s_mov_b32 m0, s20
	ds_read_b128 v[174:177], v191 offset:49152
	ds_read_b128 v[178:181], v191 offset:50176
	ds_read_b128 v[182:185], v191 offset:51200
	ds_read_b128 v[192:195], v191 offset:52224
	ds_read_b128 v[196:199], v191 offset:53248
	ds_read_b128 v[200:203], v191 offset:54272
	ds_read_b128 v[204:207], v191 offset:55296
	ds_read_b128 v[208:211], v191 offset:56320
	global_load_lds_dwordx4 v[212:213], off
	s_add_i32 m0, s20, 0x2000
	s_add_u32 s18, s18, 0xb0080
	v_lshl_add_u64 v[212:213], v[214:215], 0, s[8:9]
	s_addc_u32 s19, s19, 0
	s_add_i32 s20, s45, s25
	global_load_lds_dwordx4 v[212:213], off
	v_lshl_add_u64 v[212:213], s[18:19], 0, v[162:163]
	s_mov_b32 m0, s20
	s_nop 0
	global_load_lds_dwordx4 v[212:213], off
	v_lshl_add_u64 v[212:213], s[18:19], 0, v[166:167]
	s_add_i32 m0, s20, 0x2000
	s_nop 0
	global_load_lds_dwordx4 v[212:213], off
	v_lshl_add_u64 v[212:213], v[216:217], 0, s[8:9]
	s_mov_b32 m0, s33
	s_nop 0
	global_load_lds_dwordx4 v[212:213], off
	v_lshl_add_u64 v[212:213], v[218:219], 0, s[8:9]
	s_mov_b32 m0, s34
	s_nop 0
	global_load_lds_dwordx4 v[212:213], off
	s_waitcnt vmcnt(8)
	s_waitcnt lgkmcnt(0)
	s_barrier
	s_setprio 1
	s_waitcnt lgkmcnt(0)
	v_mfma_f32_16x16x32_bf16 v[60:63], v[128:131], v[174:177], v[60:63]
	v_mfma_f32_16x16x32_bf16 v[56:59], v[136:139], v[174:177], v[56:59]
	v_mfma_f32_16x16x32_bf16 v[48:51], v[128:131], v[182:185], v[48:51]
	v_mfma_f32_16x16x32_bf16 v[40:43], v[136:139], v[182:185], v[40:43]
	v_mfma_f32_16x16x32_bf16 v[32:35], v[128:131], v[196:199], v[32:35]
	v_mfma_f32_16x16x32_bf16 v[24:27], v[136:139], v[196:199], v[24:27]
	v_mfma_f32_16x16x32_bf16 v[16:19], v[128:131], v[204:207], v[16:19]
	v_mfma_f32_16x16x32_bf16 v[8:11], v[136:139], v[204:207], v[8:11]
	v_mfma_f32_16x16x32_bf16 v[60:63], v[132:135], v[178:181], v[60:63]
	v_mfma_f32_16x16x32_bf16 v[56:59], v[140:143], v[178:181], v[56:59]
	v_mfma_f32_16x16x32_bf16 v[48:51], v[132:135], v[192:195], v[48:51]
	v_mfma_f32_16x16x32_bf16 v[40:43], v[140:143], v[192:195], v[40:43]
	v_mfma_f32_16x16x32_bf16 v[32:35], v[132:135], v[200:203], v[32:35]
	v_mfma_f32_16x16x32_bf16 v[24:27], v[140:143], v[200:203], v[24:27]
	v_mfma_f32_16x16x32_bf16 v[16:19], v[132:135], v[208:211], v[16:19]
	v_mfma_f32_16x16x32_bf16 v[8:11], v[140:143], v[208:211], v[8:11]
	s_setprio 0
	s_setprio 1
	v_mfma_f32_16x16x32_bf16 v[52:55], v[144:147], v[174:177], v[52:55]
	v_mfma_f32_16x16x32_bf16 v[44:47], v[152:155], v[174:177], v[44:47]
	v_mfma_f32_16x16x32_bf16 v[36:39], v[144:147], v[182:185], v[36:39]
	v_mfma_f32_16x16x32_bf16 v[28:31], v[152:155], v[182:185], v[28:31]
	v_mfma_f32_16x16x32_bf16 v[20:23], v[144:147], v[196:199], v[20:23]
	v_mfma_f32_16x16x32_bf16 v[12:15], v[152:155], v[196:199], v[12:15]
	v_mfma_f32_16x16x32_bf16 v[4:7], v[144:147], v[204:207], v[4:7]
	v_mfma_f32_16x16x32_bf16 v[0:3], v[152:155], v[204:207], v[0:3]
	v_mfma_f32_16x16x32_bf16 v[52:55], v[148:151], v[178:181], v[52:55]
	v_mfma_f32_16x16x32_bf16 v[44:47], v[156:159], v[178:181], v[44:47]
	v_mfma_f32_16x16x32_bf16 v[36:39], v[148:151], v[192:195], v[36:39]
	v_mfma_f32_16x16x32_bf16 v[28:31], v[156:159], v[192:195], v[28:31]
	v_mfma_f32_16x16x32_bf16 v[20:23], v[148:151], v[200:203], v[20:23]
	v_mfma_f32_16x16x32_bf16 v[12:15], v[156:159], v[200:203], v[12:15]
	v_mfma_f32_16x16x32_bf16 v[4:7], v[148:151], v[208:211], v[4:7]
	v_mfma_f32_16x16x32_bf16 v[0:3], v[156:159], v[208:211], v[0:3]
	s_setprio 0
	s_barrier
	s_add_i32 s43, s43, 2
	s_add_u32 s16, s16, 0x100
	s_addc_u32 s17, s17, 0
	s_add_u32 s41, s41, 0x100
	s_addc_u32 s42, s42, 0
	s_cmp_gt_u32 s43, 41
